# v040 + GEMM main-loop tail SALU (pointer bumps, exit compare) moved above the last barrier of the iteration
# speedup vs baseline: 1.0065x; 1.0065x over previous
; #define PG8_STAGE(bufoff, gbase, voff) do { _Pragma("unroll") for (int _i = 0; _i < 2; ++_i) \
;         __builtin_amdgcn_global_load_lds((const unsigned*)((const char*)(gbase) + (voff)[_i]), (LAS unsigned*)(lds + (bufoff) + ldsw + _i * 8192), 16, 0, 0); } while (0)
; #define PG8_LDA(dst, b, h) do { _Pragma("unroll") for (int m = 0; m < 4; ++m) _Pragma("unroll") for (int k = 0; k < 2; ++k) dst[m][k] = *(const LAS bf16x8*)(lds + PG8_SA(b, h) + aoff + m * 2048 + k * 1024); } while (0)
; #define PG8_LDB(dst, b, h) do { _Pragma("unroll") for (int n = 0; n < 2; ++n) _Pragma("unroll") for (int k = 0; k < 2; ++k) dst[n][k] = *(const LAS bf16x8*)(lds + PG8_SB(b, h) + boff + n * 2048 + k * 1024); } while (0)
; #define PG8_MMA(ai, bj, At, Bt) do { __builtin_amdgcn_s_setprio(1); _Pragma("unroll") for (int m = 0; m < 4; ++m) _Pragma("unroll") for (int n = 0; n < 2; ++n) _Pragma("unroll") for (int k = 0; k < 2; ++k) \
;         acc[ai][bj][m][n] = __builtin_amdgcn_mfma_f32_16x16x32_bf16(Bt[n][k], At[m][k], acc[ai][bj][m][n], 0, 0, 0); __builtin_amdgcn_s_setprio(0); } while (0)
; #define PG8_WAIT_V(n) asm volatile("s_waitcnt vmcnt(" #n ")" ::: "memory")
; #define PG8_WAIT_L(n) asm volatile("s_waitcnt lgkmcnt(" #n ")" ::: "memory")
; #define PG8_BAR __builtin_amdgcn_s_barrier()
; #define PG8_SCHED __builtin_amdgcn_sched_barrier(0)
; template <class Epi>
; __device__ __forceinline__ void gemm_phase(LAS unsigned char* lds, const Gemm g, const StaticOrder& S, const Epi& E) {
;     ...
;         for (int t = 0; t < nt; t += 2) {
;             const bool last = (t == nt - 2);
;             const char* a1 = cA + (size_t)(t + 1) * kstep;
;             const char* a2 = last ? nA : cA + (size_t)(t + 2) * kstep; const char* b2 = last ? nB : cB + (size_t)(t + 2) * kstep;
;             const char* a3 = a2 + kstep; const char* b3 = b2 + kstep;
;             PG8_LDB(B0, 0, 0); PG8_LDB(B1, 0, 1); PG8_SCHED; PG8_LDA(At, 0, 0); PG8_STAGE(PG8_SA(1, 1), a1 + hstepA, voffA);
;             PG8_WAIT_V(8); PG8_WAIT_L(0); PG8_BAR; PG8_MMA(0, 0, At, B0); PG8_MMA(0, 1, At, B1); PG8_BAR; PG8_SCHED;
;             PG8_LDA(At, 0, 1); PG8_STAGE(PG8_SB(0, 0), b2, voffB); PG8_STAGE(PG8_SB(0, 1), b2 + hstepB, voffB); PG8_STAGE(PG8_SA(0, 0), a2, voffA);
;             PG8_WAIT_V(8); PG8_WAIT_L(0); PG8_BAR; PG8_MMA(1, 0, At, B0); PG8_MMA(1, 1, At, B1); PG8_BAR; PG8_SCHED;
.LBB0_2947:
	s_add_i32 s27, s6, 2
	s_add_u32 s28, s4, 0x80
	s_addc_u32 s7, s5, 0
	s_add_i32 s30, 0, 0x10000
	s_cmp_eq_u32 s96, s6
	s_cselect_b32 s7, s1, s7
	s_cselect_b32 s6, s0, s28
	v_add_u32_e32 v145, s30, v172
	s_cselect_b32 s29, s61, s9
	s_cselect_b32 s28, s60, s8
	s_add_i32 s31, 0, 0x14000
	ds_read_b128 v[146:149], v145
	ds_read_b128 v[150:153], v145 offset:1024
	ds_read_b128 v[154:157], v145 offset:2048
	ds_read_b128 v[178:181], v145 offset:3072
	v_add_u32_e32 v145, s31, v172
	ds_read_b128 v[182:185], v145
	ds_read_b128 v[186:189], v145 offset:1024
	ds_read_b128 v[190:193], v145 offset:2048
	ds_read_b128 v[194:197], v145 offset:3072
	v_lshl_add_u64 v[216:217], s[4:5], 0, v[142:143]
	s_add_i32 m0, s15, 0xc000
	ds_read_b128 v[198:201], v175
	ds_read_b128 v[202:205], v175 offset:1024
	ds_read_b128 v[206:209], v175 offset:2048
	ds_read_b128 v[222:225], v175 offset:3072
	ds_read_b128 v[226:229], v175 offset:4096
	ds_read_b128 v[230:233], v175 offset:5120
	ds_read_b128 v[234:237], v175 offset:6144
	ds_read_b128 v[238:241], v175 offset:7168
	global_load_lds_dwordx4 v[216:217], off
	v_lshl_add_u64 v[216:217], s[4:5], 0, v[140:141]
	s_add_i32 m0, s15, 0xe000
	s_nop 0
	global_load_lds_dwordx4 v[216:217], off
	s_waitcnt vmcnt(8)
	s_waitcnt lgkmcnt(0)
	s_barrier
	s_waitcnt lgkmcnt(0)
	v_mfma_f32_16x16x32_bf16 v[126:129], v[146:149], v[198:201], v[126:129]
	v_mfma_f32_16x16x32_bf16 v[122:125], v[154:157], v[198:201], v[122:125]
	v_mfma_f32_16x16x32_bf16 v[110:113], v[146:149], v[206:209], v[110:113]
	v_mfma_f32_16x16x32_bf16 v[106:109], v[154:157], v[206:209], v[106:109]
	v_mfma_f32_16x16x32_bf16 v[94:97], v[146:149], v[226:229], v[94:97]
	v_mfma_f32_16x16x32_bf16 v[90:93], v[154:157], v[226:229], v[90:93]
	v_mfma_f32_16x16x32_bf16 v[78:81], v[146:149], v[234:237], v[78:81]
	v_mfma_f32_16x16x32_bf16 v[74:77], v[154:157], v[234:237], v[74:77]
	v_mfma_f32_16x16x32_bf16 v[126:129], v[150:153], v[202:205], v[126:129]
	v_mfma_f32_16x16x32_bf16 v[122:125], v[178:181], v[202:205], v[122:125]
	v_mfma_f32_16x16x32_bf16 v[110:113], v[150:153], v[222:225], v[110:113]
	v_mfma_f32_16x16x32_bf16 v[106:109], v[178:181], v[222:225], v[106:109]
	v_mfma_f32_16x16x32_bf16 v[94:97], v[150:153], v[230:233], v[94:97]
	v_mfma_f32_16x16x32_bf16 v[90:93], v[178:181], v[230:233], v[90:93]
	v_mfma_f32_16x16x32_bf16 v[78:81], v[150:153], v[238:241], v[78:81]
	v_mfma_f32_16x16x32_bf16 v[74:77], v[178:181], v[238:241], v[74:77]
	v_mfma_f32_16x16x32_bf16 v[118:121], v[182:185], v[198:201], v[118:121]
	v_mfma_f32_16x16x32_bf16 v[114:117], v[190:193], v[198:201], v[114:117]
	v_mfma_f32_16x16x32_bf16 v[102:105], v[182:185], v[206:209], v[102:105]
	v_mfma_f32_16x16x32_bf16 v[98:101], v[190:193], v[206:209], v[98:101]
	v_mfma_f32_16x16x32_bf16 v[86:89], v[182:185], v[226:229], v[86:89]
	v_mfma_f32_16x16x32_bf16 v[82:85], v[190:193], v[226:229], v[82:85]
	v_mfma_f32_16x16x32_bf16 v[70:73], v[182:185], v[234:237], v[70:73]
	v_mfma_f32_16x16x32_bf16 v[66:69], v[190:193], v[234:237], v[66:69]
	v_mfma_f32_16x16x32_bf16 v[118:121], v[186:189], v[202:205], v[118:121]
	v_mfma_f32_16x16x32_bf16 v[114:117], v[194:197], v[202:205], v[114:117]
	v_mfma_f32_16x16x32_bf16 v[102:105], v[186:189], v[222:225], v[102:105]
	v_mfma_f32_16x16x32_bf16 v[98:101], v[194:197], v[222:225], v[98:101]
	v_mfma_f32_16x16x32_bf16 v[86:89], v[186:189], v[230:233], v[86:89]
	v_mfma_f32_16x16x32_bf16 v[82:85], v[194:197], v[230:233], v[82:85]
	v_mfma_f32_16x16x32_bf16 v[70:73], v[186:189], v[238:241], v[70:73]
	v_mfma_f32_16x16x32_bf16 v[66:69], v[194:197], v[238:241], v[66:69]
	s_barrier
	s_add_i32 s30, s30, s14
	v_lshl_add_u64 v[216:217], s[28:29], 0, v[134:135]
	s_mov_b32 m0, s30
	ds_read_b128 v[198:201], v175 offset:16384
	ds_read_b128 v[202:205], v175 offset:17408
	ds_read_b128 v[206:209], v175 offset:18432
	ds_read_b128 v[222:225], v175 offset:19456
	ds_read_b128 v[226:229], v175 offset:20480
	ds_read_b128 v[230:233], v175 offset:21504
	ds_read_b128 v[234:237], v175 offset:22528
	ds_read_b128 v[238:241], v175 offset:23552
	global_load_lds_dwordx4 v[216:217], off
	s_add_i32 m0, s30, 0x2000
	v_lshl_add_u64 v[218:219], s[28:29], 0, v[130:131]
	s_add_u32 s28, s28, s48
	s_addc_u32 s29, s29, s49
	s_add_i32 s30, s31, s14
	global_load_lds_dwordx4 v[218:219], off
	v_lshl_add_u64 v[242:243], s[28:29], 0, v[134:135]
	s_mov_b32 m0, s30
	v_lshl_add_u64 v[244:245], s[28:29], 0, v[130:131]
	global_load_lds_dwordx4 v[242:243], off
	s_add_i32 m0, s30, 0x2000
	v_lshl_add_u64 v[246:247], s[6:7], 0, v[136:137]
	global_load_lds_dwordx4 v[244:245], off
	s_mov_b32 m0, s15
	v_lshl_add_u64 v[248:249], s[6:7], 0, v[132:133]
	global_load_lds_dwordx4 v[246:247], off
	s_mov_b32 m0, s58
	s_nop 0
	global_load_lds_dwordx4 v[248:249], off
	s_waitcnt vmcnt(8)
	s_waitcnt lgkmcnt(0)
	s_barrier
; #define PG8_STAGE(bufoff, gbase, voff) do { _Pragma("unroll") for (int _i = 0; _i < 2; ++_i) \
;         __builtin_amdgcn_global_load_lds((const unsigned*)((const char*)(gbase) + (voff)[_i]), (LAS unsigned*)(lds + (bufoff) + ldsw + _i * 8192), 16, 0, 0); } while (0)
; #define PG8_LDA(dst, b, h) do { _Pragma("unroll") for (int m = 0; m < 4; ++m) _Pragma("unroll") for (int k = 0; k < 2; ++k) dst[m][k] = *(const LAS bf16x8*)(lds + PG8_SA(b, h) + aoff + m * 2048 + k * 1024); } while (0)
; #define PG8_LDB(dst, b, h) do { _Pragma("unroll") for (int n = 0; n < 2; ++n) _Pragma("unroll") for (int k = 0; k < 2; ++k) dst[n][k] = *(const LAS bf16x8*)(lds + PG8_SB(b, h) + boff + n * 2048 + k * 1024); } while (0)
; #define PG8_MMA(ai, bj, At, Bt) do { __builtin_amdgcn_s_setprio(1); _Pragma("unroll") for (int m = 0; m < 4; ++m) _Pragma("unroll") for (int n = 0; n < 2; ++n) _Pragma("unroll") for (int k = 0; k < 2; ++k) \
;         acc[ai][bj][m][n] = __builtin_amdgcn_mfma_f32_16x16x32_bf16(Bt[n][k], At[m][k], acc[ai][bj][m][n], 0, 0, 0); __builtin_amdgcn_s_setprio(0); } while (0)
; #define PG8_WAIT_V(n) asm volatile("s_waitcnt vmcnt(" #n ")" ::: "memory")
; #define PG8_WAIT_L(n) asm volatile("s_waitcnt lgkmcnt(" #n ")" ::: "memory")
; #define PG8_BAR __builtin_amdgcn_s_barrier()
; #define PG8_SCHED __builtin_amdgcn_sched_barrier(0)
; template <class Epi>
; __device__ __forceinline__ void gemm_phase(LAS unsigned char* lds, const Gemm g, const StaticOrder& S, const Epi& E) {
;     ...
;             PG8_WAIT_V(8); PG8_WAIT_L(0); PG8_BAR; PG8_MMA(1, 0, At, B0); PG8_MMA(1, 1, At, B1); PG8_BAR; PG8_SCHED;
;             PG8_LDB(B0, 1, 0); PG8_LDB(B1, 1, 1); PG8_SCHED; PG8_LDA(At, 1, 0); PG8_STAGE(PG8_SA(0, 1), a2 + hstepA, voffA);
;             PG8_WAIT_V(8); PG8_WAIT_L(0); PG8_BAR; PG8_MMA(0, 0, At, B0); PG8_MMA(0, 1, At, B1); PG8_BAR; PG8_SCHED;
	s_waitcnt lgkmcnt(0)
	v_mfma_f32_16x16x32_bf16 v[60:63], v[146:149], v[198:201], v[60:63]
	v_mfma_f32_16x16x32_bf16 v[56:59], v[154:157], v[198:201], v[56:59]
	v_mfma_f32_16x16x32_bf16 v[44:47], v[146:149], v[206:209], v[44:47]
	v_mfma_f32_16x16x32_bf16 v[40:43], v[154:157], v[206:209], v[40:43]
	v_mfma_f32_16x16x32_bf16 v[28:31], v[146:149], v[226:229], v[28:31]
	v_mfma_f32_16x16x32_bf16 v[24:27], v[154:157], v[226:229], v[24:27]
	v_mfma_f32_16x16x32_bf16 v[12:15], v[146:149], v[234:237], v[12:15]
	v_mfma_f32_16x16x32_bf16 v[8:11], v[154:157], v[234:237], v[8:11]
	v_mfma_f32_16x16x32_bf16 v[60:63], v[150:153], v[202:205], v[60:63]
	v_mfma_f32_16x16x32_bf16 v[56:59], v[178:181], v[202:205], v[56:59]
	v_mfma_f32_16x16x32_bf16 v[44:47], v[150:153], v[222:225], v[44:47]
	v_mfma_f32_16x16x32_bf16 v[40:43], v[178:181], v[222:225], v[40:43]
	v_mfma_f32_16x16x32_bf16 v[28:31], v[150:153], v[230:233], v[28:31]
	v_mfma_f32_16x16x32_bf16 v[24:27], v[178:181], v[230:233], v[24:27]
	v_mfma_f32_16x16x32_bf16 v[12:15], v[150:153], v[238:241], v[12:15]
	v_mfma_f32_16x16x32_bf16 v[8:11], v[178:181], v[238:241], v[8:11]
	v_mfma_f32_16x16x32_bf16 v[52:55], v[182:185], v[198:201], v[52:55]
	v_mfma_f32_16x16x32_bf16 v[48:51], v[190:193], v[198:201], v[48:51]
	v_mfma_f32_16x16x32_bf16 v[36:39], v[182:185], v[206:209], v[36:39]
	v_mfma_f32_16x16x32_bf16 v[32:35], v[190:193], v[206:209], v[32:35]
	v_mfma_f32_16x16x32_bf16 v[20:23], v[182:185], v[226:229], v[20:23]
	v_mfma_f32_16x16x32_bf16 v[16:19], v[190:193], v[226:229], v[16:19]
	v_mfma_f32_16x16x32_bf16 v[4:7], v[182:185], v[234:237], v[4:7]
	v_mfma_f32_16x16x32_bf16 v[0:3], v[190:193], v[234:237], v[0:3]
	v_mfma_f32_16x16x32_bf16 v[52:55], v[186:189], v[202:205], v[52:55]
	v_mfma_f32_16x16x32_bf16 v[48:51], v[194:197], v[202:205], v[48:51]
	v_mfma_f32_16x16x32_bf16 v[36:39], v[186:189], v[222:225], v[36:39]
	v_mfma_f32_16x16x32_bf16 v[32:35], v[194:197], v[222:225], v[32:35]
	v_mfma_f32_16x16x32_bf16 v[20:23], v[186:189], v[230:233], v[20:23]
	v_mfma_f32_16x16x32_bf16 v[16:19], v[194:197], v[230:233], v[16:19]
	v_mfma_f32_16x16x32_bf16 v[4:7], v[186:189], v[238:241], v[4:7]
	v_mfma_f32_16x16x32_bf16 v[0:3], v[194:197], v[238:241], v[0:3]
	s_barrier
	s_add_i32 s28, 0, 0x18000
	v_add_u32_e32 v145, s28, v172
	s_add_i32 s29, 0, 0x1c000
	ds_read_b128 v[146:149], v145
	ds_read_b128 v[150:153], v145 offset:1024
	ds_read_b128 v[154:157], v145 offset:2048
	ds_read_b128 v[178:181], v145 offset:3072
	v_add_u32_e32 v145, s29, v172
	ds_read_b128 v[182:185], v145
	ds_read_b128 v[186:189], v145 offset:1024
	ds_read_b128 v[190:193], v145 offset:2048
	ds_read_b128 v[194:197], v145 offset:3072
	s_add_u32 s6, s6, s46
	s_addc_u32 s7, s7, s47
	s_mov_b32 m0, s59
	v_lshl_add_u64 v[250:251], s[6:7], 0, v[136:137]
	ds_read_b128 v[198:201], v175 offset:32768
	ds_read_b128 v[202:205], v175 offset:33792
	ds_read_b128 v[206:209], v175 offset:34816
	ds_read_b128 v[222:225], v175 offset:35840
	ds_read_b128 v[226:229], v175 offset:36864
	ds_read_b128 v[230:233], v175 offset:37888
	ds_read_b128 v[234:237], v175 offset:38912
	ds_read_b128 v[238:241], v175 offset:39936
	global_load_lds_dwordx4 v[250:251], off
	v_lshl_add_u64 v[250:251], s[6:7], 0, v[132:133]
	s_mov_b32 m0, s68
	s_nop 0
	global_load_lds_dwordx4 v[250:251], off
	s_waitcnt vmcnt(8)
	s_waitcnt lgkmcnt(0)
	s_barrier
	s_waitcnt lgkmcnt(0)
	v_mfma_f32_16x16x32_bf16 v[126:129], v[146:149], v[198:201], v[126:129]
	v_mfma_f32_16x16x32_bf16 v[122:125], v[154:157], v[198:201], v[122:125]
	v_mfma_f32_16x16x32_bf16 v[110:113], v[146:149], v[206:209], v[110:113]
	v_mfma_f32_16x16x32_bf16 v[106:109], v[154:157], v[206:209], v[106:109]
	v_mfma_f32_16x16x32_bf16 v[94:97], v[146:149], v[226:229], v[94:97]
	v_mfma_f32_16x16x32_bf16 v[90:93], v[154:157], v[226:229], v[90:93]
	v_mfma_f32_16x16x32_bf16 v[78:81], v[146:149], v[234:237], v[78:81]
	v_mfma_f32_16x16x32_bf16 v[74:77], v[154:157], v[234:237], v[74:77]
	v_mfma_f32_16x16x32_bf16 v[126:129], v[150:153], v[202:205], v[126:129]
	v_mfma_f32_16x16x32_bf16 v[122:125], v[178:181], v[202:205], v[122:125]
	v_mfma_f32_16x16x32_bf16 v[110:113], v[150:153], v[222:225], v[110:113]
	v_mfma_f32_16x16x32_bf16 v[106:109], v[178:181], v[222:225], v[106:109]
	v_mfma_f32_16x16x32_bf16 v[94:97], v[150:153], v[230:233], v[94:97]
	v_mfma_f32_16x16x32_bf16 v[90:93], v[178:181], v[230:233], v[90:93]
	v_mfma_f32_16x16x32_bf16 v[78:81], v[150:153], v[238:241], v[78:81]
	v_mfma_f32_16x16x32_bf16 v[74:77], v[178:181], v[238:241], v[74:77]
	v_mfma_f32_16x16x32_bf16 v[118:121], v[182:185], v[198:201], v[118:121]
	v_mfma_f32_16x16x32_bf16 v[114:117], v[190:193], v[198:201], v[114:117]
	v_mfma_f32_16x16x32_bf16 v[102:105], v[182:185], v[206:209], v[102:105]
	v_mfma_f32_16x16x32_bf16 v[98:101], v[190:193], v[206:209], v[98:101]
	v_mfma_f32_16x16x32_bf16 v[86:89], v[182:185], v[226:229], v[86:89]
	v_mfma_f32_16x16x32_bf16 v[82:85], v[190:193], v[226:229], v[82:85]
	v_mfma_f32_16x16x32_bf16 v[70:73], v[182:185], v[234:237], v[70:73]
	v_mfma_f32_16x16x32_bf16 v[66:69], v[190:193], v[234:237], v[66:69]
	v_mfma_f32_16x16x32_bf16 v[118:121], v[186:189], v[202:205], v[118:121]
	v_mfma_f32_16x16x32_bf16 v[114:117], v[194:197], v[202:205], v[114:117]
	v_mfma_f32_16x16x32_bf16 v[102:105], v[186:189], v[222:225], v[102:105]
	v_mfma_f32_16x16x32_bf16 v[98:101], v[194:197], v[222:225], v[98:101]
	v_mfma_f32_16x16x32_bf16 v[86:89], v[186:189], v[230:233], v[86:89]
	v_mfma_f32_16x16x32_bf16 v[82:85], v[194:197], v[230:233], v[82:85]
	v_mfma_f32_16x16x32_bf16 v[70:73], v[186:189], v[238:241], v[70:73]
	v_mfma_f32_16x16x32_bf16 v[66:69], v[194:197], v[238:241], v[66:69]
	s_barrier
; #define PG8_STAGE(bufoff, gbase, voff) do { _Pragma("unroll") for (int _i = 0; _i < 2; ++_i) \
;         __builtin_amdgcn_global_load_lds((const unsigned*)((const char*)(gbase) + (voff)[_i]), (LAS unsigned*)(lds + (bufoff) + ldsw + _i * 8192), 16, 0, 0); } while (0)
; #define PG8_LDA(dst, b, h) do { _Pragma("unroll") for (int m = 0; m < 4; ++m) _Pragma("unroll") for (int k = 0; k < 2; ++k) dst[m][k] = *(const LAS bf16x8*)(lds + PG8_SA(b, h) + aoff + m * 2048 + k * 1024); } while (0)
; #define PG8_MMA(ai, bj, At, Bt) do { __builtin_amdgcn_s_setprio(1); _Pragma("unroll") for (int m = 0; m < 4; ++m) _Pragma("unroll") for (int n = 0; n < 2; ++n) _Pragma("unroll") for (int k = 0; k < 2; ++k) \
;         acc[ai][bj][m][n] = __builtin_amdgcn_mfma_f32_16x16x32_bf16(Bt[n][k], At[m][k], acc[ai][bj][m][n], 0, 0, 0); __builtin_amdgcn_s_setprio(0); } while (0)
; #define PG8_WAIT_V(n) asm volatile("s_waitcnt vmcnt(" #n ")" ::: "memory")
; #define PG8_WAIT_L(n) asm volatile("s_waitcnt lgkmcnt(" #n ")" ::: "memory")
; #define PG8_BAR __builtin_amdgcn_s_barrier()
; #define PG8_SCHED __builtin_amdgcn_sched_barrier(0)
; template <class Epi>
; __device__ __forceinline__ void gemm_phase(LAS unsigned char* lds, const Gemm g, const StaticOrder& S, const Epi& E) {
;     ...
;             PG8_LDA(At, 1, 1); PG8_STAGE(PG8_SB(1, 0), b3, voffB); PG8_STAGE(PG8_SB(1, 1), b3 + hstepB, voffB); PG8_STAGE(PG8_SA(1, 0), a3, voffA);
;             PG8_WAIT_V(8); PG8_WAIT_L(0); PG8_BAR; PG8_MMA(1, 0, At, B0); PG8_MMA(1, 1, At, B1); PG8_BAR; PG8_SCHED;
;         }
	s_add_i32 s6, s28, s14
	v_lshl_add_u64 v[216:217], v[216:217], 0, s[82:83]
	s_mov_b32 m0, s6
	ds_read_b128 v[198:201], v175 offset:49152
	ds_read_b128 v[202:205], v175 offset:50176
	ds_read_b128 v[206:209], v175 offset:51200
	ds_read_b128 v[222:225], v175 offset:52224
	ds_read_b128 v[226:229], v175 offset:53248
	ds_read_b128 v[230:233], v175 offset:54272
	ds_read_b128 v[234:237], v175 offset:55296
	ds_read_b128 v[238:241], v175 offset:56320
	global_load_lds_dwordx4 v[216:217], off
	v_lshl_add_u64 v[216:217], v[218:219], 0, s[82:83]
	s_add_i32 m0, s6, 0x2000
	s_add_i32 s6, s29, s14
	global_load_lds_dwordx4 v[216:217], off
	v_lshl_add_u64 v[216:217], v[242:243], 0, s[82:83]
	s_mov_b32 m0, s6
	s_nop 0
	global_load_lds_dwordx4 v[216:217], off
	v_lshl_add_u64 v[216:217], v[244:245], 0, s[82:83]
	s_add_i32 m0, s6, 0x2000
	s_nop 0
	global_load_lds_dwordx4 v[216:217], off
	v_lshl_add_u64 v[216:217], v[246:247], 0, s[82:83]
	s_mov_b32 m0, s69
	s_nop 0
	global_load_lds_dwordx4 v[216:217], off
	v_lshl_add_u64 v[216:217], v[248:249], 0, s[82:83]
	s_mov_b32 m0, s84
	s_nop 0
	global_load_lds_dwordx4 v[216:217], off
	s_waitcnt vmcnt(8)
	s_waitcnt lgkmcnt(0)
	s_barrier
	s_waitcnt lgkmcnt(0)
	v_mfma_f32_16x16x32_bf16 v[60:63], v[146:149], v[198:201], v[60:63]
	v_mfma_f32_16x16x32_bf16 v[56:59], v[154:157], v[198:201], v[56:59]
	v_mfma_f32_16x16x32_bf16 v[44:47], v[146:149], v[206:209], v[44:47]
	v_mfma_f32_16x16x32_bf16 v[40:43], v[154:157], v[206:209], v[40:43]
	v_mfma_f32_16x16x32_bf16 v[28:31], v[146:149], v[226:229], v[28:31]
	v_mfma_f32_16x16x32_bf16 v[24:27], v[154:157], v[226:229], v[24:27]
	v_mfma_f32_16x16x32_bf16 v[12:15], v[146:149], v[234:237], v[12:15]
	v_mfma_f32_16x16x32_bf16 v[8:11], v[154:157], v[234:237], v[8:11]
	v_mfma_f32_16x16x32_bf16 v[60:63], v[150:153], v[202:205], v[60:63]
	v_mfma_f32_16x16x32_bf16 v[56:59], v[178:181], v[202:205], v[56:59]
	v_mfma_f32_16x16x32_bf16 v[44:47], v[150:153], v[222:225], v[44:47]
	v_mfma_f32_16x16x32_bf16 v[40:43], v[178:181], v[222:225], v[40:43]
	v_mfma_f32_16x16x32_bf16 v[28:31], v[150:153], v[230:233], v[28:31]
	v_mfma_f32_16x16x32_bf16 v[24:27], v[178:181], v[230:233], v[24:27]
	v_mfma_f32_16x16x32_bf16 v[12:15], v[150:153], v[238:241], v[12:15]
	v_mfma_f32_16x16x32_bf16 v[8:11], v[178:181], v[238:241], v[8:11]
	v_mfma_f32_16x16x32_bf16 v[52:55], v[182:185], v[198:201], v[52:55]
	v_mfma_f32_16x16x32_bf16 v[48:51], v[190:193], v[198:201], v[48:51]
	v_mfma_f32_16x16x32_bf16 v[36:39], v[182:185], v[206:209], v[36:39]
	v_mfma_f32_16x16x32_bf16 v[32:35], v[190:193], v[206:209], v[32:35]
	v_mfma_f32_16x16x32_bf16 v[20:23], v[182:185], v[226:229], v[20:23]
	v_mfma_f32_16x16x32_bf16 v[16:19], v[190:193], v[226:229], v[16:19]
	v_mfma_f32_16x16x32_bf16 v[4:7], v[182:185], v[234:237], v[4:7]
	v_mfma_f32_16x16x32_bf16 v[0:3], v[190:193], v[234:237], v[0:3]
	v_mfma_f32_16x16x32_bf16 v[52:55], v[186:189], v[202:205], v[52:55]
	v_mfma_f32_16x16x32_bf16 v[48:51], v[194:197], v[202:205], v[48:51]
	v_mfma_f32_16x16x32_bf16 v[36:39], v[186:189], v[222:225], v[36:39]
	v_mfma_f32_16x16x32_bf16 v[32:35], v[194:197], v[222:225], v[32:35]
	v_mfma_f32_16x16x32_bf16 v[20:23], v[186:189], v[230:233], v[20:23]
	v_mfma_f32_16x16x32_bf16 v[16:19], v[194:197], v[230:233], v[16:19]
	v_mfma_f32_16x16x32_bf16 v[4:7], v[186:189], v[238:241], v[4:7]
	v_mfma_f32_16x16x32_bf16 v[0:3], v[194:197], v[238:241], v[0:3]
	s_add_u32 s8, s8, 0x100
	s_addc_u32 s9, s9, 0
	s_add_u32 s4, s4, 0x100
	s_addc_u32 s5, s5, 0
	s_cmp_ge_i32 s27, s20
	s_mov_b32 s6, s27
	s_barrier
	s_cbranch_scc0 .LBB0_2947

; #define PG8_STAGE(bufoff, gbase, voff) do { _Pragma("unroll") for (int _i = 0; _i < 2; ++_i) \
;         __builtin_amdgcn_global_load_lds((const unsigned*)((const char*)(gbase) + (voff)[_i]), (LAS unsigned*)(lds + (bufoff) + ldsw + _i * 8192), 16, 0, 0); } while (0)
; #define PG8_LDA(dst, b, h) do { _Pragma("unroll") for (int m = 0; m < 4; ++m) _Pragma("unroll") for (int k = 0; k < 2; ++k) dst[m][k] = *(const LAS bf16x8*)(lds + PG8_SA(b, h) + aoff + m * 2048 + k * 1024); } while (0)
; #define PG8_LDB(dst, b, h) do { _Pragma("unroll") for (int n = 0; n < 2; ++n) _Pragma("unroll") for (int k = 0; k < 2; ++k) dst[n][k] = *(const LAS bf16x8*)(lds + PG8_SB(b, h) + boff + n * 2048 + k * 1024); } while (0)
; #define PG8_MMA(ai, bj, At, Bt) do { __builtin_amdgcn_s_setprio(1); _Pragma("unroll") for (int m = 0; m < 4; ++m) _Pragma("unroll") for (int n = 0; n < 2; ++n) _Pragma("unroll") for (int k = 0; k < 2; ++k) \
;         acc[ai][bj][m][n] = __builtin_amdgcn_mfma_f32_16x16x32_bf16(Bt[n][k], At[m][k], acc[ai][bj][m][n], 0, 0, 0); __builtin_amdgcn_s_setprio(0); } while (0)
; #define PG8_WAIT_V(n) asm volatile("s_waitcnt vmcnt(" #n ")" ::: "memory")
; #define PG8_WAIT_L(n) asm volatile("s_waitcnt lgkmcnt(" #n ")" ::: "memory")
; #define PG8_BAR __builtin_amdgcn_s_barrier()
; #define PG8_SCHED __builtin_amdgcn_sched_barrier(0)
; template <class Epi>
; __device__ __forceinline__ void gemm_phase(LAS unsigned char* lds, const Gemm g, const StaticOrder& S, const Epi& E) {
;     ...
;         for (int t = 0; t < nt; t += 2) {
;             const bool last = (t == nt - 2);
;             const char* a1 = cA + (size_t)(t + 1) * kstep;
;             const char* a2 = last ? nA : cA + (size_t)(t + 2) * kstep; const char* b2 = last ? nB : cB + (size_t)(t + 2) * kstep;
;             const char* a3 = a2 + kstep; const char* b3 = b2 + kstep;
;             PG8_LDB(B0, 0, 0); PG8_LDB(B1, 0, 1); PG8_SCHED; PG8_LDA(At, 0, 0); PG8_STAGE(PG8_SA(1, 1), a1 + hstepA, voffA);
;             PG8_WAIT_V(8); PG8_WAIT_L(0); PG8_BAR; PG8_MMA(0, 0, At, B0); PG8_MMA(0, 1, At, B1); PG8_BAR; PG8_SCHED;
;             PG8_LDA(At, 0, 1); PG8_STAGE(PG8_SB(0, 0), b2, voffB); PG8_STAGE(PG8_SB(0, 1), b2 + hstepB, voffB); PG8_STAGE(PG8_SA(0, 0), a2, voffA);
;             PG8_WAIT_V(8); PG8_WAIT_L(0); PG8_BAR; PG8_MMA(1, 0, At, B0); PG8_MMA(1, 1, At, B1); PG8_BAR; PG8_SCHED;
.LBB0_3152:
	s_add_i32 s28, s10, 2
	s_add_u32 s29, s58, 0x80
	s_addc_u32 s11, s59, 0
	s_add_i32 s34, 0, 0x10000
	s_cmp_eq_u32 s65, s10
	s_cselect_b32 s11, s1, s11
	s_cselect_b32 s10, s0, s29
	s_cselect_b32 s31, s7, s27
	s_cselect_b32 s30, s6, s26
	s_add_i32 s29, 0, 0x14000
	v_add_u32_e32 v142, s34, v181
	v_add_u32_e32 v186, s29, v181
	ds_read_b128 v[130:133], v142
	ds_read_b128 v[134:137], v142 offset:1024
	ds_read_b128 v[138:141], v142 offset:2048
	ds_read_b128 v[142:145], v142 offset:3072
	ds_read_b128 v[146:149], v186
	ds_read_b128 v[150:153], v186 offset:1024
	ds_read_b128 v[154:157], v186 offset:2048
	ds_read_b128 v[186:189], v186 offset:3072
	v_lshl_add_u64 v[202:203], s[58:59], 0, v[184:185]
	s_add_i32 m0, s21, 0xc000
	ds_read_b128 v[190:193], v204
	ds_read_b128 v[194:197], v204 offset:1024
	ds_read_b128 v[198:201], v204 offset:2048
	ds_read_b128 v[206:209], v204 offset:3072
	ds_read_b128 v[222:225], v204 offset:4096
	ds_read_b128 v[226:229], v204 offset:5120
	ds_read_b128 v[230:233], v204 offset:6144
	ds_read_b128 v[234:237], v204 offset:7168
	global_load_lds_dwordx4 v[202:203], off
	v_lshl_add_u64 v[202:203], s[58:59], 0, v[182:183]
	s_add_i32 m0, s21, 0xe000
	s_nop 0
	global_load_lds_dwordx4 v[202:203], off
	s_waitcnt vmcnt(8)
	s_waitcnt lgkmcnt(0)
	s_barrier
	s_waitcnt lgkmcnt(0)
	v_mfma_f32_16x16x32_bf16 v[126:129], v[130:133], v[190:193], v[126:129]
	v_mfma_f32_16x16x32_bf16 v[122:125], v[138:141], v[190:193], v[122:125]
	v_mfma_f32_16x16x32_bf16 v[110:113], v[130:133], v[198:201], v[110:113]
	v_mfma_f32_16x16x32_bf16 v[106:109], v[138:141], v[198:201], v[106:109]
	v_mfma_f32_16x16x32_bf16 v[94:97], v[130:133], v[222:225], v[94:97]
	v_mfma_f32_16x16x32_bf16 v[90:93], v[138:141], v[222:225], v[90:93]
	v_mfma_f32_16x16x32_bf16 v[78:81], v[130:133], v[230:233], v[78:81]
	v_mfma_f32_16x16x32_bf16 v[74:77], v[138:141], v[230:233], v[74:77]
	v_mfma_f32_16x16x32_bf16 v[126:129], v[134:137], v[194:197], v[126:129]
	v_mfma_f32_16x16x32_bf16 v[122:125], v[142:145], v[194:197], v[122:125]
	v_mfma_f32_16x16x32_bf16 v[110:113], v[134:137], v[206:209], v[110:113]
	v_mfma_f32_16x16x32_bf16 v[106:109], v[142:145], v[206:209], v[106:109]
	v_mfma_f32_16x16x32_bf16 v[94:97], v[134:137], v[226:229], v[94:97]
	v_mfma_f32_16x16x32_bf16 v[90:93], v[142:145], v[226:229], v[90:93]
	v_mfma_f32_16x16x32_bf16 v[78:81], v[134:137], v[234:237], v[78:81]
	v_mfma_f32_16x16x32_bf16 v[74:77], v[142:145], v[234:237], v[74:77]
	v_mfma_f32_16x16x32_bf16 v[118:121], v[146:149], v[190:193], v[118:121]
	v_mfma_f32_16x16x32_bf16 v[114:117], v[154:157], v[190:193], v[114:117]
	v_mfma_f32_16x16x32_bf16 v[102:105], v[146:149], v[198:201], v[102:105]
	v_mfma_f32_16x16x32_bf16 v[98:101], v[154:157], v[198:201], v[98:101]
	v_mfma_f32_16x16x32_bf16 v[86:89], v[146:149], v[222:225], v[86:89]
	v_mfma_f32_16x16x32_bf16 v[82:85], v[154:157], v[222:225], v[82:85]
	v_mfma_f32_16x16x32_bf16 v[70:73], v[146:149], v[230:233], v[70:73]
	v_mfma_f32_16x16x32_bf16 v[66:69], v[154:157], v[230:233], v[66:69]
	v_mfma_f32_16x16x32_bf16 v[118:121], v[150:153], v[194:197], v[118:121]
	v_mfma_f32_16x16x32_bf16 v[114:117], v[186:189], v[194:197], v[114:117]
	v_mfma_f32_16x16x32_bf16 v[102:105], v[150:153], v[206:209], v[102:105]
	v_mfma_f32_16x16x32_bf16 v[98:101], v[186:189], v[206:209], v[98:101]
	v_mfma_f32_16x16x32_bf16 v[86:89], v[150:153], v[226:229], v[86:89]
	v_mfma_f32_16x16x32_bf16 v[82:85], v[186:189], v[226:229], v[82:85]
	v_mfma_f32_16x16x32_bf16 v[70:73], v[150:153], v[234:237], v[70:73]
	v_mfma_f32_16x16x32_bf16 v[66:69], v[186:189], v[234:237], v[66:69]
	s_barrier
	s_add_i32 s34, s34, s20
	v_lshl_add_u64 v[202:203], s[30:31], 0, v[176:177]
	s_mov_b32 m0, s34
	ds_read_b128 v[190:193], v204 offset:16384
	ds_read_b128 v[194:197], v204 offset:17408
	ds_read_b128 v[198:201], v204 offset:18432
	ds_read_b128 v[206:209], v204 offset:19456
	ds_read_b128 v[222:225], v204 offset:20480
	ds_read_b128 v[226:229], v204 offset:21504
	ds_read_b128 v[230:233], v204 offset:22528
	ds_read_b128 v[234:237], v204 offset:23552
	global_load_lds_dwordx4 v[202:203], off
	s_add_i32 m0, s34, 0x2000
	v_lshl_add_u64 v[216:217], s[30:31], 0, v[172:173]
	s_add_u32 s30, s30, s42
	s_addc_u32 s31, s31, s43
	s_add_i32 s29, s29, s20
	global_load_lds_dwordx4 v[216:217], off
	v_lshl_add_u64 v[218:219], s[30:31], 0, v[176:177]
	s_mov_b32 m0, s29
	v_lshl_add_u64 v[238:239], s[30:31], 0, v[172:173]
	global_load_lds_dwordx4 v[218:219], off
	s_add_i32 m0, s29, 0x2000
	v_lshl_add_u64 v[240:241], s[10:11], 0, v[178:179]
	global_load_lds_dwordx4 v[238:239], off
	s_mov_b32 m0, s21
	v_lshl_add_u64 v[242:243], s[10:11], 0, v[174:175]
	global_load_lds_dwordx4 v[240:241], off
	s_mov_b32 m0, s22
	s_nop 0
	global_load_lds_dwordx4 v[242:243], off
	s_waitcnt vmcnt(8)
	s_waitcnt lgkmcnt(0)
	s_barrier
; #define PG8_STAGE(bufoff, gbase, voff) do { _Pragma("unroll") for (int _i = 0; _i < 2; ++_i) \
;         __builtin_amdgcn_global_load_lds((const unsigned*)((const char*)(gbase) + (voff)[_i]), (LAS unsigned*)(lds + (bufoff) + ldsw + _i * 8192), 16, 0, 0); } while (0)
; #define PG8_LDA(dst, b, h) do { _Pragma("unroll") for (int m = 0; m < 4; ++m) _Pragma("unroll") for (int k = 0; k < 2; ++k) dst[m][k] = *(const LAS bf16x8*)(lds + PG8_SA(b, h) + aoff + m * 2048 + k * 1024); } while (0)
; #define PG8_LDB(dst, b, h) do { _Pragma("unroll") for (int n = 0; n < 2; ++n) _Pragma("unroll") for (int k = 0; k < 2; ++k) dst[n][k] = *(const LAS bf16x8*)(lds + PG8_SB(b, h) + boff + n * 2048 + k * 1024); } while (0)
; #define PG8_MMA(ai, bj, At, Bt) do { __builtin_amdgcn_s_setprio(1); _Pragma("unroll") for (int m = 0; m < 4; ++m) _Pragma("unroll") for (int n = 0; n < 2; ++n) _Pragma("unroll") for (int k = 0; k < 2; ++k) \
;         acc[ai][bj][m][n] = __builtin_amdgcn_mfma_f32_16x16x32_bf16(Bt[n][k], At[m][k], acc[ai][bj][m][n], 0, 0, 0); __builtin_amdgcn_s_setprio(0); } while (0)
; #define PG8_WAIT_V(n) asm volatile("s_waitcnt vmcnt(" #n ")" ::: "memory")
; #define PG8_WAIT_L(n) asm volatile("s_waitcnt lgkmcnt(" #n ")" ::: "memory")
; #define PG8_BAR __builtin_amdgcn_s_barrier()
; #define PG8_SCHED __builtin_amdgcn_sched_barrier(0)
; template <class Epi>
; __device__ __forceinline__ void gemm_phase(LAS unsigned char* lds, const Gemm g, const StaticOrder& S, const Epi& E) {
;     ...
;             PG8_WAIT_V(8); PG8_WAIT_L(0); PG8_BAR; PG8_MMA(1, 0, At, B0); PG8_MMA(1, 1, At, B1); PG8_BAR; PG8_SCHED;
;             PG8_LDB(B0, 1, 0); PG8_LDB(B1, 1, 1); PG8_SCHED; PG8_LDA(At, 1, 0); PG8_STAGE(PG8_SA(0, 1), a2 + hstepA, voffA);
;             PG8_WAIT_V(8); PG8_WAIT_L(0); PG8_BAR; PG8_MMA(0, 0, At, B0); PG8_MMA(0, 1, At, B1); PG8_BAR; PG8_SCHED;
	s_waitcnt lgkmcnt(0)
	v_mfma_f32_16x16x32_bf16 v[60:63], v[130:133], v[190:193], v[60:63]
	v_mfma_f32_16x16x32_bf16 v[56:59], v[138:141], v[190:193], v[56:59]
	v_mfma_f32_16x16x32_bf16 v[44:47], v[130:133], v[198:201], v[44:47]
	v_mfma_f32_16x16x32_bf16 v[40:43], v[138:141], v[198:201], v[40:43]
	v_mfma_f32_16x16x32_bf16 v[28:31], v[130:133], v[222:225], v[28:31]
	v_mfma_f32_16x16x32_bf16 v[24:27], v[138:141], v[222:225], v[24:27]
	v_mfma_f32_16x16x32_bf16 v[12:15], v[130:133], v[230:233], v[12:15]
	v_mfma_f32_16x16x32_bf16 v[8:11], v[138:141], v[230:233], v[8:11]
	v_mfma_f32_16x16x32_bf16 v[60:63], v[134:137], v[194:197], v[60:63]
	v_mfma_f32_16x16x32_bf16 v[56:59], v[142:145], v[194:197], v[56:59]
	v_mfma_f32_16x16x32_bf16 v[44:47], v[134:137], v[206:209], v[44:47]
	v_mfma_f32_16x16x32_bf16 v[40:43], v[142:145], v[206:209], v[40:43]
	v_mfma_f32_16x16x32_bf16 v[28:31], v[134:137], v[226:229], v[28:31]
	v_mfma_f32_16x16x32_bf16 v[24:27], v[142:145], v[226:229], v[24:27]
	v_mfma_f32_16x16x32_bf16 v[12:15], v[134:137], v[234:237], v[12:15]
	v_mfma_f32_16x16x32_bf16 v[8:11], v[142:145], v[234:237], v[8:11]
	v_mfma_f32_16x16x32_bf16 v[52:55], v[146:149], v[190:193], v[52:55]
	v_mfma_f32_16x16x32_bf16 v[48:51], v[154:157], v[190:193], v[48:51]
	v_mfma_f32_16x16x32_bf16 v[36:39], v[146:149], v[198:201], v[36:39]
	v_mfma_f32_16x16x32_bf16 v[32:35], v[154:157], v[198:201], v[32:35]
	v_mfma_f32_16x16x32_bf16 v[20:23], v[146:149], v[222:225], v[20:23]
	v_mfma_f32_16x16x32_bf16 v[16:19], v[154:157], v[222:225], v[16:19]
	v_mfma_f32_16x16x32_bf16 v[4:7], v[146:149], v[230:233], v[4:7]
	v_mfma_f32_16x16x32_bf16 v[0:3], v[154:157], v[230:233], v[0:3]
	v_mfma_f32_16x16x32_bf16 v[52:55], v[150:153], v[194:197], v[52:55]
	v_mfma_f32_16x16x32_bf16 v[48:51], v[186:189], v[194:197], v[48:51]
	v_mfma_f32_16x16x32_bf16 v[36:39], v[150:153], v[206:209], v[36:39]
	v_mfma_f32_16x16x32_bf16 v[32:35], v[186:189], v[206:209], v[32:35]
	v_mfma_f32_16x16x32_bf16 v[20:23], v[150:153], v[226:229], v[20:23]
	v_mfma_f32_16x16x32_bf16 v[16:19], v[186:189], v[226:229], v[16:19]
	v_mfma_f32_16x16x32_bf16 v[4:7], v[150:153], v[234:237], v[4:7]
	v_mfma_f32_16x16x32_bf16 v[0:3], v[186:189], v[234:237], v[0:3]
	s_barrier
	s_add_i32 s29, 0, 0x18000
	s_add_i32 s30, 0, 0x1c000
	v_add_u32_e32 v142, s29, v181
	v_add_u32_e32 v186, s30, v181
	ds_read_b128 v[130:133], v142
	ds_read_b128 v[134:137], v142 offset:1024
	ds_read_b128 v[138:141], v142 offset:2048
	ds_read_b128 v[142:145], v142 offset:3072
	ds_read_b128 v[146:149], v186
	ds_read_b128 v[150:153], v186 offset:1024
	ds_read_b128 v[154:157], v186 offset:2048
	ds_read_b128 v[186:189], v186 offset:3072
	s_add_u32 s10, s10, s40
	s_addc_u32 s11, s11, s41
	s_mov_b32 m0, s23
	v_lshl_add_u64 v[244:245], s[10:11], 0, v[178:179]
	ds_read_b128 v[190:193], v204 offset:32768
	ds_read_b128 v[194:197], v204 offset:33792
	ds_read_b128 v[198:201], v204 offset:34816
	ds_read_b128 v[206:209], v204 offset:35840
	ds_read_b128 v[222:225], v204 offset:36864
	ds_read_b128 v[226:229], v204 offset:37888
	ds_read_b128 v[230:233], v204 offset:38912
	ds_read_b128 v[234:237], v204 offset:39936
	global_load_lds_dwordx4 v[244:245], off
	v_lshl_add_u64 v[244:245], s[10:11], 0, v[174:175]
	s_mov_b32 m0, s24
	s_nop 0
	global_load_lds_dwordx4 v[244:245], off
	s_waitcnt vmcnt(8)
	s_waitcnt lgkmcnt(0)
	s_barrier
	s_waitcnt lgkmcnt(0)
	v_mfma_f32_16x16x32_bf16 v[126:129], v[130:133], v[190:193], v[126:129]
	v_mfma_f32_16x16x32_bf16 v[122:125], v[138:141], v[190:193], v[122:125]
	v_mfma_f32_16x16x32_bf16 v[110:113], v[130:133], v[198:201], v[110:113]
	v_mfma_f32_16x16x32_bf16 v[106:109], v[138:141], v[198:201], v[106:109]
	v_mfma_f32_16x16x32_bf16 v[94:97], v[130:133], v[222:225], v[94:97]
	v_mfma_f32_16x16x32_bf16 v[90:93], v[138:141], v[222:225], v[90:93]
	v_mfma_f32_16x16x32_bf16 v[78:81], v[130:133], v[230:233], v[78:81]
	v_mfma_f32_16x16x32_bf16 v[74:77], v[138:141], v[230:233], v[74:77]
	v_mfma_f32_16x16x32_bf16 v[126:129], v[134:137], v[194:197], v[126:129]
	v_mfma_f32_16x16x32_bf16 v[122:125], v[142:145], v[194:197], v[122:125]
	v_mfma_f32_16x16x32_bf16 v[110:113], v[134:137], v[206:209], v[110:113]
	v_mfma_f32_16x16x32_bf16 v[106:109], v[142:145], v[206:209], v[106:109]
	v_mfma_f32_16x16x32_bf16 v[94:97], v[134:137], v[226:229], v[94:97]
	v_mfma_f32_16x16x32_bf16 v[90:93], v[142:145], v[226:229], v[90:93]
	v_mfma_f32_16x16x32_bf16 v[78:81], v[134:137], v[234:237], v[78:81]
	v_mfma_f32_16x16x32_bf16 v[74:77], v[142:145], v[234:237], v[74:77]
	v_mfma_f32_16x16x32_bf16 v[118:121], v[146:149], v[190:193], v[118:121]
	v_mfma_f32_16x16x32_bf16 v[114:117], v[154:157], v[190:193], v[114:117]
	v_mfma_f32_16x16x32_bf16 v[102:105], v[146:149], v[198:201], v[102:105]
	v_mfma_f32_16x16x32_bf16 v[98:101], v[154:157], v[198:201], v[98:101]
	v_mfma_f32_16x16x32_bf16 v[86:89], v[146:149], v[222:225], v[86:89]
	v_mfma_f32_16x16x32_bf16 v[82:85], v[154:157], v[222:225], v[82:85]
	v_mfma_f32_16x16x32_bf16 v[70:73], v[146:149], v[230:233], v[70:73]
	v_mfma_f32_16x16x32_bf16 v[66:69], v[154:157], v[230:233], v[66:69]
	v_mfma_f32_16x16x32_bf16 v[118:121], v[150:153], v[194:197], v[118:121]
	v_mfma_f32_16x16x32_bf16 v[114:117], v[186:189], v[194:197], v[114:117]
	v_mfma_f32_16x16x32_bf16 v[102:105], v[150:153], v[206:209], v[102:105]
	v_mfma_f32_16x16x32_bf16 v[98:101], v[186:189], v[206:209], v[98:101]
	v_mfma_f32_16x16x32_bf16 v[86:89], v[150:153], v[226:229], v[86:89]
	v_mfma_f32_16x16x32_bf16 v[82:85], v[186:189], v[226:229], v[82:85]
	v_mfma_f32_16x16x32_bf16 v[70:73], v[150:153], v[234:237], v[70:73]
	v_mfma_f32_16x16x32_bf16 v[66:69], v[186:189], v[234:237], v[66:69]
	s_barrier
; #define PG8_STAGE(bufoff, gbase, voff) do { _Pragma("unroll") for (int _i = 0; _i < 2; ++_i) \
;         __builtin_amdgcn_global_load_lds((const unsigned*)((const char*)(gbase) + (voff)[_i]), (LAS unsigned*)(lds + (bufoff) + ldsw + _i * 8192), 16, 0, 0); } while (0)
; #define PG8_LDA(dst, b, h) do { _Pragma("unroll") for (int m = 0; m < 4; ++m) _Pragma("unroll") for (int k = 0; k < 2; ++k) dst[m][k] = *(const LAS bf16x8*)(lds + PG8_SA(b, h) + aoff + m * 2048 + k * 1024); } while (0)
; #define PG8_MMA(ai, bj, At, Bt) do { __builtin_amdgcn_s_setprio(1); _Pragma("unroll") for (int m = 0; m < 4; ++m) _Pragma("unroll") for (int n = 0; n < 2; ++n) _Pragma("unroll") for (int k = 0; k < 2; ++k) \
;         acc[ai][bj][m][n] = __builtin_amdgcn_mfma_f32_16x16x32_bf16(Bt[n][k], At[m][k], acc[ai][bj][m][n], 0, 0, 0); __builtin_amdgcn_s_setprio(0); } while (0)
; #define PG8_WAIT_V(n) asm volatile("s_waitcnt vmcnt(" #n ")" ::: "memory")
; #define PG8_WAIT_L(n) asm volatile("s_waitcnt lgkmcnt(" #n ")" ::: "memory")
; #define PG8_BAR __builtin_amdgcn_s_barrier()
; #define PG8_SCHED __builtin_amdgcn_sched_barrier(0)
; template <class Epi>
; __device__ __forceinline__ void gemm_phase(LAS unsigned char* lds, const Gemm g, const StaticOrder& S, const Epi& E) {
;     ...
;             PG8_LDA(At, 1, 1); PG8_STAGE(PG8_SB(1, 0), b3, voffB); PG8_STAGE(PG8_SB(1, 1), b3 + hstepB, voffB); PG8_STAGE(PG8_SA(1, 0), a3, voffA);
;             PG8_WAIT_V(8); PG8_WAIT_L(0); PG8_BAR; PG8_MMA(1, 0, At, B0); PG8_MMA(1, 1, At, B1); PG8_BAR; PG8_SCHED;
;         }
	s_add_i32 s10, s29, s20
	v_lshl_add_u64 v[202:203], v[202:203], 0, s[82:83]
	s_mov_b32 m0, s10
	ds_read_b128 v[190:193], v204 offset:49152
	ds_read_b128 v[194:197], v204 offset:50176
	ds_read_b128 v[198:201], v204 offset:51200
	ds_read_b128 v[206:209], v204 offset:52224
	ds_read_b128 v[222:225], v204 offset:53248
	ds_read_b128 v[226:229], v204 offset:54272
	ds_read_b128 v[230:233], v204 offset:55296
	ds_read_b128 v[234:237], v204 offset:56320
	global_load_lds_dwordx4 v[202:203], off
	v_lshl_add_u64 v[202:203], v[216:217], 0, s[82:83]
	s_add_i32 m0, s10, 0x2000
	s_add_i32 s10, s30, s20
	global_load_lds_dwordx4 v[202:203], off
	v_lshl_add_u64 v[202:203], v[218:219], 0, s[82:83]
	s_mov_b32 m0, s10
	s_nop 0
	global_load_lds_dwordx4 v[202:203], off
	v_lshl_add_u64 v[202:203], v[238:239], 0, s[82:83]
	s_add_i32 m0, s10, 0x2000
	s_nop 0
	global_load_lds_dwordx4 v[202:203], off
	v_lshl_add_u64 v[202:203], v[240:241], 0, s[82:83]
	s_mov_b32 m0, s25
	s_nop 0
	global_load_lds_dwordx4 v[202:203], off
	v_lshl_add_u64 v[202:203], v[242:243], 0, s[82:83]
	s_mov_b32 m0, s62
	s_nop 0
	global_load_lds_dwordx4 v[202:203], off
	s_waitcnt vmcnt(8)
	s_waitcnt lgkmcnt(0)
	s_barrier
	s_waitcnt lgkmcnt(0)
	v_mfma_f32_16x16x32_bf16 v[60:63], v[130:133], v[190:193], v[60:63]
	v_mfma_f32_16x16x32_bf16 v[56:59], v[138:141], v[190:193], v[56:59]
	v_mfma_f32_16x16x32_bf16 v[44:47], v[130:133], v[198:201], v[44:47]
	v_mfma_f32_16x16x32_bf16 v[40:43], v[138:141], v[198:201], v[40:43]
	v_mfma_f32_16x16x32_bf16 v[28:31], v[130:133], v[222:225], v[28:31]
	v_mfma_f32_16x16x32_bf16 v[24:27], v[138:141], v[222:225], v[24:27]
	v_mfma_f32_16x16x32_bf16 v[12:15], v[130:133], v[230:233], v[12:15]
	v_mfma_f32_16x16x32_bf16 v[8:11], v[138:141], v[230:233], v[8:11]
	v_mfma_f32_16x16x32_bf16 v[60:63], v[134:137], v[194:197], v[60:63]
	v_mfma_f32_16x16x32_bf16 v[56:59], v[142:145], v[194:197], v[56:59]
	v_mfma_f32_16x16x32_bf16 v[44:47], v[134:137], v[206:209], v[44:47]
	v_mfma_f32_16x16x32_bf16 v[40:43], v[142:145], v[206:209], v[40:43]
	v_mfma_f32_16x16x32_bf16 v[28:31], v[134:137], v[226:229], v[28:31]
	v_mfma_f32_16x16x32_bf16 v[24:27], v[142:145], v[226:229], v[24:27]
	v_mfma_f32_16x16x32_bf16 v[12:15], v[134:137], v[234:237], v[12:15]
	v_mfma_f32_16x16x32_bf16 v[8:11], v[142:145], v[234:237], v[8:11]
	v_mfma_f32_16x16x32_bf16 v[52:55], v[146:149], v[190:193], v[52:55]
	v_mfma_f32_16x16x32_bf16 v[48:51], v[154:157], v[190:193], v[48:51]
	v_mfma_f32_16x16x32_bf16 v[36:39], v[146:149], v[198:201], v[36:39]
	v_mfma_f32_16x16x32_bf16 v[32:35], v[154:157], v[198:201], v[32:35]
	v_mfma_f32_16x16x32_bf16 v[20:23], v[146:149], v[222:225], v[20:23]
	v_mfma_f32_16x16x32_bf16 v[16:19], v[154:157], v[222:225], v[16:19]
	v_mfma_f32_16x16x32_bf16 v[4:7], v[146:149], v[230:233], v[4:7]
	v_mfma_f32_16x16x32_bf16 v[0:3], v[154:157], v[230:233], v[0:3]
	v_mfma_f32_16x16x32_bf16 v[52:55], v[150:153], v[194:197], v[52:55]
	v_mfma_f32_16x16x32_bf16 v[48:51], v[186:189], v[194:197], v[48:51]
	v_mfma_f32_16x16x32_bf16 v[36:39], v[150:153], v[206:209], v[36:39]
	v_mfma_f32_16x16x32_bf16 v[32:35], v[186:189], v[206:209], v[32:35]
	v_mfma_f32_16x16x32_bf16 v[20:23], v[150:153], v[226:229], v[20:23]
	v_mfma_f32_16x16x32_bf16 v[16:19], v[186:189], v[226:229], v[16:19]
	v_mfma_f32_16x16x32_bf16 v[4:7], v[150:153], v[234:237], v[4:7]
	v_mfma_f32_16x16x32_bf16 v[0:3], v[186:189], v[234:237], v[0:3]
	s_add_u32 s26, s26, 0x100
	s_addc_u32 s27, s27, 0
	s_add_u32 s58, s58, 0x100
	s_addc_u32 s59, s59, 0
	s_cmp_ge_i32 s28, s64
	s_mov_b32 s10, s28
	s_barrier
	s_cbranch_scc0 .LBB0_3152

; #define PG8_STAGE(bufoff, gbase, voff) do { _Pragma("unroll") for (int _i = 0; _i < 2; ++_i) \
;         __builtin_amdgcn_global_load_lds((const unsigned*)((const char*)(gbase) + (voff)[_i]), (LAS unsigned*)(lds + (bufoff) + ldsw + _i * 8192), 16, 0, 0); } while (0)
; #define PG8_LDA(dst, b, h) do { _Pragma("unroll") for (int m = 0; m < 4; ++m) _Pragma("unroll") for (int k = 0; k < 2; ++k) dst[m][k] = *(const LAS bf16x8*)(lds + PG8_SA(b, h) + aoff + m * 2048 + k * 1024); } while (0)
; #define PG8_LDB(dst, b, h) do { _Pragma("unroll") for (int n = 0; n < 2; ++n) _Pragma("unroll") for (int k = 0; k < 2; ++k) dst[n][k] = *(const LAS bf16x8*)(lds + PG8_SB(b, h) + boff + n * 2048 + k * 1024); } while (0)
; #define PG8_MMA(ai, bj, At, Bt) do { __builtin_amdgcn_s_setprio(1); _Pragma("unroll") for (int m = 0; m < 4; ++m) _Pragma("unroll") for (int n = 0; n < 2; ++n) _Pragma("unroll") for (int k = 0; k < 2; ++k) \
;         acc[ai][bj][m][n] = __builtin_amdgcn_mfma_f32_16x16x32_bf16(Bt[n][k], At[m][k], acc[ai][bj][m][n], 0, 0, 0); __builtin_amdgcn_s_setprio(0); } while (0)
; #define PG8_WAIT_V(n) asm volatile("s_waitcnt vmcnt(" #n ")" ::: "memory")
; #define PG8_WAIT_L(n) asm volatile("s_waitcnt lgkmcnt(" #n ")" ::: "memory")
; #define PG8_BAR __builtin_amdgcn_s_barrier()
; #define PG8_SCHED __builtin_amdgcn_sched_barrier(0)
; template <class Epi>
; __device__ __forceinline__ void gemm_phase(LAS unsigned char* lds, const Gemm g, const StaticOrder& S, const Epi& E) {
;     ...
;         for (int t = 0; t < nt; t += 2) {
;             const bool last = (t == nt - 2);
;             const char* a1 = cA + (size_t)(t + 1) * kstep;
;             const char* a2 = last ? nA : cA + (size_t)(t + 2) * kstep; const char* b2 = last ? nB : cB + (size_t)(t + 2) * kstep;
;             const char* a3 = a2 + kstep; const char* b3 = b2 + kstep;
;             PG8_LDB(B0, 0, 0); PG8_LDB(B1, 0, 1); PG8_SCHED; PG8_LDA(At, 0, 0); PG8_STAGE(PG8_SA(1, 1), a1 + hstepA, voffA);
;             PG8_WAIT_V(8); PG8_WAIT_L(0); PG8_BAR; PG8_MMA(0, 0, At, B0); PG8_MMA(0, 1, At, B1); PG8_BAR; PG8_SCHED;
;             PG8_LDA(At, 0, 1); PG8_STAGE(PG8_SB(0, 0), b2, voffB); PG8_STAGE(PG8_SB(0, 1), b2 + hstepB, voffB); PG8_STAGE(PG8_SA(0, 0), a2, voffA);
;             PG8_WAIT_V(8); PG8_WAIT_L(0); PG8_BAR; PG8_MMA(1, 0, At, B0); PG8_MMA(1, 1, At, B1); PG8_BAR; PG8_SCHED;
.LBB0_3239:
	s_add_i32 s15, s10, 2
	s_add_u32 s44, s42, 0x80
	s_addc_u32 s11, s43, 0
	s_add_i32 s64, 0, 0x10000
	s_cmp_eq_u32 s97, s10
	s_cselect_b32 s11, s1, s11
	s_cselect_b32 s10, s0, s44
	v_add_u32_e32 v145, s64, v172
	s_cselect_b32 s45, s9, s14
	s_cselect_b32 s44, s8, s13
	s_add_i32 s65, 0, 0x14000
	ds_read_b128 v[146:149], v145
	ds_read_b128 v[150:153], v145 offset:1024
	ds_read_b128 v[154:157], v145 offset:2048
	ds_read_b128 v[178:181], v145 offset:3072
	v_add_u32_e32 v145, s65, v172
	ds_read_b128 v[182:185], v145
	ds_read_b128 v[186:189], v145 offset:1024
	ds_read_b128 v[190:193], v145 offset:2048
	ds_read_b128 v[194:197], v145 offset:3072
	v_lshl_add_u64 v[242:243], s[42:43], 0, v[142:143]
	s_add_i32 m0, s25, 0xc000
	ds_read_b128 v[198:201], v175
	ds_read_b128 v[202:205], v175 offset:1024
	ds_read_b128 v[206:209], v175 offset:2048
	ds_read_b128 v[222:225], v175 offset:3072
	ds_read_b128 v[226:229], v175 offset:4096
	ds_read_b128 v[230:233], v175 offset:5120
	ds_read_b128 v[234:237], v175 offset:6144
	ds_read_b128 v[238:241], v175 offset:7168
	global_load_lds_dwordx4 v[242:243], off
	v_lshl_add_u64 v[242:243], s[42:43], 0, v[140:141]
	s_add_i32 m0, s25, 0xe000
	s_nop 0
	global_load_lds_dwordx4 v[242:243], off
	s_waitcnt vmcnt(8)
	s_waitcnt lgkmcnt(0)
	s_barrier
	s_waitcnt lgkmcnt(0)
	v_mfma_f32_16x16x32_bf16 v[126:129], v[146:149], v[198:201], v[126:129]
	v_mfma_f32_16x16x32_bf16 v[122:125], v[154:157], v[198:201], v[122:125]
	v_mfma_f32_16x16x32_bf16 v[110:113], v[146:149], v[206:209], v[110:113]
	v_mfma_f32_16x16x32_bf16 v[106:109], v[154:157], v[206:209], v[106:109]
	v_mfma_f32_16x16x32_bf16 v[94:97], v[146:149], v[226:229], v[94:97]
	v_mfma_f32_16x16x32_bf16 v[90:93], v[154:157], v[226:229], v[90:93]
	v_mfma_f32_16x16x32_bf16 v[78:81], v[146:149], v[234:237], v[78:81]
	v_mfma_f32_16x16x32_bf16 v[74:77], v[154:157], v[234:237], v[74:77]
	v_mfma_f32_16x16x32_bf16 v[126:129], v[150:153], v[202:205], v[126:129]
	v_mfma_f32_16x16x32_bf16 v[122:125], v[178:181], v[202:205], v[122:125]
	v_mfma_f32_16x16x32_bf16 v[110:113], v[150:153], v[222:225], v[110:113]
	v_mfma_f32_16x16x32_bf16 v[106:109], v[178:181], v[222:225], v[106:109]
	v_mfma_f32_16x16x32_bf16 v[94:97], v[150:153], v[230:233], v[94:97]
	v_mfma_f32_16x16x32_bf16 v[90:93], v[178:181], v[230:233], v[90:93]
	v_mfma_f32_16x16x32_bf16 v[78:81], v[150:153], v[238:241], v[78:81]
	v_mfma_f32_16x16x32_bf16 v[74:77], v[178:181], v[238:241], v[74:77]
	v_mfma_f32_16x16x32_bf16 v[118:121], v[182:185], v[198:201], v[118:121]
	v_mfma_f32_16x16x32_bf16 v[114:117], v[190:193], v[198:201], v[114:117]
	v_mfma_f32_16x16x32_bf16 v[102:105], v[182:185], v[206:209], v[102:105]
	v_mfma_f32_16x16x32_bf16 v[98:101], v[190:193], v[206:209], v[98:101]
	v_mfma_f32_16x16x32_bf16 v[86:89], v[182:185], v[226:229], v[86:89]
	v_mfma_f32_16x16x32_bf16 v[82:85], v[190:193], v[226:229], v[82:85]
	v_mfma_f32_16x16x32_bf16 v[70:73], v[182:185], v[234:237], v[70:73]
	v_mfma_f32_16x16x32_bf16 v[66:69], v[190:193], v[234:237], v[66:69]
	v_mfma_f32_16x16x32_bf16 v[118:121], v[186:189], v[202:205], v[118:121]
	v_mfma_f32_16x16x32_bf16 v[114:117], v[194:197], v[202:205], v[114:117]
	v_mfma_f32_16x16x32_bf16 v[102:105], v[186:189], v[222:225], v[102:105]
	v_mfma_f32_16x16x32_bf16 v[98:101], v[194:197], v[222:225], v[98:101]
	v_mfma_f32_16x16x32_bf16 v[86:89], v[186:189], v[230:233], v[86:89]
	v_mfma_f32_16x16x32_bf16 v[82:85], v[194:197], v[230:233], v[82:85]
	v_mfma_f32_16x16x32_bf16 v[70:73], v[186:189], v[238:241], v[70:73]
	v_mfma_f32_16x16x32_bf16 v[66:69], v[194:197], v[238:241], v[66:69]
	s_barrier
	s_add_i32 s64, s64, s24
	v_lshl_add_u64 v[242:243], s[44:45], 0, v[134:135]
	s_mov_b32 m0, s64
	ds_read_b128 v[198:201], v175 offset:16384
	ds_read_b128 v[202:205], v175 offset:17408
	ds_read_b128 v[206:209], v175 offset:18432
	ds_read_b128 v[222:225], v175 offset:19456
	ds_read_b128 v[226:229], v175 offset:20480
	ds_read_b128 v[230:233], v175 offset:21504
	ds_read_b128 v[234:237], v175 offset:22528
	ds_read_b128 v[238:241], v175 offset:23552
	global_load_lds_dwordx4 v[242:243], off
	s_add_i32 m0, s64, 0x2000
	v_lshl_add_u64 v[244:245], s[44:45], 0, v[130:131]
	s_add_u32 s44, s44, s6
	s_addc_u32 s45, s45, s7
	s_add_i32 s64, s65, s24
	global_load_lds_dwordx4 v[244:245], off
	v_lshl_add_u64 v[246:247], s[44:45], 0, v[134:135]
	s_mov_b32 m0, s64
	v_lshl_add_u64 v[248:249], s[44:45], 0, v[130:131]
	global_load_lds_dwordx4 v[246:247], off
	s_add_i32 m0, s64, 0x2000
	v_lshl_add_u64 v[250:251], s[10:11], 0, v[136:137]
	global_load_lds_dwordx4 v[248:249], off
	s_mov_b32 m0, s25
	v_lshl_add_u64 v[216:217], s[10:11], 0, v[132:133]
	global_load_lds_dwordx4 v[250:251], off
	s_mov_b32 m0, s26
	s_nop 0
	global_load_lds_dwordx4 v[216:217], off
	s_waitcnt vmcnt(8)
	s_waitcnt lgkmcnt(0)
	s_barrier
; #define PG8_STAGE(bufoff, gbase, voff) do { _Pragma("unroll") for (int _i = 0; _i < 2; ++_i) \
;         __builtin_amdgcn_global_load_lds((const unsigned*)((const char*)(gbase) + (voff)[_i]), (LAS unsigned*)(lds + (bufoff) + ldsw + _i * 8192), 16, 0, 0); } while (0)
; #define PG8_LDA(dst, b, h) do { _Pragma("unroll") for (int m = 0; m < 4; ++m) _Pragma("unroll") for (int k = 0; k < 2; ++k) dst[m][k] = *(const LAS bf16x8*)(lds + PG8_SA(b, h) + aoff + m * 2048 + k * 1024); } while (0)
; #define PG8_LDB(dst, b, h) do { _Pragma("unroll") for (int n = 0; n < 2; ++n) _Pragma("unroll") for (int k = 0; k < 2; ++k) dst[n][k] = *(const LAS bf16x8*)(lds + PG8_SB(b, h) + boff + n * 2048 + k * 1024); } while (0)
; #define PG8_MMA(ai, bj, At, Bt) do { __builtin_amdgcn_s_setprio(1); _Pragma("unroll") for (int m = 0; m < 4; ++m) _Pragma("unroll") for (int n = 0; n < 2; ++n) _Pragma("unroll") for (int k = 0; k < 2; ++k) \
;         acc[ai][bj][m][n] = __builtin_amdgcn_mfma_f32_16x16x32_bf16(Bt[n][k], At[m][k], acc[ai][bj][m][n], 0, 0, 0); __builtin_amdgcn_s_setprio(0); } while (0)
; #define PG8_WAIT_V(n) asm volatile("s_waitcnt vmcnt(" #n ")" ::: "memory")
; #define PG8_WAIT_L(n) asm volatile("s_waitcnt lgkmcnt(" #n ")" ::: "memory")
; #define PG8_BAR __builtin_amdgcn_s_barrier()
; #define PG8_SCHED __builtin_amdgcn_sched_barrier(0)
; template <class Epi>
; __device__ __forceinline__ void gemm_phase(LAS unsigned char* lds, const Gemm g, const StaticOrder& S, const Epi& E) {
;     ...
;             PG8_WAIT_V(8); PG8_WAIT_L(0); PG8_BAR; PG8_MMA(1, 0, At, B0); PG8_MMA(1, 1, At, B1); PG8_BAR; PG8_SCHED;
;             PG8_LDB(B0, 1, 0); PG8_LDB(B1, 1, 1); PG8_SCHED; PG8_LDA(At, 1, 0); PG8_STAGE(PG8_SA(0, 1), a2 + hstepA, voffA);
;             PG8_WAIT_V(8); PG8_WAIT_L(0); PG8_BAR; PG8_MMA(0, 0, At, B0); PG8_MMA(0, 1, At, B1); PG8_BAR; PG8_SCHED;
	s_waitcnt lgkmcnt(0)
	v_mfma_f32_16x16x32_bf16 v[60:63], v[146:149], v[198:201], v[60:63]
	v_mfma_f32_16x16x32_bf16 v[56:59], v[154:157], v[198:201], v[56:59]
	v_mfma_f32_16x16x32_bf16 v[44:47], v[146:149], v[206:209], v[44:47]
	v_mfma_f32_16x16x32_bf16 v[40:43], v[154:157], v[206:209], v[40:43]
	v_mfma_f32_16x16x32_bf16 v[28:31], v[146:149], v[226:229], v[28:31]
	v_mfma_f32_16x16x32_bf16 v[24:27], v[154:157], v[226:229], v[24:27]
	v_mfma_f32_16x16x32_bf16 v[12:15], v[146:149], v[234:237], v[12:15]
	v_mfma_f32_16x16x32_bf16 v[8:11], v[154:157], v[234:237], v[8:11]
	v_mfma_f32_16x16x32_bf16 v[60:63], v[150:153], v[202:205], v[60:63]
	v_mfma_f32_16x16x32_bf16 v[56:59], v[178:181], v[202:205], v[56:59]
	v_mfma_f32_16x16x32_bf16 v[44:47], v[150:153], v[222:225], v[44:47]
	v_mfma_f32_16x16x32_bf16 v[40:43], v[178:181], v[222:225], v[40:43]
	v_mfma_f32_16x16x32_bf16 v[28:31], v[150:153], v[230:233], v[28:31]
	v_mfma_f32_16x16x32_bf16 v[24:27], v[178:181], v[230:233], v[24:27]
	v_mfma_f32_16x16x32_bf16 v[12:15], v[150:153], v[238:241], v[12:15]
	v_mfma_f32_16x16x32_bf16 v[8:11], v[178:181], v[238:241], v[8:11]
	v_mfma_f32_16x16x32_bf16 v[52:55], v[182:185], v[198:201], v[52:55]
	v_mfma_f32_16x16x32_bf16 v[48:51], v[190:193], v[198:201], v[48:51]
	v_mfma_f32_16x16x32_bf16 v[36:39], v[182:185], v[206:209], v[36:39]
	v_mfma_f32_16x16x32_bf16 v[32:35], v[190:193], v[206:209], v[32:35]
	v_mfma_f32_16x16x32_bf16 v[20:23], v[182:185], v[226:229], v[20:23]
	v_mfma_f32_16x16x32_bf16 v[16:19], v[190:193], v[226:229], v[16:19]
	v_mfma_f32_16x16x32_bf16 v[4:7], v[182:185], v[234:237], v[4:7]
	v_mfma_f32_16x16x32_bf16 v[0:3], v[190:193], v[234:237], v[0:3]
	v_mfma_f32_16x16x32_bf16 v[52:55], v[186:189], v[202:205], v[52:55]
	v_mfma_f32_16x16x32_bf16 v[48:51], v[194:197], v[202:205], v[48:51]
	v_mfma_f32_16x16x32_bf16 v[36:39], v[186:189], v[222:225], v[36:39]
	v_mfma_f32_16x16x32_bf16 v[32:35], v[194:197], v[222:225], v[32:35]
	v_mfma_f32_16x16x32_bf16 v[20:23], v[186:189], v[230:233], v[20:23]
	v_mfma_f32_16x16x32_bf16 v[16:19], v[194:197], v[230:233], v[16:19]
	v_mfma_f32_16x16x32_bf16 v[4:7], v[186:189], v[238:241], v[4:7]
	v_mfma_f32_16x16x32_bf16 v[0:3], v[194:197], v[238:241], v[0:3]
	s_barrier
	s_add_i32 s44, 0, 0x18000
	v_add_u32_e32 v145, s44, v172
	s_add_i32 s45, 0, 0x1c000
	ds_read_b128 v[146:149], v145
	ds_read_b128 v[150:153], v145 offset:1024
	ds_read_b128 v[154:157], v145 offset:2048
	ds_read_b128 v[178:181], v145 offset:3072
	v_add_u32_e32 v145, s45, v172
	ds_read_b128 v[182:185], v145
	ds_read_b128 v[186:189], v145 offset:1024
	ds_read_b128 v[190:193], v145 offset:2048
	ds_read_b128 v[194:197], v145 offset:3072
	s_add_u32 s10, s10, s4
	s_addc_u32 s11, s11, s5
	s_mov_b32 m0, s27
	v_lshl_add_u64 v[218:219], s[10:11], 0, v[136:137]
	ds_read_b128 v[198:201], v175 offset:32768
	ds_read_b128 v[202:205], v175 offset:33792
	ds_read_b128 v[206:209], v175 offset:34816
	ds_read_b128 v[222:225], v175 offset:35840
	ds_read_b128 v[226:229], v175 offset:36864
	ds_read_b128 v[230:233], v175 offset:37888
	ds_read_b128 v[234:237], v175 offset:38912
	ds_read_b128 v[238:241], v175 offset:39936
	global_load_lds_dwordx4 v[218:219], off
	v_lshl_add_u64 v[218:219], s[10:11], 0, v[132:133]
	s_mov_b32 m0, s68
	s_nop 0
	global_load_lds_dwordx4 v[218:219], off
	s_waitcnt vmcnt(8)
	s_waitcnt lgkmcnt(0)
	s_barrier
	s_waitcnt lgkmcnt(0)
	v_mfma_f32_16x16x32_bf16 v[126:129], v[146:149], v[198:201], v[126:129]
	v_mfma_f32_16x16x32_bf16 v[122:125], v[154:157], v[198:201], v[122:125]
	v_mfma_f32_16x16x32_bf16 v[110:113], v[146:149], v[206:209], v[110:113]
	v_mfma_f32_16x16x32_bf16 v[106:109], v[154:157], v[206:209], v[106:109]
	v_mfma_f32_16x16x32_bf16 v[94:97], v[146:149], v[226:229], v[94:97]
	v_mfma_f32_16x16x32_bf16 v[90:93], v[154:157], v[226:229], v[90:93]
	v_mfma_f32_16x16x32_bf16 v[78:81], v[146:149], v[234:237], v[78:81]
	v_mfma_f32_16x16x32_bf16 v[74:77], v[154:157], v[234:237], v[74:77]
	v_mfma_f32_16x16x32_bf16 v[126:129], v[150:153], v[202:205], v[126:129]
	v_mfma_f32_16x16x32_bf16 v[122:125], v[178:181], v[202:205], v[122:125]
	v_mfma_f32_16x16x32_bf16 v[110:113], v[150:153], v[222:225], v[110:113]
	v_mfma_f32_16x16x32_bf16 v[106:109], v[178:181], v[222:225], v[106:109]
	v_mfma_f32_16x16x32_bf16 v[94:97], v[150:153], v[230:233], v[94:97]
	v_mfma_f32_16x16x32_bf16 v[90:93], v[178:181], v[230:233], v[90:93]
	v_mfma_f32_16x16x32_bf16 v[78:81], v[150:153], v[238:241], v[78:81]
	v_mfma_f32_16x16x32_bf16 v[74:77], v[178:181], v[238:241], v[74:77]
	v_mfma_f32_16x16x32_bf16 v[118:121], v[182:185], v[198:201], v[118:121]
	v_mfma_f32_16x16x32_bf16 v[114:117], v[190:193], v[198:201], v[114:117]
	v_mfma_f32_16x16x32_bf16 v[102:105], v[182:185], v[206:209], v[102:105]
	v_mfma_f32_16x16x32_bf16 v[98:101], v[190:193], v[206:209], v[98:101]
	v_mfma_f32_16x16x32_bf16 v[86:89], v[182:185], v[226:229], v[86:89]
	v_mfma_f32_16x16x32_bf16 v[82:85], v[190:193], v[226:229], v[82:85]
	v_mfma_f32_16x16x32_bf16 v[70:73], v[182:185], v[234:237], v[70:73]
	v_mfma_f32_16x16x32_bf16 v[66:69], v[190:193], v[234:237], v[66:69]
	v_mfma_f32_16x16x32_bf16 v[118:121], v[186:189], v[202:205], v[118:121]
	v_mfma_f32_16x16x32_bf16 v[114:117], v[194:197], v[202:205], v[114:117]
	v_mfma_f32_16x16x32_bf16 v[102:105], v[186:189], v[222:225], v[102:105]
	v_mfma_f32_16x16x32_bf16 v[98:101], v[194:197], v[222:225], v[98:101]
	v_mfma_f32_16x16x32_bf16 v[86:89], v[186:189], v[230:233], v[86:89]
	v_mfma_f32_16x16x32_bf16 v[82:85], v[194:197], v[230:233], v[82:85]
	v_mfma_f32_16x16x32_bf16 v[70:73], v[186:189], v[238:241], v[70:73]
	v_mfma_f32_16x16x32_bf16 v[66:69], v[194:197], v[238:241], v[66:69]
	s_barrier
; #define PG8_STAGE(bufoff, gbase, voff) do { _Pragma("unroll") for (int _i = 0; _i < 2; ++_i) \
;         __builtin_amdgcn_global_load_lds((const unsigned*)((const char*)(gbase) + (voff)[_i]), (LAS unsigned*)(lds + (bufoff) + ldsw + _i * 8192), 16, 0, 0); } while (0)
; #define PG8_LDA(dst, b, h) do { _Pragma("unroll") for (int m = 0; m < 4; ++m) _Pragma("unroll") for (int k = 0; k < 2; ++k) dst[m][k] = *(const LAS bf16x8*)(lds + PG8_SA(b, h) + aoff + m * 2048 + k * 1024); } while (0)
; #define PG8_MMA(ai, bj, At, Bt) do { __builtin_amdgcn_s_setprio(1); _Pragma("unroll") for (int m = 0; m < 4; ++m) _Pragma("unroll") for (int n = 0; n < 2; ++n) _Pragma("unroll") for (int k = 0; k < 2; ++k) \
;         acc[ai][bj][m][n] = __builtin_amdgcn_mfma_f32_16x16x32_bf16(Bt[n][k], At[m][k], acc[ai][bj][m][n], 0, 0, 0); __builtin_amdgcn_s_setprio(0); } while (0)
; #define PG8_WAIT_V(n) asm volatile("s_waitcnt vmcnt(" #n ")" ::: "memory")
; #define PG8_WAIT_L(n) asm volatile("s_waitcnt lgkmcnt(" #n ")" ::: "memory")
; #define PG8_BAR __builtin_amdgcn_s_barrier()
; #define PG8_SCHED __builtin_amdgcn_sched_barrier(0)
; template <class Epi>
; __device__ __forceinline__ void gemm_phase(LAS unsigned char* lds, const Gemm g, const StaticOrder& S, const Epi& E) {
;     ...
;             PG8_LDA(At, 1, 1); PG8_STAGE(PG8_SB(1, 0), b3, voffB); PG8_STAGE(PG8_SB(1, 1), b3 + hstepB, voffB); PG8_STAGE(PG8_SA(1, 0), a3, voffA);
;             PG8_WAIT_V(8); PG8_WAIT_L(0); PG8_BAR; PG8_MMA(1, 0, At, B0); PG8_MMA(1, 1, At, B1); PG8_BAR; PG8_SCHED;
;         }
	s_add_i32 s10, s44, s24
	v_lshl_add_u64 v[218:219], v[242:243], 0, s[82:83]
	s_mov_b32 m0, s10
	ds_read_b128 v[198:201], v175 offset:49152
	ds_read_b128 v[202:205], v175 offset:50176
	ds_read_b128 v[206:209], v175 offset:51200
	ds_read_b128 v[222:225], v175 offset:52224
	ds_read_b128 v[226:229], v175 offset:53248
	ds_read_b128 v[230:233], v175 offset:54272
	ds_read_b128 v[234:237], v175 offset:55296
	ds_read_b128 v[238:241], v175 offset:56320
	global_load_lds_dwordx4 v[218:219], off
	v_lshl_add_u64 v[218:219], v[244:245], 0, s[82:83]
	s_add_i32 m0, s10, 0x2000
	s_add_i32 s10, s45, s24
	global_load_lds_dwordx4 v[218:219], off
	v_lshl_add_u64 v[218:219], v[246:247], 0, s[82:83]
	s_mov_b32 m0, s10
	v_lshl_add_u64 v[216:217], v[216:217], 0, s[82:83]
	global_load_lds_dwordx4 v[218:219], off
	v_lshl_add_u64 v[218:219], v[248:249], 0, s[82:83]
	s_add_i32 m0, s10, 0x2000
	s_nop 0
	global_load_lds_dwordx4 v[218:219], off
	v_lshl_add_u64 v[218:219], v[250:251], 0, s[82:83]
	s_mov_b32 m0, s73
	s_nop 0
	global_load_lds_dwordx4 v[218:219], off
	s_mov_b32 m0, s84
	s_nop 0
	global_load_lds_dwordx4 v[216:217], off
	s_waitcnt vmcnt(8)
	s_waitcnt lgkmcnt(0)
	s_barrier
	s_waitcnt lgkmcnt(0)
	v_mfma_f32_16x16x32_bf16 v[60:63], v[146:149], v[198:201], v[60:63]
	v_mfma_f32_16x16x32_bf16 v[56:59], v[154:157], v[198:201], v[56:59]
	v_mfma_f32_16x16x32_bf16 v[44:47], v[146:149], v[206:209], v[44:47]
	v_mfma_f32_16x16x32_bf16 v[40:43], v[154:157], v[206:209], v[40:43]
	v_mfma_f32_16x16x32_bf16 v[28:31], v[146:149], v[226:229], v[28:31]
	v_mfma_f32_16x16x32_bf16 v[24:27], v[154:157], v[226:229], v[24:27]
	v_mfma_f32_16x16x32_bf16 v[12:15], v[146:149], v[234:237], v[12:15]
	v_mfma_f32_16x16x32_bf16 v[8:11], v[154:157], v[234:237], v[8:11]
	v_mfma_f32_16x16x32_bf16 v[60:63], v[150:153], v[202:205], v[60:63]
	v_mfma_f32_16x16x32_bf16 v[56:59], v[178:181], v[202:205], v[56:59]
	v_mfma_f32_16x16x32_bf16 v[44:47], v[150:153], v[222:225], v[44:47]
	v_mfma_f32_16x16x32_bf16 v[40:43], v[178:181], v[222:225], v[40:43]
	v_mfma_f32_16x16x32_bf16 v[28:31], v[150:153], v[230:233], v[28:31]
	v_mfma_f32_16x16x32_bf16 v[24:27], v[178:181], v[230:233], v[24:27]
	v_mfma_f32_16x16x32_bf16 v[12:15], v[150:153], v[238:241], v[12:15]
	v_mfma_f32_16x16x32_bf16 v[8:11], v[178:181], v[238:241], v[8:11]
	v_mfma_f32_16x16x32_bf16 v[52:55], v[182:185], v[198:201], v[52:55]
	v_mfma_f32_16x16x32_bf16 v[48:51], v[190:193], v[198:201], v[48:51]
	v_mfma_f32_16x16x32_bf16 v[36:39], v[182:185], v[206:209], v[36:39]
	v_mfma_f32_16x16x32_bf16 v[32:35], v[190:193], v[206:209], v[32:35]
	v_mfma_f32_16x16x32_bf16 v[20:23], v[182:185], v[226:229], v[20:23]
	v_mfma_f32_16x16x32_bf16 v[16:19], v[190:193], v[226:229], v[16:19]
	v_mfma_f32_16x16x32_bf16 v[4:7], v[182:185], v[234:237], v[4:7]
	v_mfma_f32_16x16x32_bf16 v[0:3], v[190:193], v[234:237], v[0:3]
	v_mfma_f32_16x16x32_bf16 v[52:55], v[186:189], v[202:205], v[52:55]
	v_mfma_f32_16x16x32_bf16 v[48:51], v[194:197], v[202:205], v[48:51]
	v_mfma_f32_16x16x32_bf16 v[36:39], v[186:189], v[222:225], v[36:39]
	v_mfma_f32_16x16x32_bf16 v[32:35], v[194:197], v[222:225], v[32:35]
	v_mfma_f32_16x16x32_bf16 v[20:23], v[186:189], v[230:233], v[20:23]
	v_mfma_f32_16x16x32_bf16 v[16:19], v[194:197], v[230:233], v[16:19]
	v_mfma_f32_16x16x32_bf16 v[4:7], v[186:189], v[238:241], v[4:7]
	v_mfma_f32_16x16x32_bf16 v[0:3], v[194:197], v[238:241], v[0:3]
	s_add_u32 s13, s13, 0x100
	s_addc_u32 s14, s14, 0
	s_add_u32 s42, s42, 0x100
	s_addc_u32 s43, s43, 0
	s_cmp_ge_i32 s15, s96
	s_mov_b32 s10, s15
	s_barrier
	s_cbranch_scc0 .LBB0_3239

; #define PG8_STAGE(bufoff, gbase, voff) do { _Pragma("unroll") for (int _i = 0; _i < 2; ++_i) \
;         __builtin_amdgcn_global_load_lds((const unsigned*)((const char*)(gbase) + (voff)[_i]), (LAS unsigned*)(lds + (bufoff) + ldsw + _i * 8192), 16, 0, 0); } while (0)
; #define PG8_LDA(dst, b, h) do { _Pragma("unroll") for (int m = 0; m < 4; ++m) _Pragma("unroll") for (int k = 0; k < 2; ++k) dst[m][k] = *(const LAS bf16x8*)(lds + PG8_SA(b, h) + aoff + m * 2048 + k * 1024); } while (0)
; #define PG8_LDB(dst, b, h) do { _Pragma("unroll") for (int n = 0; n < 2; ++n) _Pragma("unroll") for (int k = 0; k < 2; ++k) dst[n][k] = *(const LAS bf16x8*)(lds + PG8_SB(b, h) + boff + n * 2048 + k * 1024); } while (0)
; #define PG8_MMA(ai, bj, At, Bt) do { __builtin_amdgcn_s_setprio(1); _Pragma("unroll") for (int m = 0; m < 4; ++m) _Pragma("unroll") for (int n = 0; n < 2; ++n) _Pragma("unroll") for (int k = 0; k < 2; ++k) \
;         acc[ai][bj][m][n] = __builtin_amdgcn_mfma_f32_16x16x32_bf16(Bt[n][k], At[m][k], acc[ai][bj][m][n], 0, 0, 0); __builtin_amdgcn_s_setprio(0); } while (0)
; #define PG8_WAIT_V(n) asm volatile("s_waitcnt vmcnt(" #n ")" ::: "memory")
; #define PG8_WAIT_L(n) asm volatile("s_waitcnt lgkmcnt(" #n ")" ::: "memory")
; #define PG8_BAR __builtin_amdgcn_s_barrier()
; #define PG8_SCHED __builtin_amdgcn_sched_barrier(0)
; template <class Epi>
; __device__ __forceinline__ void gemm_phase(LAS unsigned char* lds, const Gemm g, const StaticOrder& S, const Epi& E) {
;     ...
;         for (int t = 0; t < nt; t += 2) {
;             const bool last = (t == nt - 2);
;             const char* a1 = cA + (size_t)(t + 1) * kstep;
;             const char* a2 = last ? nA : cA + (size_t)(t + 2) * kstep; const char* b2 = last ? nB : cB + (size_t)(t + 2) * kstep;
;             const char* a3 = a2 + kstep; const char* b3 = b2 + kstep;
;             PG8_LDB(B0, 0, 0); PG8_LDB(B1, 0, 1); PG8_SCHED; PG8_LDA(At, 0, 0); PG8_STAGE(PG8_SA(1, 1), a1 + hstepA, voffA);
;             PG8_WAIT_V(8); PG8_WAIT_L(0); PG8_BAR; PG8_MMA(0, 0, At, B0); PG8_MMA(0, 1, At, B1); PG8_BAR; PG8_SCHED;
;             PG8_LDA(At, 0, 1); PG8_STAGE(PG8_SB(0, 0), b2, voffB); PG8_STAGE(PG8_SB(0, 1), b2 + hstepB, voffB); PG8_STAGE(PG8_SA(0, 0), a2, voffA);
;             PG8_WAIT_V(8); PG8_WAIT_L(0); PG8_BAR; PG8_MMA(1, 0, At, B0); PG8_MMA(1, 1, At, B1); PG8_BAR; PG8_SCHED;
.LBB0_3352:
	s_add_i32 s58, s10, 2
	s_add_u32 s59, s0, 0x80
	s_addc_u32 s11, s1, 0
	s_add_i32 s62, 0, 0x10000
	s_cmp_eq_u32 s28, s10
	s_cselect_b32 s11, s9, s11
	s_cselect_b32 s10, s8, s59
	v_add_u32_e32 v145, s62, v177
	s_cselect_b32 s61, s53, s55
	s_cselect_b32 s60, s52, s54
	s_add_i32 s59, 0, 0x14000
	ds_read_b128 v[146:149], v145
	ds_read_b128 v[150:153], v145 offset:1024
	ds_read_b128 v[154:157], v145 offset:2048
	ds_read_b128 v[172:175], v145 offset:3072
	v_add_u32_e32 v145, s59, v177
	ds_read_b128 v[182:185], v145
	ds_read_b128 v[186:189], v145 offset:1024
	ds_read_b128 v[190:193], v145 offset:2048
	ds_read_b128 v[194:197], v145 offset:3072
	v_lshl_add_u64 v[178:179], s[0:1], 0, v[142:143]
	s_add_i32 m0, s21, 0xc000
	ds_read_b128 v[198:201], v181
	ds_read_b128 v[202:205], v181 offset:1024
	ds_read_b128 v[206:209], v181 offset:2048
	ds_read_b128 v[222:225], v181 offset:3072
	ds_read_b128 v[226:229], v181 offset:4096
	ds_read_b128 v[230:233], v181 offset:5120
	ds_read_b128 v[234:237], v181 offset:6144
	ds_read_b128 v[238:241], v181 offset:7168
	global_load_lds_dwordx4 v[178:179], off
	v_lshl_add_u64 v[178:179], s[0:1], 0, v[140:141]
	s_add_i32 m0, s21, 0xe000
	s_nop 0
	global_load_lds_dwordx4 v[178:179], off
	s_waitcnt vmcnt(8)
	s_waitcnt lgkmcnt(0)
	s_barrier
	s_waitcnt lgkmcnt(0)
	v_mfma_f32_16x16x32_bf16 v[126:129], v[146:149], v[198:201], v[126:129]
	v_mfma_f32_16x16x32_bf16 v[122:125], v[154:157], v[198:201], v[122:125]
	v_mfma_f32_16x16x32_bf16 v[110:113], v[146:149], v[206:209], v[110:113]
	v_mfma_f32_16x16x32_bf16 v[106:109], v[154:157], v[206:209], v[106:109]
	v_mfma_f32_16x16x32_bf16 v[94:97], v[146:149], v[226:229], v[94:97]
	v_mfma_f32_16x16x32_bf16 v[90:93], v[154:157], v[226:229], v[90:93]
	v_mfma_f32_16x16x32_bf16 v[78:81], v[146:149], v[234:237], v[78:81]
	v_mfma_f32_16x16x32_bf16 v[74:77], v[154:157], v[234:237], v[74:77]
	v_mfma_f32_16x16x32_bf16 v[126:129], v[150:153], v[202:205], v[126:129]
	v_mfma_f32_16x16x32_bf16 v[122:125], v[172:175], v[202:205], v[122:125]
	v_mfma_f32_16x16x32_bf16 v[110:113], v[150:153], v[222:225], v[110:113]
	v_mfma_f32_16x16x32_bf16 v[106:109], v[172:175], v[222:225], v[106:109]
	v_mfma_f32_16x16x32_bf16 v[94:97], v[150:153], v[230:233], v[94:97]
	v_mfma_f32_16x16x32_bf16 v[90:93], v[172:175], v[230:233], v[90:93]
	v_mfma_f32_16x16x32_bf16 v[78:81], v[150:153], v[238:241], v[78:81]
	v_mfma_f32_16x16x32_bf16 v[74:77], v[172:175], v[238:241], v[74:77]
	v_mfma_f32_16x16x32_bf16 v[118:121], v[182:185], v[198:201], v[118:121]
	v_mfma_f32_16x16x32_bf16 v[114:117], v[190:193], v[198:201], v[114:117]
	v_mfma_f32_16x16x32_bf16 v[102:105], v[182:185], v[206:209], v[102:105]
	v_mfma_f32_16x16x32_bf16 v[98:101], v[190:193], v[206:209], v[98:101]
	v_mfma_f32_16x16x32_bf16 v[86:89], v[182:185], v[226:229], v[86:89]
	v_mfma_f32_16x16x32_bf16 v[82:85], v[190:193], v[226:229], v[82:85]
	v_mfma_f32_16x16x32_bf16 v[70:73], v[182:185], v[234:237], v[70:73]
	v_mfma_f32_16x16x32_bf16 v[66:69], v[190:193], v[234:237], v[66:69]
	v_mfma_f32_16x16x32_bf16 v[118:121], v[186:189], v[202:205], v[118:121]
	v_mfma_f32_16x16x32_bf16 v[114:117], v[194:197], v[202:205], v[114:117]
	v_mfma_f32_16x16x32_bf16 v[102:105], v[186:189], v[222:225], v[102:105]
	v_mfma_f32_16x16x32_bf16 v[98:101], v[194:197], v[222:225], v[98:101]
	v_mfma_f32_16x16x32_bf16 v[86:89], v[186:189], v[230:233], v[86:89]
	v_mfma_f32_16x16x32_bf16 v[82:85], v[194:197], v[230:233], v[82:85]
	v_mfma_f32_16x16x32_bf16 v[70:73], v[186:189], v[238:241], v[70:73]
	v_mfma_f32_16x16x32_bf16 v[66:69], v[194:197], v[238:241], v[66:69]
	s_barrier
	s_add_i32 s62, s62, s20
	v_lshl_add_u64 v[178:179], s[60:61], 0, v[134:135]
	s_mov_b32 m0, s62
	ds_read_b128 v[198:201], v181 offset:16384
	ds_read_b128 v[202:205], v181 offset:17408
	ds_read_b128 v[206:209], v181 offset:18432
	ds_read_b128 v[222:225], v181 offset:19456
	ds_read_b128 v[226:229], v181 offset:20480
	ds_read_b128 v[230:233], v181 offset:21504
	ds_read_b128 v[234:237], v181 offset:22528
	ds_read_b128 v[238:241], v181 offset:23552
	global_load_lds_dwordx4 v[178:179], off
	s_add_i32 m0, s62, 0x2000
	v_lshl_add_u64 v[216:217], s[60:61], 0, v[130:131]
	s_add_u32 s60, s60, s38
	s_addc_u32 s61, s61, s39
	s_add_i32 s59, s59, s20
	global_load_lds_dwordx4 v[216:217], off
	v_lshl_add_u64 v[218:219], s[60:61], 0, v[134:135]
	s_mov_b32 m0, s59
	v_lshl_add_u64 v[242:243], s[60:61], 0, v[130:131]
	global_load_lds_dwordx4 v[218:219], off
	s_add_i32 m0, s59, 0x2000
	v_lshl_add_u64 v[244:245], s[10:11], 0, v[136:137]
	global_load_lds_dwordx4 v[242:243], off
	s_mov_b32 m0, s21
	v_lshl_add_u64 v[246:247], s[10:11], 0, v[132:133]
	global_load_lds_dwordx4 v[244:245], off
	s_mov_b32 m0, s22
	s_nop 0
	global_load_lds_dwordx4 v[246:247], off
	s_waitcnt vmcnt(8)
	s_waitcnt lgkmcnt(0)
	s_barrier
; #define PG8_STAGE(bufoff, gbase, voff) do { _Pragma("unroll") for (int _i = 0; _i < 2; ++_i) \
;         __builtin_amdgcn_global_load_lds((const unsigned*)((const char*)(gbase) + (voff)[_i]), (LAS unsigned*)(lds + (bufoff) + ldsw + _i * 8192), 16, 0, 0); } while (0)
; #define PG8_LDA(dst, b, h) do { _Pragma("unroll") for (int m = 0; m < 4; ++m) _Pragma("unroll") for (int k = 0; k < 2; ++k) dst[m][k] = *(const LAS bf16x8*)(lds + PG8_SA(b, h) + aoff + m * 2048 + k * 1024); } while (0)
; #define PG8_LDB(dst, b, h) do { _Pragma("unroll") for (int n = 0; n < 2; ++n) _Pragma("unroll") for (int k = 0; k < 2; ++k) dst[n][k] = *(const LAS bf16x8*)(lds + PG8_SB(b, h) + boff + n * 2048 + k * 1024); } while (0)
; #define PG8_MMA(ai, bj, At, Bt) do { __builtin_amdgcn_s_setprio(1); _Pragma("unroll") for (int m = 0; m < 4; ++m) _Pragma("unroll") for (int n = 0; n < 2; ++n) _Pragma("unroll") for (int k = 0; k < 2; ++k) \
;         acc[ai][bj][m][n] = __builtin_amdgcn_mfma_f32_16x16x32_bf16(Bt[n][k], At[m][k], acc[ai][bj][m][n], 0, 0, 0); __builtin_amdgcn_s_setprio(0); } while (0)
; #define PG8_WAIT_V(n) asm volatile("s_waitcnt vmcnt(" #n ")" ::: "memory")
; #define PG8_WAIT_L(n) asm volatile("s_waitcnt lgkmcnt(" #n ")" ::: "memory")
; #define PG8_BAR __builtin_amdgcn_s_barrier()
; #define PG8_SCHED __builtin_amdgcn_sched_barrier(0)
; template <class Epi>
; __device__ __forceinline__ void gemm_phase(LAS unsigned char* lds, const Gemm g, const StaticOrder& S, const Epi& E) {
;     ...
;             PG8_WAIT_V(8); PG8_WAIT_L(0); PG8_BAR; PG8_MMA(1, 0, At, B0); PG8_MMA(1, 1, At, B1); PG8_BAR; PG8_SCHED;
;             PG8_LDB(B0, 1, 0); PG8_LDB(B1, 1, 1); PG8_SCHED; PG8_LDA(At, 1, 0); PG8_STAGE(PG8_SA(0, 1), a2 + hstepA, voffA);
;             PG8_WAIT_V(8); PG8_WAIT_L(0); PG8_BAR; PG8_MMA(0, 0, At, B0); PG8_MMA(0, 1, At, B1); PG8_BAR; PG8_SCHED;
	s_waitcnt lgkmcnt(0)
	v_mfma_f32_16x16x32_bf16 v[60:63], v[146:149], v[198:201], v[60:63]
	v_mfma_f32_16x16x32_bf16 v[56:59], v[154:157], v[198:201], v[56:59]
	v_mfma_f32_16x16x32_bf16 v[44:47], v[146:149], v[206:209], v[44:47]
	v_mfma_f32_16x16x32_bf16 v[40:43], v[154:157], v[206:209], v[40:43]
	v_mfma_f32_16x16x32_bf16 v[28:31], v[146:149], v[226:229], v[28:31]
	v_mfma_f32_16x16x32_bf16 v[24:27], v[154:157], v[226:229], v[24:27]
	v_mfma_f32_16x16x32_bf16 v[12:15], v[146:149], v[234:237], v[12:15]
	v_mfma_f32_16x16x32_bf16 v[8:11], v[154:157], v[234:237], v[8:11]
	v_mfma_f32_16x16x32_bf16 v[60:63], v[150:153], v[202:205], v[60:63]
	v_mfma_f32_16x16x32_bf16 v[56:59], v[172:175], v[202:205], v[56:59]
	v_mfma_f32_16x16x32_bf16 v[44:47], v[150:153], v[222:225], v[44:47]
	v_mfma_f32_16x16x32_bf16 v[40:43], v[172:175], v[222:225], v[40:43]
	v_mfma_f32_16x16x32_bf16 v[28:31], v[150:153], v[230:233], v[28:31]
	v_mfma_f32_16x16x32_bf16 v[24:27], v[172:175], v[230:233], v[24:27]
	v_mfma_f32_16x16x32_bf16 v[12:15], v[150:153], v[238:241], v[12:15]
	v_mfma_f32_16x16x32_bf16 v[8:11], v[172:175], v[238:241], v[8:11]
	v_mfma_f32_16x16x32_bf16 v[52:55], v[182:185], v[198:201], v[52:55]
	v_mfma_f32_16x16x32_bf16 v[48:51], v[190:193], v[198:201], v[48:51]
	v_mfma_f32_16x16x32_bf16 v[36:39], v[182:185], v[206:209], v[36:39]
	v_mfma_f32_16x16x32_bf16 v[32:35], v[190:193], v[206:209], v[32:35]
	v_mfma_f32_16x16x32_bf16 v[20:23], v[182:185], v[226:229], v[20:23]
	v_mfma_f32_16x16x32_bf16 v[16:19], v[190:193], v[226:229], v[16:19]
	v_mfma_f32_16x16x32_bf16 v[4:7], v[182:185], v[234:237], v[4:7]
	v_mfma_f32_16x16x32_bf16 v[0:3], v[190:193], v[234:237], v[0:3]
	v_mfma_f32_16x16x32_bf16 v[52:55], v[186:189], v[202:205], v[52:55]
	v_mfma_f32_16x16x32_bf16 v[48:51], v[194:197], v[202:205], v[48:51]
	v_mfma_f32_16x16x32_bf16 v[36:39], v[186:189], v[222:225], v[36:39]
	v_mfma_f32_16x16x32_bf16 v[32:35], v[194:197], v[222:225], v[32:35]
	v_mfma_f32_16x16x32_bf16 v[20:23], v[186:189], v[230:233], v[20:23]
	v_mfma_f32_16x16x32_bf16 v[16:19], v[194:197], v[230:233], v[16:19]
	v_mfma_f32_16x16x32_bf16 v[4:7], v[186:189], v[238:241], v[4:7]
	v_mfma_f32_16x16x32_bf16 v[0:3], v[194:197], v[238:241], v[0:3]
	s_barrier
	s_add_i32 s59, 0, 0x18000
	v_add_u32_e32 v145, s59, v177
	s_add_i32 s60, 0, 0x1c000
	ds_read_b128 v[146:149], v145
	ds_read_b128 v[150:153], v145 offset:1024
	ds_read_b128 v[154:157], v145 offset:2048
	ds_read_b128 v[172:175], v145 offset:3072
	v_add_u32_e32 v145, s60, v177
	ds_read_b128 v[182:185], v145
	ds_read_b128 v[186:189], v145 offset:1024
	ds_read_b128 v[190:193], v145 offset:2048
	ds_read_b128 v[194:197], v145 offset:3072
	s_add_u32 s10, s10, s6
	s_addc_u32 s11, s11, s7
	s_mov_b32 m0, s23
	v_lshl_add_u64 v[248:249], s[10:11], 0, v[136:137]
	ds_read_b128 v[198:201], v181 offset:32768
	ds_read_b128 v[202:205], v181 offset:33792
	ds_read_b128 v[206:209], v181 offset:34816
	ds_read_b128 v[222:225], v181 offset:35840
	ds_read_b128 v[226:229], v181 offset:36864
	ds_read_b128 v[230:233], v181 offset:37888
	ds_read_b128 v[234:237], v181 offset:38912
	ds_read_b128 v[238:241], v181 offset:39936
	global_load_lds_dwordx4 v[248:249], off
	v_lshl_add_u64 v[248:249], s[10:11], 0, v[132:133]
	s_mov_b32 m0, s24
	s_nop 0
	global_load_lds_dwordx4 v[248:249], off
	s_waitcnt vmcnt(8)
	s_waitcnt lgkmcnt(0)
	s_barrier
	s_waitcnt lgkmcnt(0)
	v_mfma_f32_16x16x32_bf16 v[126:129], v[146:149], v[198:201], v[126:129]
	v_mfma_f32_16x16x32_bf16 v[122:125], v[154:157], v[198:201], v[122:125]
	v_mfma_f32_16x16x32_bf16 v[110:113], v[146:149], v[206:209], v[110:113]
	v_mfma_f32_16x16x32_bf16 v[106:109], v[154:157], v[206:209], v[106:109]
	v_mfma_f32_16x16x32_bf16 v[94:97], v[146:149], v[226:229], v[94:97]
	v_mfma_f32_16x16x32_bf16 v[90:93], v[154:157], v[226:229], v[90:93]
	v_mfma_f32_16x16x32_bf16 v[78:81], v[146:149], v[234:237], v[78:81]
	v_mfma_f32_16x16x32_bf16 v[74:77], v[154:157], v[234:237], v[74:77]
	v_mfma_f32_16x16x32_bf16 v[126:129], v[150:153], v[202:205], v[126:129]
	v_mfma_f32_16x16x32_bf16 v[122:125], v[172:175], v[202:205], v[122:125]
	v_mfma_f32_16x16x32_bf16 v[110:113], v[150:153], v[222:225], v[110:113]
	v_mfma_f32_16x16x32_bf16 v[106:109], v[172:175], v[222:225], v[106:109]
	v_mfma_f32_16x16x32_bf16 v[94:97], v[150:153], v[230:233], v[94:97]
	v_mfma_f32_16x16x32_bf16 v[90:93], v[172:175], v[230:233], v[90:93]
	v_mfma_f32_16x16x32_bf16 v[78:81], v[150:153], v[238:241], v[78:81]
	v_mfma_f32_16x16x32_bf16 v[74:77], v[172:175], v[238:241], v[74:77]
	v_mfma_f32_16x16x32_bf16 v[118:121], v[182:185], v[198:201], v[118:121]
	v_mfma_f32_16x16x32_bf16 v[114:117], v[190:193], v[198:201], v[114:117]
	v_mfma_f32_16x16x32_bf16 v[102:105], v[182:185], v[206:209], v[102:105]
	v_mfma_f32_16x16x32_bf16 v[98:101], v[190:193], v[206:209], v[98:101]
	v_mfma_f32_16x16x32_bf16 v[86:89], v[182:185], v[226:229], v[86:89]
	v_mfma_f32_16x16x32_bf16 v[82:85], v[190:193], v[226:229], v[82:85]
	v_mfma_f32_16x16x32_bf16 v[70:73], v[182:185], v[234:237], v[70:73]
	v_mfma_f32_16x16x32_bf16 v[66:69], v[190:193], v[234:237], v[66:69]
	v_mfma_f32_16x16x32_bf16 v[118:121], v[186:189], v[202:205], v[118:121]
	v_mfma_f32_16x16x32_bf16 v[114:117], v[194:197], v[202:205], v[114:117]
	v_mfma_f32_16x16x32_bf16 v[102:105], v[186:189], v[222:225], v[102:105]
	v_mfma_f32_16x16x32_bf16 v[98:101], v[194:197], v[222:225], v[98:101]
	v_mfma_f32_16x16x32_bf16 v[86:89], v[186:189], v[230:233], v[86:89]
	v_mfma_f32_16x16x32_bf16 v[82:85], v[194:197], v[230:233], v[82:85]
	v_mfma_f32_16x16x32_bf16 v[70:73], v[186:189], v[238:241], v[70:73]
	v_mfma_f32_16x16x32_bf16 v[66:69], v[194:197], v[238:241], v[66:69]
	s_barrier
; #define PG8_STAGE(bufoff, gbase, voff) do { _Pragma("unroll") for (int _i = 0; _i < 2; ++_i) \
;         __builtin_amdgcn_global_load_lds((const unsigned*)((const char*)(gbase) + (voff)[_i]), (LAS unsigned*)(lds + (bufoff) + ldsw + _i * 8192), 16, 0, 0); } while (0)
; #define PG8_LDA(dst, b, h) do { _Pragma("unroll") for (int m = 0; m < 4; ++m) _Pragma("unroll") for (int k = 0; k < 2; ++k) dst[m][k] = *(const LAS bf16x8*)(lds + PG8_SA(b, h) + aoff + m * 2048 + k * 1024); } while (0)
; #define PG8_MMA(ai, bj, At, Bt) do { __builtin_amdgcn_s_setprio(1); _Pragma("unroll") for (int m = 0; m < 4; ++m) _Pragma("unroll") for (int n = 0; n < 2; ++n) _Pragma("unroll") for (int k = 0; k < 2; ++k) \
;         acc[ai][bj][m][n] = __builtin_amdgcn_mfma_f32_16x16x32_bf16(Bt[n][k], At[m][k], acc[ai][bj][m][n], 0, 0, 0); __builtin_amdgcn_s_setprio(0); } while (0)
; #define PG8_WAIT_V(n) asm volatile("s_waitcnt vmcnt(" #n ")" ::: "memory")
; #define PG8_WAIT_L(n) asm volatile("s_waitcnt lgkmcnt(" #n ")" ::: "memory")
; #define PG8_BAR __builtin_amdgcn_s_barrier()
; #define PG8_SCHED __builtin_amdgcn_sched_barrier(0)
; template <class Epi>
; __device__ __forceinline__ void gemm_phase(LAS unsigned char* lds, const Gemm g, const StaticOrder& S, const Epi& E) {
;     ...
;             PG8_LDA(At, 1, 1); PG8_STAGE(PG8_SB(1, 0), b3, voffB); PG8_STAGE(PG8_SB(1, 1), b3 + hstepB, voffB); PG8_STAGE(PG8_SA(1, 0), a3, voffA);
;             PG8_WAIT_V(8); PG8_WAIT_L(0); PG8_BAR; PG8_MMA(1, 0, At, B0); PG8_MMA(1, 1, At, B1); PG8_BAR; PG8_SCHED;
;         }
	s_add_i32 s10, s59, s20
	v_lshl_add_u64 v[178:179], v[178:179], 0, s[82:83]
	s_mov_b32 m0, s10
	ds_read_b128 v[198:201], v181 offset:49152
	ds_read_b128 v[202:205], v181 offset:50176
	ds_read_b128 v[206:209], v181 offset:51200
	ds_read_b128 v[222:225], v181 offset:52224
	ds_read_b128 v[226:229], v181 offset:53248
	ds_read_b128 v[230:233], v181 offset:54272
	ds_read_b128 v[234:237], v181 offset:55296
	ds_read_b128 v[238:241], v181 offset:56320
	global_load_lds_dwordx4 v[178:179], off
	v_lshl_add_u64 v[178:179], v[216:217], 0, s[82:83]
	s_add_i32 m0, s10, 0x2000
	s_add_i32 s10, s60, s20
	global_load_lds_dwordx4 v[178:179], off
	v_lshl_add_u64 v[178:179], v[218:219], 0, s[82:83]
	s_mov_b32 m0, s10
	s_nop 0
	global_load_lds_dwordx4 v[178:179], off
	v_lshl_add_u64 v[178:179], v[242:243], 0, s[82:83]
	s_add_i32 m0, s10, 0x2000
	s_nop 0
	global_load_lds_dwordx4 v[178:179], off
	v_lshl_add_u64 v[178:179], v[244:245], 0, s[82:83]
	s_mov_b32 m0, s25
	s_nop 0
	global_load_lds_dwordx4 v[178:179], off
	v_lshl_add_u64 v[178:179], v[246:247], 0, s[82:83]
	s_mov_b32 m0, s26
	s_nop 0
	global_load_lds_dwordx4 v[178:179], off
	s_waitcnt vmcnt(8)
	s_waitcnt lgkmcnt(0)
	s_barrier
	s_waitcnt lgkmcnt(0)
	v_mfma_f32_16x16x32_bf16 v[60:63], v[146:149], v[198:201], v[60:63]
	v_mfma_f32_16x16x32_bf16 v[56:59], v[154:157], v[198:201], v[56:59]
	v_mfma_f32_16x16x32_bf16 v[44:47], v[146:149], v[206:209], v[44:47]
	v_mfma_f32_16x16x32_bf16 v[40:43], v[154:157], v[206:209], v[40:43]
	v_mfma_f32_16x16x32_bf16 v[28:31], v[146:149], v[226:229], v[28:31]
	v_mfma_f32_16x16x32_bf16 v[24:27], v[154:157], v[226:229], v[24:27]
	v_mfma_f32_16x16x32_bf16 v[12:15], v[146:149], v[234:237], v[12:15]
	v_mfma_f32_16x16x32_bf16 v[8:11], v[154:157], v[234:237], v[8:11]
	v_mfma_f32_16x16x32_bf16 v[60:63], v[150:153], v[202:205], v[60:63]
	v_mfma_f32_16x16x32_bf16 v[56:59], v[172:175], v[202:205], v[56:59]
	v_mfma_f32_16x16x32_bf16 v[44:47], v[150:153], v[222:225], v[44:47]
	v_mfma_f32_16x16x32_bf16 v[40:43], v[172:175], v[222:225], v[40:43]
	v_mfma_f32_16x16x32_bf16 v[28:31], v[150:153], v[230:233], v[28:31]
	v_mfma_f32_16x16x32_bf16 v[24:27], v[172:175], v[230:233], v[24:27]
	v_mfma_f32_16x16x32_bf16 v[12:15], v[150:153], v[238:241], v[12:15]
	v_mfma_f32_16x16x32_bf16 v[8:11], v[172:175], v[238:241], v[8:11]
	v_mfma_f32_16x16x32_bf16 v[52:55], v[182:185], v[198:201], v[52:55]
	v_mfma_f32_16x16x32_bf16 v[48:51], v[190:193], v[198:201], v[48:51]
	v_mfma_f32_16x16x32_bf16 v[36:39], v[182:185], v[206:209], v[36:39]
	v_mfma_f32_16x16x32_bf16 v[32:35], v[190:193], v[206:209], v[32:35]
	v_mfma_f32_16x16x32_bf16 v[20:23], v[182:185], v[226:229], v[20:23]
	v_mfma_f32_16x16x32_bf16 v[16:19], v[190:193], v[226:229], v[16:19]
	v_mfma_f32_16x16x32_bf16 v[4:7], v[182:185], v[234:237], v[4:7]
	v_mfma_f32_16x16x32_bf16 v[0:3], v[190:193], v[234:237], v[0:3]
	v_mfma_f32_16x16x32_bf16 v[52:55], v[186:189], v[202:205], v[52:55]
	v_mfma_f32_16x16x32_bf16 v[48:51], v[194:197], v[202:205], v[48:51]
	v_mfma_f32_16x16x32_bf16 v[36:39], v[186:189], v[222:225], v[36:39]
	v_mfma_f32_16x16x32_bf16 v[32:35], v[194:197], v[222:225], v[32:35]
	v_mfma_f32_16x16x32_bf16 v[20:23], v[186:189], v[230:233], v[20:23]
	v_mfma_f32_16x16x32_bf16 v[16:19], v[194:197], v[230:233], v[16:19]
	v_mfma_f32_16x16x32_bf16 v[4:7], v[186:189], v[238:241], v[4:7]
	v_mfma_f32_16x16x32_bf16 v[0:3], v[194:197], v[238:241], v[0:3]
	s_add_u32 s54, s54, 0x100
	s_addc_u32 s55, s55, 0
	s_add_u32 s0, s0, 0x100
	s_addc_u32 s1, s1, 0
	s_cmp_ge_i32 s58, s27
	s_mov_b32 s10, s58
	s_barrier
	s_cbranch_scc0 .LBB0_3352

; #define PG8_STAGE(bufoff, gbase, voff) do { _Pragma("unroll") for (int _i = 0; _i < 2; ++_i) \
;         __builtin_amdgcn_global_load_lds((const unsigned*)((const char*)(gbase) + (voff)[_i]), (LAS unsigned*)(lds + (bufoff) + ldsw + _i * 8192), 16, 0, 0); } while (0)
; #define PG8_LDA(dst, b, h) do { _Pragma("unroll") for (int m = 0; m < 4; ++m) _Pragma("unroll") for (int k = 0; k < 2; ++k) dst[m][k] = *(const LAS bf16x8*)(lds + PG8_SA(b, h) + aoff + m * 2048 + k * 1024); } while (0)
; #define PG8_LDB(dst, b, h) do { _Pragma("unroll") for (int n = 0; n < 2; ++n) _Pragma("unroll") for (int k = 0; k < 2; ++k) dst[n][k] = *(const LAS bf16x8*)(lds + PG8_SB(b, h) + boff + n * 2048 + k * 1024); } while (0)
; #define PG8_MMA(ai, bj, At, Bt) do { __builtin_amdgcn_s_setprio(1); _Pragma("unroll") for (int m = 0; m < 4; ++m) _Pragma("unroll") for (int n = 0; n < 2; ++n) _Pragma("unroll") for (int k = 0; k < 2; ++k) \
;         acc[ai][bj][m][n] = __builtin_amdgcn_mfma_f32_16x16x32_bf16(Bt[n][k], At[m][k], acc[ai][bj][m][n], 0, 0, 0); __builtin_amdgcn_s_setprio(0); } while (0)
; #define PG8_WAIT_V(n) asm volatile("s_waitcnt vmcnt(" #n ")" ::: "memory")
; #define PG8_WAIT_L(n) asm volatile("s_waitcnt lgkmcnt(" #n ")" ::: "memory")
; #define PG8_BAR __builtin_amdgcn_s_barrier()
; #define PG8_SCHED __builtin_amdgcn_sched_barrier(0)
; template <class Epi>
; __device__ __forceinline__ void gemm_phase(LAS unsigned char* lds, const Gemm g, const StaticOrder& S, const Epi& E) {
;     ...
;         for (int t = 0; t < nt; t += 2) {
;             const bool last = (t == nt - 2);
;             const char* a1 = cA + (size_t)(t + 1) * kstep;
;             const char* a2 = last ? nA : cA + (size_t)(t + 2) * kstep; const char* b2 = last ? nB : cB + (size_t)(t + 2) * kstep;
;             const char* a3 = a2 + kstep; const char* b3 = b2 + kstep;
;             PG8_LDB(B0, 0, 0); PG8_LDB(B1, 0, 1); PG8_SCHED; PG8_LDA(At, 0, 0); PG8_STAGE(PG8_SA(1, 1), a1 + hstepA, voffA);
;             PG8_WAIT_V(8); PG8_WAIT_L(0); PG8_BAR; PG8_MMA(0, 0, At, B0); PG8_MMA(0, 1, At, B1); PG8_BAR; PG8_SCHED;
;             PG8_LDA(At, 0, 1); PG8_STAGE(PG8_SB(0, 0), b2, voffB); PG8_STAGE(PG8_SB(0, 1), b2 + hstepB, voffB); PG8_STAGE(PG8_SA(0, 0), a2, voffA);
;             PG8_WAIT_V(8); PG8_WAIT_L(0); PG8_BAR; PG8_MMA(1, 0, At, B0); PG8_MMA(1, 1, At, B1); PG8_BAR; PG8_SCHED;
.LBB0_3377:
	s_add_i32 s30, s8, 2
	s_add_u32 s31, s0, 0x80
	s_addc_u32 s9, s1, 0
	s_add_i32 s40, 0, 0x10000
	s_cmp_eq_u32 s64, s8
	s_cselect_b32 s9, s5, s9
	s_cselect_b32 s8, s4, s31
	s_cselect_b32 s35, s61, s29
	s_cselect_b32 s34, s60, s11
	s_add_i32 s31, 0, 0x14000
	v_add_u32_e32 v172, s40, v139
	v_add_u32_e32 v188, s31, v139
	ds_read_b128 v[146:149], v172
	ds_read_b128 v[150:153], v172 offset:1024
	ds_read_b128 v[154:157], v172 offset:2048
	ds_read_b128 v[172:175], v172 offset:3072
	ds_read_b128 v[176:179], v188
	ds_read_b128 v[180:183], v188 offset:1024
	ds_read_b128 v[184:187], v188 offset:2048
	ds_read_b128 v[188:191], v188 offset:3072
	v_lshl_add_u64 v[216:217], s[0:1], 0, v[144:145]
	s_add_i32 m0, s21, 0xc000
	ds_read_b128 v[192:195], v200
	ds_read_b128 v[196:199], v200 offset:1024
	ds_read_b128 v[202:205], v200 offset:2048
	ds_read_b128 v[206:209], v200 offset:3072
	ds_read_b128 v[222:225], v200 offset:4096
	ds_read_b128 v[226:229], v200 offset:5120
	ds_read_b128 v[230:233], v200 offset:6144
	ds_read_b128 v[234:237], v200 offset:7168
	global_load_lds_dwordx4 v[216:217], off
	v_lshl_add_u64 v[216:217], s[0:1], 0, v[142:143]
	s_add_i32 m0, s21, 0xe000
	s_nop 0
	global_load_lds_dwordx4 v[216:217], off
	s_waitcnt vmcnt(8)
	s_waitcnt lgkmcnt(0)
	s_barrier
	s_waitcnt lgkmcnt(0)
	v_mfma_f32_16x16x32_bf16 v[126:129], v[146:149], v[192:195], v[126:129]
	v_mfma_f32_16x16x32_bf16 v[122:125], v[154:157], v[192:195], v[122:125]
	v_mfma_f32_16x16x32_bf16 v[110:113], v[146:149], v[202:205], v[110:113]
	v_mfma_f32_16x16x32_bf16 v[106:109], v[154:157], v[202:205], v[106:109]
	v_mfma_f32_16x16x32_bf16 v[94:97], v[146:149], v[222:225], v[94:97]
	v_mfma_f32_16x16x32_bf16 v[90:93], v[154:157], v[222:225], v[90:93]
	v_mfma_f32_16x16x32_bf16 v[78:81], v[146:149], v[230:233], v[78:81]
	v_mfma_f32_16x16x32_bf16 v[74:77], v[154:157], v[230:233], v[74:77]
	v_mfma_f32_16x16x32_bf16 v[126:129], v[150:153], v[196:199], v[126:129]
	v_mfma_f32_16x16x32_bf16 v[122:125], v[172:175], v[196:199], v[122:125]
	v_mfma_f32_16x16x32_bf16 v[110:113], v[150:153], v[206:209], v[110:113]
	v_mfma_f32_16x16x32_bf16 v[106:109], v[172:175], v[206:209], v[106:109]
	v_mfma_f32_16x16x32_bf16 v[94:97], v[150:153], v[226:229], v[94:97]
	v_mfma_f32_16x16x32_bf16 v[90:93], v[172:175], v[226:229], v[90:93]
	v_mfma_f32_16x16x32_bf16 v[78:81], v[150:153], v[234:237], v[78:81]
	v_mfma_f32_16x16x32_bf16 v[74:77], v[172:175], v[234:237], v[74:77]
	v_mfma_f32_16x16x32_bf16 v[118:121], v[176:179], v[192:195], v[118:121]
	v_mfma_f32_16x16x32_bf16 v[114:117], v[184:187], v[192:195], v[114:117]
	v_mfma_f32_16x16x32_bf16 v[102:105], v[176:179], v[202:205], v[102:105]
	v_mfma_f32_16x16x32_bf16 v[98:101], v[184:187], v[202:205], v[98:101]
	v_mfma_f32_16x16x32_bf16 v[86:89], v[176:179], v[222:225], v[86:89]
	v_mfma_f32_16x16x32_bf16 v[82:85], v[184:187], v[222:225], v[82:85]
	v_mfma_f32_16x16x32_bf16 v[70:73], v[176:179], v[230:233], v[70:73]
	v_mfma_f32_16x16x32_bf16 v[66:69], v[184:187], v[230:233], v[66:69]
	v_mfma_f32_16x16x32_bf16 v[118:121], v[180:183], v[196:199], v[118:121]
	v_mfma_f32_16x16x32_bf16 v[114:117], v[188:191], v[196:199], v[114:117]
	v_mfma_f32_16x16x32_bf16 v[102:105], v[180:183], v[206:209], v[102:105]
	v_mfma_f32_16x16x32_bf16 v[98:101], v[188:191], v[206:209], v[98:101]
	v_mfma_f32_16x16x32_bf16 v[86:89], v[180:183], v[226:229], v[86:89]
	v_mfma_f32_16x16x32_bf16 v[82:85], v[188:191], v[226:229], v[82:85]
	v_mfma_f32_16x16x32_bf16 v[70:73], v[180:183], v[234:237], v[70:73]
	v_mfma_f32_16x16x32_bf16 v[66:69], v[188:191], v[234:237], v[66:69]
	s_barrier
	s_add_i32 s40, s40, s20
	v_lshl_add_u64 v[216:217], s[34:35], 0, v[134:135]
	s_mov_b32 m0, s40
	ds_read_b128 v[192:195], v200 offset:16384
	ds_read_b128 v[196:199], v200 offset:17408
	ds_read_b128 v[202:205], v200 offset:18432
	ds_read_b128 v[206:209], v200 offset:19456
	ds_read_b128 v[222:225], v200 offset:20480
	ds_read_b128 v[226:229], v200 offset:21504
	ds_read_b128 v[230:233], v200 offset:22528
	ds_read_b128 v[234:237], v200 offset:23552
	global_load_lds_dwordx4 v[216:217], off
	s_add_i32 m0, s40, 0x2000
	v_lshl_add_u64 v[218:219], s[34:35], 0, v[130:131]
	s_add_u32 s34, s34, s36
	s_addc_u32 s35, s35, s37
	s_add_i32 s31, s31, s20
	global_load_lds_dwordx4 v[218:219], off
	v_lshl_add_u64 v[238:239], s[34:35], 0, v[134:135]
	s_mov_b32 m0, s31
	v_lshl_add_u64 v[240:241], s[34:35], 0, v[130:131]
	global_load_lds_dwordx4 v[238:239], off
	s_add_i32 m0, s31, 0x2000
	v_lshl_add_u64 v[242:243], s[8:9], 0, v[136:137]
	global_load_lds_dwordx4 v[240:241], off
	s_mov_b32 m0, s21
	v_lshl_add_u64 v[244:245], s[8:9], 0, v[132:133]
	global_load_lds_dwordx4 v[242:243], off
	s_mov_b32 m0, s22
	s_nop 0
	global_load_lds_dwordx4 v[244:245], off
	s_waitcnt vmcnt(8)
	s_waitcnt lgkmcnt(0)
	s_barrier
; #define PG8_STAGE(bufoff, gbase, voff) do { _Pragma("unroll") for (int _i = 0; _i < 2; ++_i) \
;         __builtin_amdgcn_global_load_lds((const unsigned*)((const char*)(gbase) + (voff)[_i]), (LAS unsigned*)(lds + (bufoff) + ldsw + _i * 8192), 16, 0, 0); } while (0)
; #define PG8_LDA(dst, b, h) do { _Pragma("unroll") for (int m = 0; m < 4; ++m) _Pragma("unroll") for (int k = 0; k < 2; ++k) dst[m][k] = *(const LAS bf16x8*)(lds + PG8_SA(b, h) + aoff + m * 2048 + k * 1024); } while (0)
; #define PG8_LDB(dst, b, h) do { _Pragma("unroll") for (int n = 0; n < 2; ++n) _Pragma("unroll") for (int k = 0; k < 2; ++k) dst[n][k] = *(const LAS bf16x8*)(lds + PG8_SB(b, h) + boff + n * 2048 + k * 1024); } while (0)
; #define PG8_MMA(ai, bj, At, Bt) do { __builtin_amdgcn_s_setprio(1); _Pragma("unroll") for (int m = 0; m < 4; ++m) _Pragma("unroll") for (int n = 0; n < 2; ++n) _Pragma("unroll") for (int k = 0; k < 2; ++k) \
;         acc[ai][bj][m][n] = __builtin_amdgcn_mfma_f32_16x16x32_bf16(Bt[n][k], At[m][k], acc[ai][bj][m][n], 0, 0, 0); __builtin_amdgcn_s_setprio(0); } while (0)
; #define PG8_WAIT_V(n) asm volatile("s_waitcnt vmcnt(" #n ")" ::: "memory")
; #define PG8_WAIT_L(n) asm volatile("s_waitcnt lgkmcnt(" #n ")" ::: "memory")
; #define PG8_BAR __builtin_amdgcn_s_barrier()
; #define PG8_SCHED __builtin_amdgcn_sched_barrier(0)
; template <class Epi>
; __device__ __forceinline__ void gemm_phase(LAS unsigned char* lds, const Gemm g, const StaticOrder& S, const Epi& E) {
;     ...
;             PG8_WAIT_V(8); PG8_WAIT_L(0); PG8_BAR; PG8_MMA(1, 0, At, B0); PG8_MMA(1, 1, At, B1); PG8_BAR; PG8_SCHED;
;             PG8_LDB(B0, 1, 0); PG8_LDB(B1, 1, 1); PG8_SCHED; PG8_LDA(At, 1, 0); PG8_STAGE(PG8_SA(0, 1), a2 + hstepA, voffA);
;             PG8_WAIT_V(8); PG8_WAIT_L(0); PG8_BAR; PG8_MMA(0, 0, At, B0); PG8_MMA(0, 1, At, B1); PG8_BAR; PG8_SCHED;
	s_waitcnt lgkmcnt(0)
	v_mfma_f32_16x16x32_bf16 v[60:63], v[146:149], v[192:195], v[60:63]
	v_mfma_f32_16x16x32_bf16 v[56:59], v[154:157], v[192:195], v[56:59]
	v_mfma_f32_16x16x32_bf16 v[44:47], v[146:149], v[202:205], v[44:47]
	v_mfma_f32_16x16x32_bf16 v[40:43], v[154:157], v[202:205], v[40:43]
	v_mfma_f32_16x16x32_bf16 v[28:31], v[146:149], v[222:225], v[28:31]
	v_mfma_f32_16x16x32_bf16 v[24:27], v[154:157], v[222:225], v[24:27]
	v_mfma_f32_16x16x32_bf16 v[12:15], v[146:149], v[230:233], v[12:15]
	v_mfma_f32_16x16x32_bf16 v[8:11], v[154:157], v[230:233], v[8:11]
	v_mfma_f32_16x16x32_bf16 v[60:63], v[150:153], v[196:199], v[60:63]
	v_mfma_f32_16x16x32_bf16 v[56:59], v[172:175], v[196:199], v[56:59]
	v_mfma_f32_16x16x32_bf16 v[44:47], v[150:153], v[206:209], v[44:47]
	v_mfma_f32_16x16x32_bf16 v[40:43], v[172:175], v[206:209], v[40:43]
	v_mfma_f32_16x16x32_bf16 v[28:31], v[150:153], v[226:229], v[28:31]
	v_mfma_f32_16x16x32_bf16 v[24:27], v[172:175], v[226:229], v[24:27]
	v_mfma_f32_16x16x32_bf16 v[12:15], v[150:153], v[234:237], v[12:15]
	v_mfma_f32_16x16x32_bf16 v[8:11], v[172:175], v[234:237], v[8:11]
	v_mfma_f32_16x16x32_bf16 v[52:55], v[176:179], v[192:195], v[52:55]
	v_mfma_f32_16x16x32_bf16 v[48:51], v[184:187], v[192:195], v[48:51]
	v_mfma_f32_16x16x32_bf16 v[36:39], v[176:179], v[202:205], v[36:39]
	v_mfma_f32_16x16x32_bf16 v[32:35], v[184:187], v[202:205], v[32:35]
	v_mfma_f32_16x16x32_bf16 v[20:23], v[176:179], v[222:225], v[20:23]
	v_mfma_f32_16x16x32_bf16 v[16:19], v[184:187], v[222:225], v[16:19]
	v_mfma_f32_16x16x32_bf16 v[4:7], v[176:179], v[230:233], v[4:7]
	v_mfma_f32_16x16x32_bf16 v[0:3], v[184:187], v[230:233], v[0:3]
	v_mfma_f32_16x16x32_bf16 v[52:55], v[180:183], v[196:199], v[52:55]
	v_mfma_f32_16x16x32_bf16 v[48:51], v[188:191], v[196:199], v[48:51]
	v_mfma_f32_16x16x32_bf16 v[36:39], v[180:183], v[206:209], v[36:39]
	v_mfma_f32_16x16x32_bf16 v[32:35], v[188:191], v[206:209], v[32:35]
	v_mfma_f32_16x16x32_bf16 v[20:23], v[180:183], v[226:229], v[20:23]
	v_mfma_f32_16x16x32_bf16 v[16:19], v[188:191], v[226:229], v[16:19]
	v_mfma_f32_16x16x32_bf16 v[4:7], v[180:183], v[234:237], v[4:7]
	v_mfma_f32_16x16x32_bf16 v[0:3], v[188:191], v[234:237], v[0:3]
	s_barrier
	s_add_i32 s31, 0, 0x18000
	s_add_i32 s34, 0, 0x1c000
	v_add_u32_e32 v172, s31, v139
	v_add_u32_e32 v188, s34, v139
	ds_read_b128 v[146:149], v172
	ds_read_b128 v[150:153], v172 offset:1024
	ds_read_b128 v[154:157], v172 offset:2048
	ds_read_b128 v[172:175], v172 offset:3072
	ds_read_b128 v[176:179], v188
	ds_read_b128 v[180:183], v188 offset:1024
	ds_read_b128 v[184:187], v188 offset:2048
	ds_read_b128 v[188:191], v188 offset:3072
	s_add_u32 s8, s8, s6
	s_addc_u32 s9, s9, s7
	s_mov_b32 m0, s23
	v_lshl_add_u64 v[246:247], s[8:9], 0, v[136:137]
	ds_read_b128 v[192:195], v200 offset:32768
	ds_read_b128 v[196:199], v200 offset:33792
	ds_read_b128 v[202:205], v200 offset:34816
	ds_read_b128 v[206:209], v200 offset:35840
	ds_read_b128 v[222:225], v200 offset:36864
	ds_read_b128 v[226:229], v200 offset:37888
	ds_read_b128 v[230:233], v200 offset:38912
	ds_read_b128 v[234:237], v200 offset:39936
	global_load_lds_dwordx4 v[246:247], off
	v_lshl_add_u64 v[246:247], s[8:9], 0, v[132:133]
	s_mov_b32 m0, s24
	s_nop 0
	global_load_lds_dwordx4 v[246:247], off
	s_waitcnt vmcnt(8)
	s_waitcnt lgkmcnt(0)
	s_barrier
	s_waitcnt lgkmcnt(0)
	v_mfma_f32_16x16x32_bf16 v[126:129], v[146:149], v[192:195], v[126:129]
	v_mfma_f32_16x16x32_bf16 v[122:125], v[154:157], v[192:195], v[122:125]
	v_mfma_f32_16x16x32_bf16 v[110:113], v[146:149], v[202:205], v[110:113]
	v_mfma_f32_16x16x32_bf16 v[106:109], v[154:157], v[202:205], v[106:109]
	v_mfma_f32_16x16x32_bf16 v[94:97], v[146:149], v[222:225], v[94:97]
	v_mfma_f32_16x16x32_bf16 v[90:93], v[154:157], v[222:225], v[90:93]
	v_mfma_f32_16x16x32_bf16 v[78:81], v[146:149], v[230:233], v[78:81]
	v_mfma_f32_16x16x32_bf16 v[74:77], v[154:157], v[230:233], v[74:77]
	v_mfma_f32_16x16x32_bf16 v[126:129], v[150:153], v[196:199], v[126:129]
	v_mfma_f32_16x16x32_bf16 v[122:125], v[172:175], v[196:199], v[122:125]
	v_mfma_f32_16x16x32_bf16 v[110:113], v[150:153], v[206:209], v[110:113]
	v_mfma_f32_16x16x32_bf16 v[106:109], v[172:175], v[206:209], v[106:109]
	v_mfma_f32_16x16x32_bf16 v[94:97], v[150:153], v[226:229], v[94:97]
	v_mfma_f32_16x16x32_bf16 v[90:93], v[172:175], v[226:229], v[90:93]
	v_mfma_f32_16x16x32_bf16 v[78:81], v[150:153], v[234:237], v[78:81]
	v_mfma_f32_16x16x32_bf16 v[74:77], v[172:175], v[234:237], v[74:77]
	v_mfma_f32_16x16x32_bf16 v[118:121], v[176:179], v[192:195], v[118:121]
	v_mfma_f32_16x16x32_bf16 v[114:117], v[184:187], v[192:195], v[114:117]
	v_mfma_f32_16x16x32_bf16 v[102:105], v[176:179], v[202:205], v[102:105]
	v_mfma_f32_16x16x32_bf16 v[98:101], v[184:187], v[202:205], v[98:101]
	v_mfma_f32_16x16x32_bf16 v[86:89], v[176:179], v[222:225], v[86:89]
	v_mfma_f32_16x16x32_bf16 v[82:85], v[184:187], v[222:225], v[82:85]
	v_mfma_f32_16x16x32_bf16 v[70:73], v[176:179], v[230:233], v[70:73]
	v_mfma_f32_16x16x32_bf16 v[66:69], v[184:187], v[230:233], v[66:69]
	v_mfma_f32_16x16x32_bf16 v[118:121], v[180:183], v[196:199], v[118:121]
	v_mfma_f32_16x16x32_bf16 v[114:117], v[188:191], v[196:199], v[114:117]
	v_mfma_f32_16x16x32_bf16 v[102:105], v[180:183], v[206:209], v[102:105]
	v_mfma_f32_16x16x32_bf16 v[98:101], v[188:191], v[206:209], v[98:101]
	v_mfma_f32_16x16x32_bf16 v[86:89], v[180:183], v[226:229], v[86:89]
	v_mfma_f32_16x16x32_bf16 v[82:85], v[188:191], v[226:229], v[82:85]
	v_mfma_f32_16x16x32_bf16 v[70:73], v[180:183], v[234:237], v[70:73]
	v_mfma_f32_16x16x32_bf16 v[66:69], v[188:191], v[234:237], v[66:69]
	s_barrier
; #define PG8_STAGE(bufoff, gbase, voff) do { _Pragma("unroll") for (int _i = 0; _i < 2; ++_i) \
;         __builtin_amdgcn_global_load_lds((const unsigned*)((const char*)(gbase) + (voff)[_i]), (LAS unsigned*)(lds + (bufoff) + ldsw + _i * 8192), 16, 0, 0); } while (0)
; #define PG8_LDA(dst, b, h) do { _Pragma("unroll") for (int m = 0; m < 4; ++m) _Pragma("unroll") for (int k = 0; k < 2; ++k) dst[m][k] = *(const LAS bf16x8*)(lds + PG8_SA(b, h) + aoff + m * 2048 + k * 1024); } while (0)
; #define PG8_MMA(ai, bj, At, Bt) do { __builtin_amdgcn_s_setprio(1); _Pragma("unroll") for (int m = 0; m < 4; ++m) _Pragma("unroll") for (int n = 0; n < 2; ++n) _Pragma("unroll") for (int k = 0; k < 2; ++k) \
;         acc[ai][bj][m][n] = __builtin_amdgcn_mfma_f32_16x16x32_bf16(Bt[n][k], At[m][k], acc[ai][bj][m][n], 0, 0, 0); __builtin_amdgcn_s_setprio(0); } while (0)
; #define PG8_WAIT_V(n) asm volatile("s_waitcnt vmcnt(" #n ")" ::: "memory")
; #define PG8_WAIT_L(n) asm volatile("s_waitcnt lgkmcnt(" #n ")" ::: "memory")
; #define PG8_BAR __builtin_amdgcn_s_barrier()
; #define PG8_SCHED __builtin_amdgcn_sched_barrier(0)
; template <class Epi>
; __device__ __forceinline__ void gemm_phase(LAS unsigned char* lds, const Gemm g, const StaticOrder& S, const Epi& E) {
;     ...
;             PG8_LDA(At, 1, 1); PG8_STAGE(PG8_SB(1, 0), b3, voffB); PG8_STAGE(PG8_SB(1, 1), b3 + hstepB, voffB); PG8_STAGE(PG8_SA(1, 0), a3, voffA);
;             PG8_WAIT_V(8); PG8_WAIT_L(0); PG8_BAR; PG8_MMA(1, 0, At, B0); PG8_MMA(1, 1, At, B1); PG8_BAR; PG8_SCHED;
;         }
	s_add_i32 s8, s31, s20
	v_lshl_add_u64 v[216:217], v[216:217], 0, s[82:83]
	s_mov_b32 m0, s8
	ds_read_b128 v[192:195], v200 offset:49152
	ds_read_b128 v[196:199], v200 offset:50176
	ds_read_b128 v[202:205], v200 offset:51200
	ds_read_b128 v[206:209], v200 offset:52224
	ds_read_b128 v[222:225], v200 offset:53248
	ds_read_b128 v[226:229], v200 offset:54272
	ds_read_b128 v[230:233], v200 offset:55296
	ds_read_b128 v[234:237], v200 offset:56320
	global_load_lds_dwordx4 v[216:217], off
	v_lshl_add_u64 v[216:217], v[218:219], 0, s[82:83]
	s_add_i32 m0, s8, 0x2000
	s_add_i32 s8, s34, s20
	global_load_lds_dwordx4 v[216:217], off
	v_lshl_add_u64 v[216:217], v[238:239], 0, s[82:83]
	s_mov_b32 m0, s8
	s_nop 0
	global_load_lds_dwordx4 v[216:217], off
	v_lshl_add_u64 v[216:217], v[240:241], 0, s[82:83]
	s_add_i32 m0, s8, 0x2000
	s_nop 0
	global_load_lds_dwordx4 v[216:217], off
	v_lshl_add_u64 v[216:217], v[242:243], 0, s[82:83]
	s_mov_b32 m0, s25
	s_nop 0
	global_load_lds_dwordx4 v[216:217], off
	v_lshl_add_u64 v[216:217], v[244:245], 0, s[82:83]
	s_mov_b32 m0, s26
	s_nop 0
	global_load_lds_dwordx4 v[216:217], off
	s_waitcnt vmcnt(8)
	s_waitcnt lgkmcnt(0)
	s_barrier
	s_waitcnt lgkmcnt(0)
	v_mfma_f32_16x16x32_bf16 v[60:63], v[146:149], v[192:195], v[60:63]
	v_mfma_f32_16x16x32_bf16 v[56:59], v[154:157], v[192:195], v[56:59]
	v_mfma_f32_16x16x32_bf16 v[44:47], v[146:149], v[202:205], v[44:47]
	v_mfma_f32_16x16x32_bf16 v[40:43], v[154:157], v[202:205], v[40:43]
	v_mfma_f32_16x16x32_bf16 v[28:31], v[146:149], v[222:225], v[28:31]
	v_mfma_f32_16x16x32_bf16 v[24:27], v[154:157], v[222:225], v[24:27]
	v_mfma_f32_16x16x32_bf16 v[12:15], v[146:149], v[230:233], v[12:15]
	v_mfma_f32_16x16x32_bf16 v[8:11], v[154:157], v[230:233], v[8:11]
	v_mfma_f32_16x16x32_bf16 v[60:63], v[150:153], v[196:199], v[60:63]
	v_mfma_f32_16x16x32_bf16 v[56:59], v[172:175], v[196:199], v[56:59]
	v_mfma_f32_16x16x32_bf16 v[44:47], v[150:153], v[206:209], v[44:47]
	v_mfma_f32_16x16x32_bf16 v[40:43], v[172:175], v[206:209], v[40:43]
	v_mfma_f32_16x16x32_bf16 v[28:31], v[150:153], v[226:229], v[28:31]
	v_mfma_f32_16x16x32_bf16 v[24:27], v[172:175], v[226:229], v[24:27]
	v_mfma_f32_16x16x32_bf16 v[12:15], v[150:153], v[234:237], v[12:15]
	v_mfma_f32_16x16x32_bf16 v[8:11], v[172:175], v[234:237], v[8:11]
	v_mfma_f32_16x16x32_bf16 v[52:55], v[176:179], v[192:195], v[52:55]
	v_mfma_f32_16x16x32_bf16 v[48:51], v[184:187], v[192:195], v[48:51]
	v_mfma_f32_16x16x32_bf16 v[36:39], v[176:179], v[202:205], v[36:39]
	v_mfma_f32_16x16x32_bf16 v[32:35], v[184:187], v[202:205], v[32:35]
	v_mfma_f32_16x16x32_bf16 v[20:23], v[176:179], v[222:225], v[20:23]
	v_mfma_f32_16x16x32_bf16 v[16:19], v[184:187], v[222:225], v[16:19]
	v_mfma_f32_16x16x32_bf16 v[4:7], v[176:179], v[230:233], v[4:7]
	v_mfma_f32_16x16x32_bf16 v[0:3], v[184:187], v[230:233], v[0:3]
	v_mfma_f32_16x16x32_bf16 v[52:55], v[180:183], v[196:199], v[52:55]
	v_mfma_f32_16x16x32_bf16 v[48:51], v[188:191], v[196:199], v[48:51]
	v_mfma_f32_16x16x32_bf16 v[36:39], v[180:183], v[206:209], v[36:39]
	v_mfma_f32_16x16x32_bf16 v[32:35], v[188:191], v[206:209], v[32:35]
	v_mfma_f32_16x16x32_bf16 v[20:23], v[180:183], v[226:229], v[20:23]
	v_mfma_f32_16x16x32_bf16 v[16:19], v[188:191], v[226:229], v[16:19]
	v_mfma_f32_16x16x32_bf16 v[4:7], v[180:183], v[234:237], v[4:7]
	v_mfma_f32_16x16x32_bf16 v[0:3], v[188:191], v[234:237], v[0:3]
	s_add_u32 s11, s11, 0x100
	s_addc_u32 s29, s29, 0
	s_add_u32 s0, s0, 0x100
	s_addc_u32 s1, s1, 0
	s_cmp_ge_i32 s30, s27
	s_mov_b32 s8, s30
	s_barrier
	s_cbranch_scc0 .LBB0_3377
	s_movk_i32 s34, 0xff80
	s_mov_b32 s35, -1

; #define PG8_STAGE(bufoff, gbase, voff) do { _Pragma("unroll") for (int _i = 0; _i < 2; ++_i) \
;         __builtin_amdgcn_global_load_lds((const unsigned*)((const char*)(gbase) + (voff)[_i]), (LAS unsigned*)(lds + (bufoff) + ldsw + _i * 8192), 16, 0, 0); } while (0)
; #define PG8_LDA(dst, b, h) do { _Pragma("unroll") for (int m = 0; m < 4; ++m) _Pragma("unroll") for (int k = 0; k < 2; ++k) dst[m][k] = *(const LAS bf16x8*)(lds + PG8_SA(b, h) + aoff + m * 2048 + k * 1024); } while (0)
; #define PG8_LDB(dst, b, h) do { _Pragma("unroll") for (int n = 0; n < 2; ++n) _Pragma("unroll") for (int k = 0; k < 2; ++k) dst[n][k] = *(const LAS bf16x8*)(lds + PG8_SB(b, h) + boff + n * 2048 + k * 1024); } while (0)
; #define PG8_MMA(ai, bj, At, Bt) do { __builtin_amdgcn_s_setprio(1); _Pragma("unroll") for (int m = 0; m < 4; ++m) _Pragma("unroll") for (int n = 0; n < 2; ++n) _Pragma("unroll") for (int k = 0; k < 2; ++k) \
;         acc[ai][bj][m][n] = __builtin_amdgcn_mfma_f32_16x16x32_bf16(Bt[n][k], At[m][k], acc[ai][bj][m][n], 0, 0, 0); __builtin_amdgcn_s_setprio(0); } while (0)
; #define PG8_WAIT_V(n) asm volatile("s_waitcnt vmcnt(" #n ")" ::: "memory")
; #define PG8_WAIT_L(n) asm volatile("s_waitcnt lgkmcnt(" #n ")" ::: "memory")
; #define PG8_BAR __builtin_amdgcn_s_barrier()
; #define PG8_SCHED __builtin_amdgcn_sched_barrier(0)
; template <class Epi>
; __device__ __forceinline__ void gemm_phase(LAS unsigned char* lds, const Gemm g, const StaticOrder& S, const Epi& E) {
;     ...
;         for (int t = 0; t < nt; t += 2) {
;             const bool last = (t == nt - 2);
;             const char* a1 = cA + (size_t)(t + 1) * kstep;
;             const char* a2 = last ? nA : cA + (size_t)(t + 2) * kstep; const char* b2 = last ? nB : cB + (size_t)(t + 2) * kstep;
;             const char* a3 = a2 + kstep; const char* b3 = b2 + kstep;
;             PG8_LDB(B0, 0, 0); PG8_LDB(B1, 0, 1); PG8_SCHED; PG8_LDA(At, 0, 0); PG8_STAGE(PG8_SA(1, 1), a1 + hstepA, voffA);
;             PG8_WAIT_V(8); PG8_WAIT_L(0); PG8_BAR; PG8_MMA(0, 0, At, B0); PG8_MMA(0, 1, At, B1); PG8_BAR; PG8_SCHED;
;             PG8_LDA(At, 0, 1); PG8_STAGE(PG8_SB(0, 0), b2, voffB); PG8_STAGE(PG8_SB(0, 1), b2 + hstepB, voffB); PG8_STAGE(PG8_SA(0, 0), a2, voffA);
;             PG8_WAIT_V(8); PG8_WAIT_L(0); PG8_BAR; PG8_MMA(1, 0, At, B0); PG8_MMA(1, 1, At, B1); PG8_BAR; PG8_SCHED;
.LBB0_3848:
	s_add_i32 s30, s10, 2
	s_add_u32 s31, s8, 0x80
	s_addc_u32 s11, s9, 0
	s_add_i32 s58, 0, 0x10000
	s_cmp_eq_u32 s62, s10
	s_cselect_b32 s11, s1, s11
	s_cselect_b32 s10, s0, s31
	v_add_u32_e32 v145, s58, v154
	s_cselect_b32 s35, s7, s29
	s_cselect_b32 s34, s6, s28
	s_add_i32 s31, 0, 0x14000
	ds_read_b128 v[146:149], v145
	ds_read_b128 v[150:153], v145 offset:1024
	ds_read_b128 v[174:177], v145 offset:2048
	ds_read_b128 v[178:181], v145 offset:3072
	v_add_u32_e32 v145, s31, v154
	ds_read_b128 v[182:185], v145
	ds_read_b128 v[186:189], v145 offset:1024
	ds_read_b128 v[190:193], v145 offset:2048
	ds_read_b128 v[194:197], v145 offset:3072
	v_lshl_add_u64 v[216:217], s[8:9], 0, v[142:143]
	s_add_i32 m0, s21, 0xc000
	ds_read_b128 v[198:201], v157
	ds_read_b128 v[202:205], v157 offset:1024
	ds_read_b128 v[206:209], v157 offset:2048
	ds_read_b128 v[222:225], v157 offset:3072
	ds_read_b128 v[226:229], v157 offset:4096
	ds_read_b128 v[230:233], v157 offset:5120
	ds_read_b128 v[234:237], v157 offset:6144
	ds_read_b128 v[238:241], v157 offset:7168
	global_load_lds_dwordx4 v[216:217], off
	v_lshl_add_u64 v[216:217], s[8:9], 0, v[140:141]
	s_add_i32 m0, s21, 0xe000
	s_nop 0
	global_load_lds_dwordx4 v[216:217], off
	s_waitcnt vmcnt(8)
	s_waitcnt lgkmcnt(0)
	s_barrier
	s_waitcnt lgkmcnt(0)
	v_mfma_f32_16x16x32_bf16 v[126:129], v[146:149], v[198:201], v[126:129]
	v_mfma_f32_16x16x32_bf16 v[118:121], v[174:177], v[198:201], v[118:121]
	v_mfma_f32_16x16x32_bf16 v[110:113], v[146:149], v[206:209], v[110:113]
	v_mfma_f32_16x16x32_bf16 v[102:105], v[174:177], v[206:209], v[102:105]
	v_mfma_f32_16x16x32_bf16 v[94:97], v[146:149], v[226:229], v[94:97]
	v_mfma_f32_16x16x32_bf16 v[86:89], v[174:177], v[226:229], v[86:89]
	v_mfma_f32_16x16x32_bf16 v[78:81], v[146:149], v[234:237], v[78:81]
	v_mfma_f32_16x16x32_bf16 v[70:73], v[174:177], v[234:237], v[70:73]
	v_mfma_f32_16x16x32_bf16 v[126:129], v[150:153], v[202:205], v[126:129]
	v_mfma_f32_16x16x32_bf16 v[118:121], v[178:181], v[202:205], v[118:121]
	v_mfma_f32_16x16x32_bf16 v[110:113], v[150:153], v[222:225], v[110:113]
	v_mfma_f32_16x16x32_bf16 v[102:105], v[178:181], v[222:225], v[102:105]
	v_mfma_f32_16x16x32_bf16 v[94:97], v[150:153], v[230:233], v[94:97]
	v_mfma_f32_16x16x32_bf16 v[86:89], v[178:181], v[230:233], v[86:89]
	v_mfma_f32_16x16x32_bf16 v[78:81], v[150:153], v[238:241], v[78:81]
	v_mfma_f32_16x16x32_bf16 v[70:73], v[178:181], v[238:241], v[70:73]
	v_mfma_f32_16x16x32_bf16 v[122:125], v[182:185], v[198:201], v[122:125]
	v_mfma_f32_16x16x32_bf16 v[114:117], v[190:193], v[198:201], v[114:117]
	v_mfma_f32_16x16x32_bf16 v[106:109], v[182:185], v[206:209], v[106:109]
	v_mfma_f32_16x16x32_bf16 v[98:101], v[190:193], v[206:209], v[98:101]
	v_mfma_f32_16x16x32_bf16 v[90:93], v[182:185], v[226:229], v[90:93]
	v_mfma_f32_16x16x32_bf16 v[82:85], v[190:193], v[226:229], v[82:85]
	v_mfma_f32_16x16x32_bf16 v[74:77], v[182:185], v[234:237], v[74:77]
	v_mfma_f32_16x16x32_bf16 v[66:69], v[190:193], v[234:237], v[66:69]
	v_mfma_f32_16x16x32_bf16 v[122:125], v[186:189], v[202:205], v[122:125]
	v_mfma_f32_16x16x32_bf16 v[114:117], v[194:197], v[202:205], v[114:117]
	v_mfma_f32_16x16x32_bf16 v[106:109], v[186:189], v[222:225], v[106:109]
	v_mfma_f32_16x16x32_bf16 v[98:101], v[194:197], v[222:225], v[98:101]
	v_mfma_f32_16x16x32_bf16 v[90:93], v[186:189], v[230:233], v[90:93]
	v_mfma_f32_16x16x32_bf16 v[82:85], v[194:197], v[230:233], v[82:85]
	v_mfma_f32_16x16x32_bf16 v[74:77], v[186:189], v[238:241], v[74:77]
	v_mfma_f32_16x16x32_bf16 v[66:69], v[194:197], v[238:241], v[66:69]
	s_barrier
	s_add_i32 s58, s58, s20
	v_lshl_add_u64 v[216:217], s[34:35], 0, v[134:135]
	s_mov_b32 m0, s58
	ds_read_b128 v[198:201], v157 offset:16384
	ds_read_b128 v[202:205], v157 offset:17408
	ds_read_b128 v[206:209], v157 offset:18432
	ds_read_b128 v[222:225], v157 offset:19456
	ds_read_b128 v[226:229], v157 offset:20480
	ds_read_b128 v[230:233], v157 offset:21504
	ds_read_b128 v[234:237], v157 offset:22528
	ds_read_b128 v[238:241], v157 offset:23552
	global_load_lds_dwordx4 v[216:217], off
	s_add_i32 m0, s58, 0x2000
	v_lshl_add_u64 v[218:219], s[34:35], 0, v[130:131]
	s_add_u32 s34, s34, s42
	s_addc_u32 s35, s35, s43
	s_add_i32 s31, s31, s20
	global_load_lds_dwordx4 v[218:219], off
	v_lshl_add_u64 v[242:243], s[34:35], 0, v[134:135]
	s_mov_b32 m0, s31
	v_lshl_add_u64 v[244:245], s[34:35], 0, v[130:131]
	global_load_lds_dwordx4 v[242:243], off
	s_add_i32 m0, s31, 0x2000
	v_lshl_add_u64 v[246:247], s[10:11], 0, v[136:137]
	global_load_lds_dwordx4 v[244:245], off
	s_mov_b32 m0, s21
	v_lshl_add_u64 v[248:249], s[10:11], 0, v[132:133]
	global_load_lds_dwordx4 v[246:247], off
	s_mov_b32 m0, s22
	s_nop 0
	global_load_lds_dwordx4 v[248:249], off
	s_waitcnt vmcnt(8)
	s_waitcnt lgkmcnt(0)
	s_barrier
; #define PG8_STAGE(bufoff, gbase, voff) do { _Pragma("unroll") for (int _i = 0; _i < 2; ++_i) \
;         __builtin_amdgcn_global_load_lds((const unsigned*)((const char*)(gbase) + (voff)[_i]), (LAS unsigned*)(lds + (bufoff) + ldsw + _i * 8192), 16, 0, 0); } while (0)
; #define PG8_LDA(dst, b, h) do { _Pragma("unroll") for (int m = 0; m < 4; ++m) _Pragma("unroll") for (int k = 0; k < 2; ++k) dst[m][k] = *(const LAS bf16x8*)(lds + PG8_SA(b, h) + aoff + m * 2048 + k * 1024); } while (0)
; #define PG8_LDB(dst, b, h) do { _Pragma("unroll") for (int n = 0; n < 2; ++n) _Pragma("unroll") for (int k = 0; k < 2; ++k) dst[n][k] = *(const LAS bf16x8*)(lds + PG8_SB(b, h) + boff + n * 2048 + k * 1024); } while (0)
; #define PG8_MMA(ai, bj, At, Bt) do { __builtin_amdgcn_s_setprio(1); _Pragma("unroll") for (int m = 0; m < 4; ++m) _Pragma("unroll") for (int n = 0; n < 2; ++n) _Pragma("unroll") for (int k = 0; k < 2; ++k) \
;         acc[ai][bj][m][n] = __builtin_amdgcn_mfma_f32_16x16x32_bf16(Bt[n][k], At[m][k], acc[ai][bj][m][n], 0, 0, 0); __builtin_amdgcn_s_setprio(0); } while (0)
; #define PG8_WAIT_V(n) asm volatile("s_waitcnt vmcnt(" #n ")" ::: "memory")
; #define PG8_WAIT_L(n) asm volatile("s_waitcnt lgkmcnt(" #n ")" ::: "memory")
; #define PG8_BAR __builtin_amdgcn_s_barrier()
; #define PG8_SCHED __builtin_amdgcn_sched_barrier(0)
; template <class Epi>
; __device__ __forceinline__ void gemm_phase(LAS unsigned char* lds, const Gemm g, const StaticOrder& S, const Epi& E) {
;     ...
;             PG8_WAIT_V(8); PG8_WAIT_L(0); PG8_BAR; PG8_MMA(1, 0, At, B0); PG8_MMA(1, 1, At, B1); PG8_BAR; PG8_SCHED;
;             PG8_LDB(B0, 1, 0); PG8_LDB(B1, 1, 1); PG8_SCHED; PG8_LDA(At, 1, 0); PG8_STAGE(PG8_SA(0, 1), a2 + hstepA, voffA);
;             PG8_WAIT_V(8); PG8_WAIT_L(0); PG8_BAR; PG8_MMA(0, 0, At, B0); PG8_MMA(0, 1, At, B1); PG8_BAR; PG8_SCHED;
	s_waitcnt lgkmcnt(0)
	v_mfma_f32_16x16x32_bf16 v[60:63], v[146:149], v[198:201], v[60:63]
	v_mfma_f32_16x16x32_bf16 v[52:55], v[174:177], v[198:201], v[52:55]
	v_mfma_f32_16x16x32_bf16 v[44:47], v[146:149], v[206:209], v[44:47]
	v_mfma_f32_16x16x32_bf16 v[36:39], v[174:177], v[206:209], v[36:39]
	v_mfma_f32_16x16x32_bf16 v[28:31], v[146:149], v[226:229], v[28:31]
	v_mfma_f32_16x16x32_bf16 v[20:23], v[174:177], v[226:229], v[20:23]
	v_mfma_f32_16x16x32_bf16 v[12:15], v[146:149], v[234:237], v[12:15]
	v_mfma_f32_16x16x32_bf16 v[4:7], v[174:177], v[234:237], v[4:7]
	v_mfma_f32_16x16x32_bf16 v[60:63], v[150:153], v[202:205], v[60:63]
	v_mfma_f32_16x16x32_bf16 v[52:55], v[178:181], v[202:205], v[52:55]
	v_mfma_f32_16x16x32_bf16 v[44:47], v[150:153], v[222:225], v[44:47]
	v_mfma_f32_16x16x32_bf16 v[36:39], v[178:181], v[222:225], v[36:39]
	v_mfma_f32_16x16x32_bf16 v[28:31], v[150:153], v[230:233], v[28:31]
	v_mfma_f32_16x16x32_bf16 v[20:23], v[178:181], v[230:233], v[20:23]
	v_mfma_f32_16x16x32_bf16 v[12:15], v[150:153], v[238:241], v[12:15]
	v_mfma_f32_16x16x32_bf16 v[4:7], v[178:181], v[238:241], v[4:7]
	v_mfma_f32_16x16x32_bf16 v[56:59], v[182:185], v[198:201], v[56:59]
	v_mfma_f32_16x16x32_bf16 v[48:51], v[190:193], v[198:201], v[48:51]
	v_mfma_f32_16x16x32_bf16 v[40:43], v[182:185], v[206:209], v[40:43]
	v_mfma_f32_16x16x32_bf16 v[32:35], v[190:193], v[206:209], v[32:35]
	v_mfma_f32_16x16x32_bf16 v[24:27], v[182:185], v[226:229], v[24:27]
	v_mfma_f32_16x16x32_bf16 v[16:19], v[190:193], v[226:229], v[16:19]
	v_mfma_f32_16x16x32_bf16 v[8:11], v[182:185], v[234:237], v[8:11]
	v_mfma_f32_16x16x32_bf16 v[0:3], v[190:193], v[234:237], v[0:3]
	v_mfma_f32_16x16x32_bf16 v[56:59], v[186:189], v[202:205], v[56:59]
	v_mfma_f32_16x16x32_bf16 v[48:51], v[194:197], v[202:205], v[48:51]
	v_mfma_f32_16x16x32_bf16 v[40:43], v[186:189], v[222:225], v[40:43]
	v_mfma_f32_16x16x32_bf16 v[32:35], v[194:197], v[222:225], v[32:35]
	v_mfma_f32_16x16x32_bf16 v[24:27], v[186:189], v[230:233], v[24:27]
	v_mfma_f32_16x16x32_bf16 v[16:19], v[194:197], v[230:233], v[16:19]
	v_mfma_f32_16x16x32_bf16 v[8:11], v[186:189], v[238:241], v[8:11]
	v_mfma_f32_16x16x32_bf16 v[0:3], v[194:197], v[238:241], v[0:3]
	s_barrier
	s_add_i32 s31, 0, 0x18000
	v_add_u32_e32 v145, s31, v154
	s_add_i32 s34, 0, 0x1c000
	ds_read_b128 v[146:149], v145
	ds_read_b128 v[150:153], v145 offset:1024
	ds_read_b128 v[174:177], v145 offset:2048
	ds_read_b128 v[178:181], v145 offset:3072
	v_add_u32_e32 v145, s34, v154
	ds_read_b128 v[182:185], v145
	ds_read_b128 v[186:189], v145 offset:1024
	ds_read_b128 v[190:193], v145 offset:2048
	ds_read_b128 v[194:197], v145 offset:3072
	s_add_u32 s10, s10, s4
	s_addc_u32 s11, s11, s5
	s_mov_b32 m0, s23
	v_lshl_add_u64 v[250:251], s[10:11], 0, v[136:137]
	ds_read_b128 v[198:201], v157 offset:32768
	ds_read_b128 v[202:205], v157 offset:33792
	ds_read_b128 v[206:209], v157 offset:34816
	ds_read_b128 v[222:225], v157 offset:35840
	ds_read_b128 v[226:229], v157 offset:36864
	ds_read_b128 v[230:233], v157 offset:37888
	ds_read_b128 v[234:237], v157 offset:38912
	ds_read_b128 v[238:241], v157 offset:39936
	global_load_lds_dwordx4 v[250:251], off
	v_lshl_add_u64 v[250:251], s[10:11], 0, v[132:133]
	s_mov_b32 m0, s24
	s_nop 0
	global_load_lds_dwordx4 v[250:251], off
	s_waitcnt vmcnt(8)
	s_waitcnt lgkmcnt(0)
	s_barrier
	s_waitcnt lgkmcnt(0)
	v_mfma_f32_16x16x32_bf16 v[126:129], v[146:149], v[198:201], v[126:129]
	v_mfma_f32_16x16x32_bf16 v[118:121], v[174:177], v[198:201], v[118:121]
	v_mfma_f32_16x16x32_bf16 v[110:113], v[146:149], v[206:209], v[110:113]
	v_mfma_f32_16x16x32_bf16 v[102:105], v[174:177], v[206:209], v[102:105]
	v_mfma_f32_16x16x32_bf16 v[94:97], v[146:149], v[226:229], v[94:97]
	v_mfma_f32_16x16x32_bf16 v[86:89], v[174:177], v[226:229], v[86:89]
	v_mfma_f32_16x16x32_bf16 v[78:81], v[146:149], v[234:237], v[78:81]
	v_mfma_f32_16x16x32_bf16 v[70:73], v[174:177], v[234:237], v[70:73]
	v_mfma_f32_16x16x32_bf16 v[126:129], v[150:153], v[202:205], v[126:129]
	v_mfma_f32_16x16x32_bf16 v[118:121], v[178:181], v[202:205], v[118:121]
	v_mfma_f32_16x16x32_bf16 v[110:113], v[150:153], v[222:225], v[110:113]
	v_mfma_f32_16x16x32_bf16 v[102:105], v[178:181], v[222:225], v[102:105]
	v_mfma_f32_16x16x32_bf16 v[94:97], v[150:153], v[230:233], v[94:97]
	v_mfma_f32_16x16x32_bf16 v[86:89], v[178:181], v[230:233], v[86:89]
	v_mfma_f32_16x16x32_bf16 v[78:81], v[150:153], v[238:241], v[78:81]
	v_mfma_f32_16x16x32_bf16 v[70:73], v[178:181], v[238:241], v[70:73]
	v_mfma_f32_16x16x32_bf16 v[122:125], v[182:185], v[198:201], v[122:125]
	v_mfma_f32_16x16x32_bf16 v[114:117], v[190:193], v[198:201], v[114:117]
	v_mfma_f32_16x16x32_bf16 v[106:109], v[182:185], v[206:209], v[106:109]
	v_mfma_f32_16x16x32_bf16 v[98:101], v[190:193], v[206:209], v[98:101]
	v_mfma_f32_16x16x32_bf16 v[90:93], v[182:185], v[226:229], v[90:93]
	v_mfma_f32_16x16x32_bf16 v[82:85], v[190:193], v[226:229], v[82:85]
	v_mfma_f32_16x16x32_bf16 v[74:77], v[182:185], v[234:237], v[74:77]
	v_mfma_f32_16x16x32_bf16 v[66:69], v[190:193], v[234:237], v[66:69]
	v_mfma_f32_16x16x32_bf16 v[122:125], v[186:189], v[202:205], v[122:125]
	v_mfma_f32_16x16x32_bf16 v[114:117], v[194:197], v[202:205], v[114:117]
	v_mfma_f32_16x16x32_bf16 v[106:109], v[186:189], v[222:225], v[106:109]
	v_mfma_f32_16x16x32_bf16 v[98:101], v[194:197], v[222:225], v[98:101]
	v_mfma_f32_16x16x32_bf16 v[90:93], v[186:189], v[230:233], v[90:93]
	v_mfma_f32_16x16x32_bf16 v[82:85], v[194:197], v[230:233], v[82:85]
	v_mfma_f32_16x16x32_bf16 v[74:77], v[186:189], v[238:241], v[74:77]
	v_mfma_f32_16x16x32_bf16 v[66:69], v[194:197], v[238:241], v[66:69]
	s_barrier
; #define PG8_STAGE(bufoff, gbase, voff) do { _Pragma("unroll") for (int _i = 0; _i < 2; ++_i) \
;         __builtin_amdgcn_global_load_lds((const unsigned*)((const char*)(gbase) + (voff)[_i]), (LAS unsigned*)(lds + (bufoff) + ldsw + _i * 8192), 16, 0, 0); } while (0)
; #define PG8_LDA(dst, b, h) do { _Pragma("unroll") for (int m = 0; m < 4; ++m) _Pragma("unroll") for (int k = 0; k < 2; ++k) dst[m][k] = *(const LAS bf16x8*)(lds + PG8_SA(b, h) + aoff + m * 2048 + k * 1024); } while (0)
; #define PG8_MMA(ai, bj, At, Bt) do { __builtin_amdgcn_s_setprio(1); _Pragma("unroll") for (int m = 0; m < 4; ++m) _Pragma("unroll") for (int n = 0; n < 2; ++n) _Pragma("unroll") for (int k = 0; k < 2; ++k) \
;         acc[ai][bj][m][n] = __builtin_amdgcn_mfma_f32_16x16x32_bf16(Bt[n][k], At[m][k], acc[ai][bj][m][n], 0, 0, 0); __builtin_amdgcn_s_setprio(0); } while (0)
; #define PG8_WAIT_V(n) asm volatile("s_waitcnt vmcnt(" #n ")" ::: "memory")
; #define PG8_WAIT_L(n) asm volatile("s_waitcnt lgkmcnt(" #n ")" ::: "memory")
; #define PG8_BAR __builtin_amdgcn_s_barrier()
; #define PG8_SCHED __builtin_amdgcn_sched_barrier(0)
; template <class Epi>
; __device__ __forceinline__ void gemm_phase(LAS unsigned char* lds, const Gemm g, const StaticOrder& S, const Epi& E) {
;     ...
;             PG8_LDA(At, 1, 1); PG8_STAGE(PG8_SB(1, 0), b3, voffB); PG8_STAGE(PG8_SB(1, 1), b3 + hstepB, voffB); PG8_STAGE(PG8_SA(1, 0), a3, voffA);
;             PG8_WAIT_V(8); PG8_WAIT_L(0); PG8_BAR; PG8_MMA(1, 0, At, B0); PG8_MMA(1, 1, At, B1); PG8_BAR; PG8_SCHED;
;         }
	s_add_i32 s10, s31, s20
	v_lshl_add_u64 v[216:217], v[216:217], 0, s[82:83]
	s_mov_b32 m0, s10
	ds_read_b128 v[198:201], v157 offset:49152
	ds_read_b128 v[202:205], v157 offset:50176
	ds_read_b128 v[206:209], v157 offset:51200
	ds_read_b128 v[222:225], v157 offset:52224
	ds_read_b128 v[226:229], v157 offset:53248
	ds_read_b128 v[230:233], v157 offset:54272
	ds_read_b128 v[234:237], v157 offset:55296
	ds_read_b128 v[238:241], v157 offset:56320
	global_load_lds_dwordx4 v[216:217], off
	v_lshl_add_u64 v[216:217], v[218:219], 0, s[82:83]
	s_add_i32 m0, s10, 0x2000
	s_add_i32 s10, s34, s20
	global_load_lds_dwordx4 v[216:217], off
	v_lshl_add_u64 v[216:217], v[242:243], 0, s[82:83]
	s_mov_b32 m0, s10
	s_nop 0
	global_load_lds_dwordx4 v[216:217], off
	v_lshl_add_u64 v[216:217], v[244:245], 0, s[82:83]
	s_add_i32 m0, s10, 0x2000
	s_nop 0
	global_load_lds_dwordx4 v[216:217], off
	v_lshl_add_u64 v[216:217], v[246:247], 0, s[82:83]
	s_mov_b32 m0, s25
	s_nop 0
	global_load_lds_dwordx4 v[216:217], off
	v_lshl_add_u64 v[216:217], v[248:249], 0, s[82:83]
	s_mov_b32 m0, s60
	s_nop 0
	global_load_lds_dwordx4 v[216:217], off
	s_waitcnt vmcnt(8)
	s_waitcnt lgkmcnt(0)
	s_barrier
	s_waitcnt lgkmcnt(0)
	v_mfma_f32_16x16x32_bf16 v[60:63], v[146:149], v[198:201], v[60:63]
	v_mfma_f32_16x16x32_bf16 v[52:55], v[174:177], v[198:201], v[52:55]
	v_mfma_f32_16x16x32_bf16 v[44:47], v[146:149], v[206:209], v[44:47]
	v_mfma_f32_16x16x32_bf16 v[36:39], v[174:177], v[206:209], v[36:39]
	v_mfma_f32_16x16x32_bf16 v[28:31], v[146:149], v[226:229], v[28:31]
	v_mfma_f32_16x16x32_bf16 v[20:23], v[174:177], v[226:229], v[20:23]
	v_mfma_f32_16x16x32_bf16 v[12:15], v[146:149], v[234:237], v[12:15]
	v_mfma_f32_16x16x32_bf16 v[4:7], v[174:177], v[234:237], v[4:7]
	v_mfma_f32_16x16x32_bf16 v[60:63], v[150:153], v[202:205], v[60:63]
	v_mfma_f32_16x16x32_bf16 v[52:55], v[178:181], v[202:205], v[52:55]
	v_mfma_f32_16x16x32_bf16 v[44:47], v[150:153], v[222:225], v[44:47]
	v_mfma_f32_16x16x32_bf16 v[36:39], v[178:181], v[222:225], v[36:39]
	v_mfma_f32_16x16x32_bf16 v[28:31], v[150:153], v[230:233], v[28:31]
	v_mfma_f32_16x16x32_bf16 v[20:23], v[178:181], v[230:233], v[20:23]
	v_mfma_f32_16x16x32_bf16 v[12:15], v[150:153], v[238:241], v[12:15]
	v_mfma_f32_16x16x32_bf16 v[4:7], v[178:181], v[238:241], v[4:7]
	v_mfma_f32_16x16x32_bf16 v[56:59], v[182:185], v[198:201], v[56:59]
	v_mfma_f32_16x16x32_bf16 v[48:51], v[190:193], v[198:201], v[48:51]
	v_mfma_f32_16x16x32_bf16 v[40:43], v[182:185], v[206:209], v[40:43]
	v_mfma_f32_16x16x32_bf16 v[32:35], v[190:193], v[206:209], v[32:35]
	v_mfma_f32_16x16x32_bf16 v[24:27], v[182:185], v[226:229], v[24:27]
	v_mfma_f32_16x16x32_bf16 v[16:19], v[190:193], v[226:229], v[16:19]
	v_mfma_f32_16x16x32_bf16 v[8:11], v[182:185], v[234:237], v[8:11]
	v_mfma_f32_16x16x32_bf16 v[0:3], v[190:193], v[234:237], v[0:3]
	v_mfma_f32_16x16x32_bf16 v[56:59], v[186:189], v[202:205], v[56:59]
	v_mfma_f32_16x16x32_bf16 v[48:51], v[194:197], v[202:205], v[48:51]
	v_mfma_f32_16x16x32_bf16 v[40:43], v[186:189], v[222:225], v[40:43]
	v_mfma_f32_16x16x32_bf16 v[32:35], v[194:197], v[222:225], v[32:35]
	v_mfma_f32_16x16x32_bf16 v[24:27], v[186:189], v[230:233], v[24:27]
	v_mfma_f32_16x16x32_bf16 v[16:19], v[194:197], v[230:233], v[16:19]
	v_mfma_f32_16x16x32_bf16 v[8:11], v[186:189], v[238:241], v[8:11]
	v_mfma_f32_16x16x32_bf16 v[0:3], v[194:197], v[238:241], v[0:3]
	s_add_u32 s28, s28, 0x100
	s_addc_u32 s29, s29, 0
	s_add_u32 s8, s8, 0x100
	s_addc_u32 s9, s9, 0
	s_cmp_ge_i32 s30, s61
	s_mov_b32 s10, s30
	s_barrier
	s_cbranch_scc0 .LBB0_3848

; #define PG8_STAGE(bufoff, gbase, voff) do { _Pragma("unroll") for (int _i = 0; _i < 2; ++_i) \
;         __builtin_amdgcn_global_load_lds((const unsigned*)((const char*)(gbase) + (voff)[_i]), (LAS unsigned*)(lds + (bufoff) + ldsw + _i * 8192), 16, 0, 0); } while (0)
; #define PG8_LDA(dst, b, h) do { _Pragma("unroll") for (int m = 0; m < 4; ++m) _Pragma("unroll") for (int k = 0; k < 2; ++k) dst[m][k] = *(const LAS bf16x8*)(lds + PG8_SA(b, h) + aoff + m * 2048 + k * 1024); } while (0)
; #define PG8_LDB(dst, b, h) do { _Pragma("unroll") for (int n = 0; n < 2; ++n) _Pragma("unroll") for (int k = 0; k < 2; ++k) dst[n][k] = *(const LAS bf16x8*)(lds + PG8_SB(b, h) + boff + n * 2048 + k * 1024); } while (0)
; #define PG8_MMA(ai, bj, At, Bt) do { __builtin_amdgcn_s_setprio(1); _Pragma("unroll") for (int m = 0; m < 4; ++m) _Pragma("unroll") for (int n = 0; n < 2; ++n) _Pragma("unroll") for (int k = 0; k < 2; ++k) \
;         acc[ai][bj][m][n] = __builtin_amdgcn_mfma_f32_16x16x32_bf16(Bt[n][k], At[m][k], acc[ai][bj][m][n], 0, 0, 0); __builtin_amdgcn_s_setprio(0); } while (0)
; #define PG8_WAIT_V(n) asm volatile("s_waitcnt vmcnt(" #n ")" ::: "memory")
; #define PG8_WAIT_L(n) asm volatile("s_waitcnt lgkmcnt(" #n ")" ::: "memory")
; #define PG8_BAR __builtin_amdgcn_s_barrier()
; #define PG8_SCHED __builtin_amdgcn_sched_barrier(0)
; template <class Epi>
; __device__ __forceinline__ void gemm_phase(LAS unsigned char* lds, const Gemm g, const StaticOrder& S, const Epi& E) {
;     ...
;         for (int t = 0; t < nt; t += 2) {
;             const bool last = (t == nt - 2);
;             const char* a1 = cA + (size_t)(t + 1) * kstep;
;             const char* a2 = last ? nA : cA + (size_t)(t + 2) * kstep; const char* b2 = last ? nB : cB + (size_t)(t + 2) * kstep;
;             const char* a3 = a2 + kstep; const char* b3 = b2 + kstep;
;             PG8_LDB(B0, 0, 0); PG8_LDB(B1, 0, 1); PG8_SCHED; PG8_LDA(At, 0, 0); PG8_STAGE(PG8_SA(1, 1), a1 + hstepA, voffA);
;             PG8_WAIT_V(8); PG8_WAIT_L(0); PG8_BAR; PG8_MMA(0, 0, At, B0); PG8_MMA(0, 1, At, B1); PG8_BAR; PG8_SCHED;
;             PG8_LDA(At, 0, 1); PG8_STAGE(PG8_SB(0, 0), b2, voffB); PG8_STAGE(PG8_SB(0, 1), b2 + hstepB, voffB); PG8_STAGE(PG8_SA(0, 0), a2, voffA);
;             PG8_WAIT_V(8); PG8_WAIT_L(0); PG8_BAR; PG8_MMA(1, 0, At, B0); PG8_MMA(1, 1, At, B1); PG8_BAR; PG8_SCHED;
.LBB0_3925:
	s_add_i32 s29, s10, 2
	s_add_u32 s30, s38, 0x80
	s_addc_u32 s11, s39, 0
	s_add_i32 s34, 0, 0x10000
	s_cmp_eq_u32 s96, s10
	s_cselect_b32 s11, s1, s11
	s_cselect_b32 s10, s0, s30
	s_cselect_b32 s31, s69, s28
	s_cselect_b32 s30, s68, s27
	s_add_i32 s35, 0, 0x14000
	v_add_u32_e32 v142, s34, v181
	v_add_u32_e32 v186, s35, v181
	ds_read_b128 v[130:133], v142
	ds_read_b128 v[134:137], v142 offset:1024
	ds_read_b128 v[138:141], v142 offset:2048
	ds_read_b128 v[142:145], v142 offset:3072
	ds_read_b128 v[146:149], v186
	ds_read_b128 v[150:153], v186 offset:1024
	ds_read_b128 v[154:157], v186 offset:2048
	ds_read_b128 v[186:189], v186 offset:3072
	v_lshl_add_u64 v[202:203], s[38:39], 0, v[184:185]
	s_add_i32 m0, s21, 0xc000
	ds_read_b128 v[190:193], v204
	ds_read_b128 v[194:197], v204 offset:1024
	ds_read_b128 v[198:201], v204 offset:2048
	ds_read_b128 v[206:209], v204 offset:3072
	ds_read_b128 v[222:225], v204 offset:4096
	ds_read_b128 v[226:229], v204 offset:5120
	ds_read_b128 v[230:233], v204 offset:6144
	ds_read_b128 v[234:237], v204 offset:7168
	global_load_lds_dwordx4 v[202:203], off
	v_lshl_add_u64 v[202:203], s[38:39], 0, v[182:183]
	s_add_i32 m0, s21, 0xe000
	s_nop 0
	global_load_lds_dwordx4 v[202:203], off
	s_waitcnt vmcnt(8)
	s_waitcnt lgkmcnt(0)
	s_barrier
	s_waitcnt lgkmcnt(0)
	v_mfma_f32_16x16x32_bf16 v[122:125], v[130:133], v[190:193], v[122:125]
	v_mfma_f32_16x16x32_bf16 v[126:129], v[138:141], v[190:193], v[126:129]
	v_mfma_f32_16x16x32_bf16 v[110:113], v[130:133], v[198:201], v[110:113]
	v_mfma_f32_16x16x32_bf16 v[106:109], v[138:141], v[198:201], v[106:109]
	v_mfma_f32_16x16x32_bf16 v[94:97], v[130:133], v[222:225], v[94:97]
	v_mfma_f32_16x16x32_bf16 v[90:93], v[138:141], v[222:225], v[90:93]
	v_mfma_f32_16x16x32_bf16 v[78:81], v[130:133], v[230:233], v[78:81]
	v_mfma_f32_16x16x32_bf16 v[74:77], v[138:141], v[230:233], v[74:77]
	v_mfma_f32_16x16x32_bf16 v[122:125], v[134:137], v[194:197], v[122:125]
	v_mfma_f32_16x16x32_bf16 v[126:129], v[142:145], v[194:197], v[126:129]
	v_mfma_f32_16x16x32_bf16 v[110:113], v[134:137], v[206:209], v[110:113]
	v_mfma_f32_16x16x32_bf16 v[106:109], v[142:145], v[206:209], v[106:109]
	v_mfma_f32_16x16x32_bf16 v[94:97], v[134:137], v[226:229], v[94:97]
	v_mfma_f32_16x16x32_bf16 v[90:93], v[142:145], v[226:229], v[90:93]
	v_mfma_f32_16x16x32_bf16 v[78:81], v[134:137], v[234:237], v[78:81]
	v_mfma_f32_16x16x32_bf16 v[74:77], v[142:145], v[234:237], v[74:77]
	v_mfma_f32_16x16x32_bf16 v[118:121], v[146:149], v[190:193], v[118:121]
	v_mfma_f32_16x16x32_bf16 v[114:117], v[154:157], v[190:193], v[114:117]
	v_mfma_f32_16x16x32_bf16 v[102:105], v[146:149], v[198:201], v[102:105]
	v_mfma_f32_16x16x32_bf16 v[98:101], v[154:157], v[198:201], v[98:101]
	v_mfma_f32_16x16x32_bf16 v[86:89], v[146:149], v[222:225], v[86:89]
	v_mfma_f32_16x16x32_bf16 v[82:85], v[154:157], v[222:225], v[82:85]
	v_mfma_f32_16x16x32_bf16 v[70:73], v[146:149], v[230:233], v[70:73]
	v_mfma_f32_16x16x32_bf16 v[66:69], v[154:157], v[230:233], v[66:69]
	v_mfma_f32_16x16x32_bf16 v[118:121], v[150:153], v[194:197], v[118:121]
	v_mfma_f32_16x16x32_bf16 v[114:117], v[186:189], v[194:197], v[114:117]
	v_mfma_f32_16x16x32_bf16 v[102:105], v[150:153], v[206:209], v[102:105]
	v_mfma_f32_16x16x32_bf16 v[98:101], v[186:189], v[206:209], v[98:101]
	v_mfma_f32_16x16x32_bf16 v[86:89], v[150:153], v[226:229], v[86:89]
	v_mfma_f32_16x16x32_bf16 v[82:85], v[186:189], v[226:229], v[82:85]
	v_mfma_f32_16x16x32_bf16 v[70:73], v[150:153], v[234:237], v[70:73]
	v_mfma_f32_16x16x32_bf16 v[66:69], v[186:189], v[234:237], v[66:69]
	s_barrier
	s_add_i32 s34, s34, s20
	v_lshl_add_u64 v[202:203], s[30:31], 0, v[176:177]
	s_mov_b32 m0, s34
	ds_read_b128 v[190:193], v204 offset:16384
	ds_read_b128 v[194:197], v204 offset:17408
	ds_read_b128 v[198:201], v204 offset:18432
	ds_read_b128 v[206:209], v204 offset:19456
	ds_read_b128 v[222:225], v204 offset:20480
	ds_read_b128 v[226:229], v204 offset:21504
	ds_read_b128 v[230:233], v204 offset:22528
	ds_read_b128 v[234:237], v204 offset:23552
	global_load_lds_dwordx4 v[202:203], off
	s_add_i32 m0, s34, 0x2000
	v_lshl_add_u64 v[216:217], s[30:31], 0, v[172:173]
	s_add_u32 s30, s30, s46
	s_addc_u32 s31, s31, s47
	s_add_i32 s34, s35, s20
	global_load_lds_dwordx4 v[216:217], off
	v_lshl_add_u64 v[218:219], s[30:31], 0, v[176:177]
	s_mov_b32 m0, s34
	v_lshl_add_u64 v[238:239], s[30:31], 0, v[172:173]
	global_load_lds_dwordx4 v[218:219], off
	s_add_i32 m0, s34, 0x2000
	v_lshl_add_u64 v[240:241], s[10:11], 0, v[178:179]
	global_load_lds_dwordx4 v[238:239], off
	s_mov_b32 m0, s21
	v_lshl_add_u64 v[242:243], s[10:11], 0, v[174:175]
	global_load_lds_dwordx4 v[240:241], off
	s_mov_b32 m0, s22
	s_nop 0
	global_load_lds_dwordx4 v[242:243], off
	s_waitcnt vmcnt(8)
	s_waitcnt lgkmcnt(0)
	s_barrier
; #define PG8_STAGE(bufoff, gbase, voff) do { _Pragma("unroll") for (int _i = 0; _i < 2; ++_i) \
;         __builtin_amdgcn_global_load_lds((const unsigned*)((const char*)(gbase) + (voff)[_i]), (LAS unsigned*)(lds + (bufoff) + ldsw + _i * 8192), 16, 0, 0); } while (0)
; #define PG8_LDA(dst, b, h) do { _Pragma("unroll") for (int m = 0; m < 4; ++m) _Pragma("unroll") for (int k = 0; k < 2; ++k) dst[m][k] = *(const LAS bf16x8*)(lds + PG8_SA(b, h) + aoff + m * 2048 + k * 1024); } while (0)
; #define PG8_LDB(dst, b, h) do { _Pragma("unroll") for (int n = 0; n < 2; ++n) _Pragma("unroll") for (int k = 0; k < 2; ++k) dst[n][k] = *(const LAS bf16x8*)(lds + PG8_SB(b, h) + boff + n * 2048 + k * 1024); } while (0)
; #define PG8_MMA(ai, bj, At, Bt) do { __builtin_amdgcn_s_setprio(1); _Pragma("unroll") for (int m = 0; m < 4; ++m) _Pragma("unroll") for (int n = 0; n < 2; ++n) _Pragma("unroll") for (int k = 0; k < 2; ++k) \
;         acc[ai][bj][m][n] = __builtin_amdgcn_mfma_f32_16x16x32_bf16(Bt[n][k], At[m][k], acc[ai][bj][m][n], 0, 0, 0); __builtin_amdgcn_s_setprio(0); } while (0)
; #define PG8_WAIT_V(n) asm volatile("s_waitcnt vmcnt(" #n ")" ::: "memory")
; #define PG8_WAIT_L(n) asm volatile("s_waitcnt lgkmcnt(" #n ")" ::: "memory")
; #define PG8_BAR __builtin_amdgcn_s_barrier()
; #define PG8_SCHED __builtin_amdgcn_sched_barrier(0)
; template <class Epi>
; __device__ __forceinline__ void gemm_phase(LAS unsigned char* lds, const Gemm g, const StaticOrder& S, const Epi& E) {
;     ...
;             PG8_WAIT_V(8); PG8_WAIT_L(0); PG8_BAR; PG8_MMA(1, 0, At, B0); PG8_MMA(1, 1, At, B1); PG8_BAR; PG8_SCHED;
;             PG8_LDB(B0, 1, 0); PG8_LDB(B1, 1, 1); PG8_SCHED; PG8_LDA(At, 1, 0); PG8_STAGE(PG8_SA(0, 1), a2 + hstepA, voffA);
;             PG8_WAIT_V(8); PG8_WAIT_L(0); PG8_BAR; PG8_MMA(0, 0, At, B0); PG8_MMA(0, 1, At, B1); PG8_BAR; PG8_SCHED;
	s_waitcnt lgkmcnt(0)
	v_mfma_f32_16x16x32_bf16 v[60:63], v[130:133], v[190:193], v[60:63]
	v_mfma_f32_16x16x32_bf16 v[56:59], v[138:141], v[190:193], v[56:59]
	v_mfma_f32_16x16x32_bf16 v[44:47], v[130:133], v[198:201], v[44:47]
	v_mfma_f32_16x16x32_bf16 v[40:43], v[138:141], v[198:201], v[40:43]
	v_mfma_f32_16x16x32_bf16 v[28:31], v[130:133], v[222:225], v[28:31]
	v_mfma_f32_16x16x32_bf16 v[24:27], v[138:141], v[222:225], v[24:27]
	v_mfma_f32_16x16x32_bf16 v[12:15], v[130:133], v[230:233], v[12:15]
	v_mfma_f32_16x16x32_bf16 v[8:11], v[138:141], v[230:233], v[8:11]
	v_mfma_f32_16x16x32_bf16 v[60:63], v[134:137], v[194:197], v[60:63]
	v_mfma_f32_16x16x32_bf16 v[56:59], v[142:145], v[194:197], v[56:59]
	v_mfma_f32_16x16x32_bf16 v[44:47], v[134:137], v[206:209], v[44:47]
	v_mfma_f32_16x16x32_bf16 v[40:43], v[142:145], v[206:209], v[40:43]
	v_mfma_f32_16x16x32_bf16 v[28:31], v[134:137], v[226:229], v[28:31]
	v_mfma_f32_16x16x32_bf16 v[24:27], v[142:145], v[226:229], v[24:27]
	v_mfma_f32_16x16x32_bf16 v[12:15], v[134:137], v[234:237], v[12:15]
	v_mfma_f32_16x16x32_bf16 v[8:11], v[142:145], v[234:237], v[8:11]
	v_mfma_f32_16x16x32_bf16 v[52:55], v[146:149], v[190:193], v[52:55]
	v_mfma_f32_16x16x32_bf16 v[48:51], v[154:157], v[190:193], v[48:51]
	v_mfma_f32_16x16x32_bf16 v[36:39], v[146:149], v[198:201], v[36:39]
	v_mfma_f32_16x16x32_bf16 v[32:35], v[154:157], v[198:201], v[32:35]
	v_mfma_f32_16x16x32_bf16 v[20:23], v[146:149], v[222:225], v[20:23]
	v_mfma_f32_16x16x32_bf16 v[16:19], v[154:157], v[222:225], v[16:19]
	v_mfma_f32_16x16x32_bf16 v[4:7], v[146:149], v[230:233], v[4:7]
	v_mfma_f32_16x16x32_bf16 v[0:3], v[154:157], v[230:233], v[0:3]
	v_mfma_f32_16x16x32_bf16 v[52:55], v[150:153], v[194:197], v[52:55]
	v_mfma_f32_16x16x32_bf16 v[48:51], v[186:189], v[194:197], v[48:51]
	v_mfma_f32_16x16x32_bf16 v[36:39], v[150:153], v[206:209], v[36:39]
	v_mfma_f32_16x16x32_bf16 v[32:35], v[186:189], v[206:209], v[32:35]
	v_mfma_f32_16x16x32_bf16 v[20:23], v[150:153], v[226:229], v[20:23]
	v_mfma_f32_16x16x32_bf16 v[16:19], v[186:189], v[226:229], v[16:19]
	v_mfma_f32_16x16x32_bf16 v[4:7], v[150:153], v[234:237], v[4:7]
	v_mfma_f32_16x16x32_bf16 v[0:3], v[186:189], v[234:237], v[0:3]
	s_barrier
	s_add_i32 s30, 0, 0x18000
	s_add_i32 s31, 0, 0x1c000
	v_add_u32_e32 v142, s30, v181
	v_add_u32_e32 v186, s31, v181
	ds_read_b128 v[130:133], v142
	ds_read_b128 v[134:137], v142 offset:1024
	ds_read_b128 v[138:141], v142 offset:2048
	ds_read_b128 v[142:145], v142 offset:3072
	ds_read_b128 v[146:149], v186
	ds_read_b128 v[150:153], v186 offset:1024
	ds_read_b128 v[154:157], v186 offset:2048
	ds_read_b128 v[186:189], v186 offset:3072
	s_add_u32 s10, s10, s44
	s_addc_u32 s11, s11, s45
	s_mov_b32 m0, s23
	v_lshl_add_u64 v[244:245], s[10:11], 0, v[178:179]
	ds_read_b128 v[190:193], v204 offset:32768
	ds_read_b128 v[194:197], v204 offset:33792
	ds_read_b128 v[198:201], v204 offset:34816
	ds_read_b128 v[206:209], v204 offset:35840
	ds_read_b128 v[222:225], v204 offset:36864
	ds_read_b128 v[226:229], v204 offset:37888
	ds_read_b128 v[230:233], v204 offset:38912
	ds_read_b128 v[234:237], v204 offset:39936
	global_load_lds_dwordx4 v[244:245], off
	v_lshl_add_u64 v[244:245], s[10:11], 0, v[174:175]
	s_mov_b32 m0, s24
	s_nop 0
	global_load_lds_dwordx4 v[244:245], off
	s_waitcnt vmcnt(8)
	s_waitcnt lgkmcnt(0)
	s_barrier
	s_waitcnt lgkmcnt(0)
	v_mfma_f32_16x16x32_bf16 v[122:125], v[130:133], v[190:193], v[122:125]
	v_mfma_f32_16x16x32_bf16 v[126:129], v[138:141], v[190:193], v[126:129]
	v_mfma_f32_16x16x32_bf16 v[110:113], v[130:133], v[198:201], v[110:113]
	v_mfma_f32_16x16x32_bf16 v[106:109], v[138:141], v[198:201], v[106:109]
	v_mfma_f32_16x16x32_bf16 v[94:97], v[130:133], v[222:225], v[94:97]
	v_mfma_f32_16x16x32_bf16 v[90:93], v[138:141], v[222:225], v[90:93]
	v_mfma_f32_16x16x32_bf16 v[78:81], v[130:133], v[230:233], v[78:81]
	v_mfma_f32_16x16x32_bf16 v[74:77], v[138:141], v[230:233], v[74:77]
	v_mfma_f32_16x16x32_bf16 v[122:125], v[134:137], v[194:197], v[122:125]
	v_mfma_f32_16x16x32_bf16 v[126:129], v[142:145], v[194:197], v[126:129]
	v_mfma_f32_16x16x32_bf16 v[110:113], v[134:137], v[206:209], v[110:113]
	v_mfma_f32_16x16x32_bf16 v[106:109], v[142:145], v[206:209], v[106:109]
	v_mfma_f32_16x16x32_bf16 v[94:97], v[134:137], v[226:229], v[94:97]
	v_mfma_f32_16x16x32_bf16 v[90:93], v[142:145], v[226:229], v[90:93]
	v_mfma_f32_16x16x32_bf16 v[78:81], v[134:137], v[234:237], v[78:81]
	v_mfma_f32_16x16x32_bf16 v[74:77], v[142:145], v[234:237], v[74:77]
	v_mfma_f32_16x16x32_bf16 v[118:121], v[146:149], v[190:193], v[118:121]
	v_mfma_f32_16x16x32_bf16 v[114:117], v[154:157], v[190:193], v[114:117]
	v_mfma_f32_16x16x32_bf16 v[102:105], v[146:149], v[198:201], v[102:105]
	v_mfma_f32_16x16x32_bf16 v[98:101], v[154:157], v[198:201], v[98:101]
	v_mfma_f32_16x16x32_bf16 v[86:89], v[146:149], v[222:225], v[86:89]
	v_mfma_f32_16x16x32_bf16 v[82:85], v[154:157], v[222:225], v[82:85]
	v_mfma_f32_16x16x32_bf16 v[70:73], v[146:149], v[230:233], v[70:73]
	v_mfma_f32_16x16x32_bf16 v[66:69], v[154:157], v[230:233], v[66:69]
	v_mfma_f32_16x16x32_bf16 v[118:121], v[150:153], v[194:197], v[118:121]
	v_mfma_f32_16x16x32_bf16 v[114:117], v[186:189], v[194:197], v[114:117]
	v_mfma_f32_16x16x32_bf16 v[102:105], v[150:153], v[206:209], v[102:105]
	v_mfma_f32_16x16x32_bf16 v[98:101], v[186:189], v[206:209], v[98:101]
	v_mfma_f32_16x16x32_bf16 v[86:89], v[150:153], v[226:229], v[86:89]
	v_mfma_f32_16x16x32_bf16 v[82:85], v[186:189], v[226:229], v[82:85]
	v_mfma_f32_16x16x32_bf16 v[70:73], v[150:153], v[234:237], v[70:73]
	v_mfma_f32_16x16x32_bf16 v[66:69], v[186:189], v[234:237], v[66:69]
	s_barrier
; #define PG8_STAGE(bufoff, gbase, voff) do { _Pragma("unroll") for (int _i = 0; _i < 2; ++_i) \
;         __builtin_amdgcn_global_load_lds((const unsigned*)((const char*)(gbase) + (voff)[_i]), (LAS unsigned*)(lds + (bufoff) + ldsw + _i * 8192), 16, 0, 0); } while (0)
; #define PG8_LDA(dst, b, h) do { _Pragma("unroll") for (int m = 0; m < 4; ++m) _Pragma("unroll") for (int k = 0; k < 2; ++k) dst[m][k] = *(const LAS bf16x8*)(lds + PG8_SA(b, h) + aoff + m * 2048 + k * 1024); } while (0)
; #define PG8_MMA(ai, bj, At, Bt) do { __builtin_amdgcn_s_setprio(1); _Pragma("unroll") for (int m = 0; m < 4; ++m) _Pragma("unroll") for (int n = 0; n < 2; ++n) _Pragma("unroll") for (int k = 0; k < 2; ++k) \
;         acc[ai][bj][m][n] = __builtin_amdgcn_mfma_f32_16x16x32_bf16(Bt[n][k], At[m][k], acc[ai][bj][m][n], 0, 0, 0); __builtin_amdgcn_s_setprio(0); } while (0)
; #define PG8_WAIT_V(n) asm volatile("s_waitcnt vmcnt(" #n ")" ::: "memory")
; #define PG8_WAIT_L(n) asm volatile("s_waitcnt lgkmcnt(" #n ")" ::: "memory")
; #define PG8_BAR __builtin_amdgcn_s_barrier()
; #define PG8_SCHED __builtin_amdgcn_sched_barrier(0)
; template <class Epi>
; __device__ __forceinline__ void gemm_phase(LAS unsigned char* lds, const Gemm g, const StaticOrder& S, const Epi& E) {
;     ...
;             PG8_LDA(At, 1, 1); PG8_STAGE(PG8_SB(1, 0), b3, voffB); PG8_STAGE(PG8_SB(1, 1), b3 + hstepB, voffB); PG8_STAGE(PG8_SA(1, 0), a3, voffA);
;             PG8_WAIT_V(8); PG8_WAIT_L(0); PG8_BAR; PG8_MMA(1, 0, At, B0); PG8_MMA(1, 1, At, B1); PG8_BAR; PG8_SCHED;
;         }
	s_add_i32 s10, s30, s20
	v_lshl_add_u64 v[202:203], v[202:203], 0, s[82:83]
	s_mov_b32 m0, s10
	ds_read_b128 v[190:193], v204 offset:49152
	ds_read_b128 v[194:197], v204 offset:50176
	ds_read_b128 v[198:201], v204 offset:51200
	ds_read_b128 v[206:209], v204 offset:52224
	ds_read_b128 v[222:225], v204 offset:53248
	ds_read_b128 v[226:229], v204 offset:54272
	ds_read_b128 v[230:233], v204 offset:55296
	ds_read_b128 v[234:237], v204 offset:56320
	global_load_lds_dwordx4 v[202:203], off
	v_lshl_add_u64 v[202:203], v[216:217], 0, s[82:83]
	s_add_i32 m0, s10, 0x2000
	s_add_i32 s10, s31, s20
	global_load_lds_dwordx4 v[202:203], off
	v_lshl_add_u64 v[202:203], v[218:219], 0, s[82:83]
	s_mov_b32 m0, s10
	s_nop 0
	global_load_lds_dwordx4 v[202:203], off
	v_lshl_add_u64 v[202:203], v[238:239], 0, s[82:83]
	s_add_i32 m0, s10, 0x2000
	s_nop 0
	global_load_lds_dwordx4 v[202:203], off
	v_lshl_add_u64 v[202:203], v[240:241], 0, s[82:83]
	s_mov_b32 m0, s25
	s_nop 0
	global_load_lds_dwordx4 v[202:203], off
	v_lshl_add_u64 v[202:203], v[242:243], 0, s[82:83]
	s_mov_b32 m0, s72
	s_nop 0
	global_load_lds_dwordx4 v[202:203], off
	s_waitcnt vmcnt(8)
	s_waitcnt lgkmcnt(0)
	s_barrier
	s_waitcnt lgkmcnt(0)
	v_mfma_f32_16x16x32_bf16 v[60:63], v[130:133], v[190:193], v[60:63]
	v_mfma_f32_16x16x32_bf16 v[56:59], v[138:141], v[190:193], v[56:59]
	v_mfma_f32_16x16x32_bf16 v[44:47], v[130:133], v[198:201], v[44:47]
	v_mfma_f32_16x16x32_bf16 v[40:43], v[138:141], v[198:201], v[40:43]
	v_mfma_f32_16x16x32_bf16 v[28:31], v[130:133], v[222:225], v[28:31]
	v_mfma_f32_16x16x32_bf16 v[24:27], v[138:141], v[222:225], v[24:27]
	v_mfma_f32_16x16x32_bf16 v[12:15], v[130:133], v[230:233], v[12:15]
	v_mfma_f32_16x16x32_bf16 v[8:11], v[138:141], v[230:233], v[8:11]
	v_mfma_f32_16x16x32_bf16 v[60:63], v[134:137], v[194:197], v[60:63]
	v_mfma_f32_16x16x32_bf16 v[56:59], v[142:145], v[194:197], v[56:59]
	v_mfma_f32_16x16x32_bf16 v[44:47], v[134:137], v[206:209], v[44:47]
	v_mfma_f32_16x16x32_bf16 v[40:43], v[142:145], v[206:209], v[40:43]
	v_mfma_f32_16x16x32_bf16 v[28:31], v[134:137], v[226:229], v[28:31]
	v_mfma_f32_16x16x32_bf16 v[24:27], v[142:145], v[226:229], v[24:27]
	v_mfma_f32_16x16x32_bf16 v[12:15], v[134:137], v[234:237], v[12:15]
	v_mfma_f32_16x16x32_bf16 v[8:11], v[142:145], v[234:237], v[8:11]
	v_mfma_f32_16x16x32_bf16 v[52:55], v[146:149], v[190:193], v[52:55]
	v_mfma_f32_16x16x32_bf16 v[48:51], v[154:157], v[190:193], v[48:51]
	v_mfma_f32_16x16x32_bf16 v[36:39], v[146:149], v[198:201], v[36:39]
	v_mfma_f32_16x16x32_bf16 v[32:35], v[154:157], v[198:201], v[32:35]
	v_mfma_f32_16x16x32_bf16 v[20:23], v[146:149], v[222:225], v[20:23]
	v_mfma_f32_16x16x32_bf16 v[16:19], v[154:157], v[222:225], v[16:19]
	v_mfma_f32_16x16x32_bf16 v[4:7], v[146:149], v[230:233], v[4:7]
	v_mfma_f32_16x16x32_bf16 v[0:3], v[154:157], v[230:233], v[0:3]
	v_mfma_f32_16x16x32_bf16 v[52:55], v[150:153], v[194:197], v[52:55]
	v_mfma_f32_16x16x32_bf16 v[48:51], v[186:189], v[194:197], v[48:51]
	v_mfma_f32_16x16x32_bf16 v[36:39], v[150:153], v[206:209], v[36:39]
	v_mfma_f32_16x16x32_bf16 v[32:35], v[186:189], v[206:209], v[32:35]
	v_mfma_f32_16x16x32_bf16 v[20:23], v[150:153], v[226:229], v[20:23]
	v_mfma_f32_16x16x32_bf16 v[16:19], v[186:189], v[226:229], v[16:19]
	v_mfma_f32_16x16x32_bf16 v[4:7], v[150:153], v[234:237], v[4:7]
	v_mfma_f32_16x16x32_bf16 v[0:3], v[186:189], v[234:237], v[0:3]
	s_add_u32 s27, s27, 0x100
	s_addc_u32 s28, s28, 0
	s_add_u32 s38, s38, 0x100
	s_addc_u32 s39, s39, 0
	s_cmp_ge_i32 s29, s85
	s_mov_b32 s10, s29
	s_barrier
	s_cbranch_scc0 .LBB0_3925
